# fallback (non-XCD-aware) NSA path converted to the same 16-byte-pair fragment layout and dwordx4 loads, so both deal paths agree with the new buffers (no change on the 256-CU path)
# speedup vs baseline: 1.0853x; 1.0034x over previous
; __device__ __forceinline__ unsigned cvt_pk_bf16(float lo, float hi) { f32x2 v = {lo, hi}; bf16x2_t b = __builtin_convertvector(v, bf16x2_t); return __builtin_bit_cast(unsigned, b); }
; __device__ __forceinline__ float bf2f(unsigned short b) { return __uint_as_float(((unsigned)b) << 16); }
; __device__ __forceinline__ float bflo(unsigned w) { return __uint_as_float(w << 16); }
; __device__ __forceinline__ float bfhi(unsigned w) { return __uint_as_float(w & 0xffff0000u); }
; __device__ __forceinline__ float quad_total(float v) { v += __shfl_xor(v, 16); v += __shfl_xor(v, 32); return v; }
; __device__ __forceinline__ void nsa_unit(int unit, const bf16_t* proj, const bf16_t* kc, const bf16_t* vc, const bf16_t* gn, const float* cs, const float* sn, ...
;     ...
;     { const float g2 = bf2f(gn[(size_t)tc * 32 + head * 3 + 2]); const float lt = quad_total(st.l), inv = (lt > 0.f ? 1.f / lt : 0.f) * g2;
; #pragma unroll
;         for (int i = 0; i < 8; ++i) { const f32x4 o = st.o[i] * inv; u32x2 w = outl[64 * i]; w.x = cvt_pk_bf16(bflo(w.x) + o[0], bfhi(w.x) + o[1]); w.y = cvt_pk_bf16(bflo(w.y) + o[2], bfhi(w.y) + o[3]); outl[64 * i] = w; } }
;     bf16_t* op = nsaout + (size_t)tc * NOLD + head * 128 + 4 * kq;
; #pragma unroll
;     for (int db = 0; db < 8; ++db) *(u32x2*)(op + 16 * db) = outl[64 * db];
; __global__ void __launch_bounds__(512, 2) fwd_megakernel(Params P) {
;     ...
;       } else { for (int u = gw; u < 8192; u += ngw) nsa_unit(u, PROJ, KC, VC, GN, RCOS, RSIN, KSLF, VSLF, KWNF, VWNF, NSAOUT, wl, lane); } }
.LBB0_826:
	s_waitcnt vmcnt(8)
	global_load_ushort v0, v[76:77], off offset:4
	ds_bpermute_b32 v35, v227, v34
	ds_read2st64_b64 v[36:39], v228 offset0:27 offset1:28
	ds_read2st64_b64 v[40:43], v228 offset0:29 offset1:30
	ds_read2st64_b64 v[44:47], v228 offset0:31 offset1:32
	ds_read2st64_b64 v[48:51], v228 offset0:33 offset1:34
	s_add_i32 s72, s72, s34
	s_waitcnt lgkmcnt(3)
	v_lshlrev_b32_e32 v52, 16, v38
	v_and_b32_e32 v53, 0xffff0000, v38
	v_add_f32_e32 v64, v34, v35
	ds_bpermute_b32 v65, v226, v64
	v_lshlrev_b32_e32 v34, 16, v36
	v_and_b32_e32 v35, 0xffff0000, v36
	v_lshlrev_b32_e32 v36, 16, v37
	v_and_b32_e32 v37, 0xffff0000, v37
	s_waitcnt lgkmcnt(0)
	v_add_f32_e32 v64, v64, v65
	v_div_scale_f32 v65, s[10:11], v64, v64, 1.0
	v_rcp_f32_e32 v66, v65
	v_div_scale_f32 v67, vcc, 1.0, v64, 1.0
	v_lshlrev_b32_e32 v38, 16, v39
	v_fma_f32 v68, -v65, v66, 1.0
	v_fmac_f32_e32 v66, v68, v66
	v_mul_f32_e32 v68, v67, v66
	v_fma_f32 v69, -v65, v68, v67
	v_fmac_f32_e32 v68, v69, v66
	v_fma_f32 v65, -v65, v68, v67
	v_div_fmas_f32 v65, v65, v66, v68
	v_div_fixup_f32 v65, v65, v64, 1.0
	v_cmp_lt_f32_e32 vcc, 0, v64
	v_and_b32_e32 v39, 0xffff0000, v39
	v_lshlrev_b32_e32 v56, 16, v42
	v_cndmask_b32_e32 v64, 0, v65, vcc
	v_and_b32_e32 v57, 0xffff0000, v42
	v_lshlrev_b32_e32 v42, 16, v43
	v_and_b32_e32 v43, 0xffff0000, v43
	v_lshlrev_b32_e32 v62, 16, v48
	v_and_b32_e32 v63, 0xffff0000, v48
	v_lshlrev_b32_e32 v48, 16, v49
	v_and_b32_e32 v49, 0xffff0000, v49
	v_lshlrev_b32_e32 v54, 16, v40
	v_and_b32_e32 v55, 0xffff0000, v40
	v_lshlrev_b32_e32 v40, 16, v41
	v_and_b32_e32 v41, 0xffff0000, v41
	v_lshlrev_b32_e32 v58, 16, v44
	v_and_b32_e32 v59, 0xffff0000, v44
	v_lshlrev_b32_e32 v44, 16, v45
	v_and_b32_e32 v45, 0xffff0000, v45
	v_lshlrev_b32_e32 v60, 16, v46
	v_and_b32_e32 v61, 0xffff0000, v46
	v_lshlrev_b32_e32 v46, 16, v47
	v_and_b32_e32 v47, 0xffff0000, v47
	s_movk_i32 s10, 0xc00
	s_cmpk_lt_i32 s72, 0x2000
	s_waitcnt vmcnt(0)
	v_lshlrev_b32_e32 v0, 16, v0
	v_mul_f32_e32 v0, v64, v0
	v_pk_fma_f32 v[6:7], v[6:7], v[0:1], v[34:35] op_sel_hi:[1,0,1]
	v_pk_fma_f32 v[8:9], v[8:9], v[0:1], v[36:37] op_sel_hi:[1,0,1]
	v_pk_fma_f32 v[12:13], v[12:13], v[0:1], v[38:39] op_sel_hi:[1,0,1]
	v_pk_fma_f32 v[20:21], v[20:21], v[0:1], v[42:43] op_sel_hi:[1,0,1]
	v_cvt_pk_bf16_f32 v6, v6, v7
	v_cvt_pk_bf16_f32 v7, v8, v9
	v_cvt_pk_bf16_f32 v9, v12, v13
	v_cvt_pk_bf16_f32 v13, v20, v21
	v_lshlrev_b32_e32 v20, 16, v50
	v_and_b32_e32 v21, 0xffff0000, v50
	v_pk_fma_f32 v[2:3], v[2:3], v[0:1], v[20:21] op_sel_hi:[1,0,1]
	v_lshlrev_b32_e32 v20, 16, v51
	v_and_b32_e32 v21, 0xffff0000, v51
	v_pk_fma_f32 v[10:11], v[10:11], v[0:1], v[52:53] op_sel_hi:[1,0,1]
	v_pk_fma_f32 v[18:19], v[18:19], v[0:1], v[56:57] op_sel_hi:[1,0,1]
	v_pk_fma_f32 v[30:31], v[30:31], v[0:1], v[62:63] op_sel_hi:[1,0,1]
	v_pk_fma_f32 v[32:33], v[32:33], v[0:1], v[48:49] op_sel_hi:[1,0,1]
	v_pk_fma_f32 v[4:5], v[4:5], v[0:1], v[20:21] op_sel_hi:[1,0,1]
	v_pk_fma_f32 v[14:15], v[14:15], v[0:1], v[54:55] op_sel_hi:[1,0,1]
	v_pk_fma_f32 v[16:17], v[16:17], v[0:1], v[40:41] op_sel_hi:[1,0,1]
	v_pk_fma_f32 v[22:23], v[22:23], v[0:1], v[58:59] op_sel_hi:[1,0,1]
	v_pk_fma_f32 v[24:25], v[24:25], v[0:1], v[44:45] op_sel_hi:[1,0,1]
	v_pk_fma_f32 v[26:27], v[26:27], v[0:1], v[60:61] op_sel_hi:[1,0,1]
	v_pk_fma_f32 v[28:29], v[28:29], v[0:1], v[46:47] op_sel_hi:[1,0,1]
	v_cvt_pk_bf16_f32 v8, v10, v11
	v_cvt_pk_bf16_f32 v12, v18, v19
	v_cvt_pk_bf16_f32 v18, v30, v31
	v_cvt_pk_bf16_f32 v19, v32, v33
	v_cvt_pk_bf16_f32 v2, v2, v3
	v_cvt_pk_bf16_f32 v3, v4, v5
	v_mad_i64_i32 v[4:5], s[10:11], v132, s10, v[126:127]
	v_cvt_pk_bf16_f32 v10, v14, v15
	v_cvt_pk_bf16_f32 v11, v16, v17
	v_cvt_pk_bf16_f32 v14, v22, v23
	v_cvt_pk_bf16_f32 v15, v24, v25
	v_cvt_pk_bf16_f32 v16, v26, v27
	v_cvt_pk_bf16_f32 v17, v28, v29
	ds_write2st64_b64 v228, v[6:7], v[8:9] offset0:27 offset1:28
	ds_write2st64_b64 v228, v[10:11], v[12:13] offset0:29 offset1:30
	ds_write2st64_b64 v228, v[14:15], v[16:17] offset0:31 offset1:32
	ds_write2st64_b64 v228, v[18:19], v[2:3] offset0:33 offset1:34
	global_store_dwordx2 v[4:5], v[6:7], off
	global_store_dwordx2 v[4:5], v[8:9], off offset:32
	global_store_dwordx2 v[4:5], v[10:11], off offset:64
	global_store_dwordx2 v[4:5], v[12:13], off offset:96
	global_store_dwordx2 v[4:5], v[14:15], off offset:128
	global_store_dwordx2 v[4:5], v[16:17], off offset:160
	global_store_dwordx2 v[4:5], v[18:19], off offset:192
	global_store_dwordx2 v[4:5], v[2:3], off offset:224
	s_cbranch_scc0 .LBB0_922

; __device__ __forceinline__ void nsa_unit(int unit, const bf16_t* proj, const bf16_t* kc, const bf16_t* vc, const bf16_t* gn, const float* cs, const float* sn, ...
;     ...
; #pragma unroll
;     for (int s2 = 0; s2 < 2; ++s2) {
;         const int d = 32 * s2 + 8 * kq; f32x4 c[2], sv[2];
;         c[0] = *(const f32x4*)(cs + (size_t)tc * 64 + d); c[1] = *(const f32x4*)(cs + (size_t)tc * 64 + d + 4);
;         sv[0] = *(const f32x4*)(sn + (size_t)tc * 64 + d); sv[1] = *(const f32x4*)(sn + (size_t)tc * 64 + d + 4);
;         float o1[8], o2[8];
; #pragma unroll
;         for (int j = 0; j < 8; ++j) { const float x1 = bf2f((unsigned short)qf[s2][j]), x2 = bf2f((unsigned short)qf[s2 + 2][j]), cc = c[j >> 2][j & 3], ss = sv[j >> 2][j & 3];
;             o1[j] = x1 * cc - x2 * ss; o2[j] = x2 * cc + x1 * ss; }
;         u32x4 w1, w2; w1.x = cvt_pk_bf16(o1[0], o1[1]); w1.y = cvt_pk_bf16(o1[2], o1[3]); w1.z = cvt_pk_bf16(o1[4], o1[5]); w1.w = cvt_pk_bf16(o1[6], o1[7]);
;         w2.x = cvt_pk_bf16(o2[0], o2[1]); w2.y = cvt_pk_bf16(o2[2], o2[3]); w2.z = cvt_pk_bf16(o2[4], o2[5]); w2.w = cvt_pk_bf16(o2[6], o2[7]);
;         qf[s2] = __builtin_bit_cast(bf16x8, w1); qf[s2 + 2] = __builtin_bit_cast(bf16x8, w2);
;     }
;     unsigned key[4][4];
; #pragma unroll
;     for (int q = 0; q < 4; ++q) { const int cur = (t0 + q) >> 6; const f32x4 v = *(const LAS f32x4*)(imp + q * IMP_LD + 4 * lane);
; #pragma unroll
;         for (int i = 0; i < 4; ++i) { const int j = 4 * lane + i; const bool valid = j <= cur, forced = (j == 0) | (j == cur) | (j == cur - 1);
;             const unsigned kb = forced ? 0xffffffu : ((__float_as_uint(fmaxf(v[i], 0.f)) >> 8) + 1u);
;             key[q][i] = valid ? ((kb << 8) | (unsigned)(255 - j)) : 0u; } }
; #pragma unroll 1
;     for (int r = 0; r < 16; ++r) {
;         unsigned mx[4];
; #pragma unroll
;         for (int q = 0; q < 4; ++q) { unsigned a = key[q][0] > key[q][1] ? key[q][0] : key[q][1], b = key[q][2] > key[q][3] ? key[q][2] : key[q][3]; mx[q] = a > b ? a : b; }
; #pragma unroll
;         for (int o = 1; o < 64; o <<= 1)
; #pragma unroll
;             for (int q = 0; q < 4; ++q) { const unsigned other = (unsigned)__shfl_xor((int)mx[q], o); mx[q] = other > mx[q] ? other : mx[q]; }
; #pragma unroll
;         for (int q = 0; q < 4; ++q) {
; #pragma unroll
;             for (int i = 0; i < 4; ++i) if (key[q][i] == mx[q]) key[q][i] = 0u;
.LBB0_857:
	s_or_b64 exec, exec, s[12:13]
	v_and_b32_e32 v51, 0xffff0000, v14
	v_lshlrev_b32_e32 v50, 16, v14
	v_and_b32_e32 v53, 0xffff0000, v10
	v_lshlrev_b32_e32 v52, 16, v10
	s_waitcnt vmcnt(4)
	v_pk_mul_f32 v[54:55], v[46:47], v[52:53]
	v_pk_mul_f32 v[46:47], v[46:47], v[50:51]
	v_pk_fma_f32 v[54:55], v[42:43], v[50:51], v[54:55] neg_lo:[0,0,1] neg_hi:[0,0,1]
	v_pk_fma_f32 v[42:43], v[42:43], v[52:53], v[46:47]
	v_and_b32_e32 v47, 0xffff0000, v15
	v_lshlrev_b32_e32 v46, 16, v15
	v_and_b32_e32 v15, 0xffff0000, v11
	v_lshlrev_b32_e32 v14, 16, v11
	v_pk_mul_f32 v[10:11], v[48:49], v[14:15]
	v_cvt_pk_bf16_f32 v0, v54, v55
	v_pk_fma_f32 v[10:11], v[44:45], v[46:47], v[10:11] neg_lo:[0,0,1] neg_hi:[0,0,1]
	v_pk_mul_f32 v[46:47], v[48:49], v[46:47]
	v_mov_b32_e32 v79, v1
	v_pk_fma_f32 v[14:15], v[44:45], v[14:15], v[46:47]
	v_and_b32_e32 v45, 0xffff0000, v16
	v_lshlrev_b32_e32 v44, 16, v16
	v_and_b32_e32 v47, 0xffff0000, v12
	v_lshlrev_b32_e32 v46, 16, v12
	v_pk_mul_f32 v[48:49], v[38:39], v[46:47]
	v_pk_mul_f32 v[38:39], v[38:39], v[44:45]
	v_pk_fma_f32 v[48:49], v[34:35], v[44:45], v[48:49] neg_lo:[0,0,1] neg_hi:[0,0,1]
	v_pk_fma_f32 v[34:35], v[34:35], v[46:47], v[38:39]
	v_and_b32_e32 v39, 0xffff0000, v17
	v_lshlrev_b32_e32 v38, 16, v17
	v_and_b32_e32 v17, 0xffff0000, v13
	v_lshlrev_b32_e32 v16, 16, v13
	v_pk_mul_f32 v[12:13], v[40:41], v[16:17]
	v_cvt_pk_bf16_f32 v34, v34, v35
	v_pk_fma_f32 v[12:13], v[36:37], v[38:39], v[12:13] neg_lo:[0,0,1] neg_hi:[0,0,1]
	v_pk_mul_f32 v[38:39], v[40:41], v[38:39]
	v_cvt_pk_bf16_f32 v40, v14, v15
	v_pk_fma_f32 v[16:17], v[36:37], v[16:17], v[38:39]
	v_cvt_pk_bf16_f32 v38, v12, v13
	v_and_b32_e32 v13, 0xffff0000, v2
	v_lshlrev_b32_e32 v12, 16, v2
	v_cvt_pk_bf16_f32 v36, v10, v11
	v_and_b32_e32 v11, 0xffff0000, v6
	v_lshlrev_b32_e32 v10, 16, v6
	s_waitcnt vmcnt(0)
	v_pk_mul_f32 v[14:15], v[30:31], v[12:13]
	v_lshlrev_b32_e32 v6, 16, v3
	v_pk_fma_f32 v[14:15], v[26:27], v[10:11], v[14:15] neg_lo:[0,0,1] neg_hi:[0,0,1]
	v_pk_mul_f32 v[10:11], v[30:31], v[10:11]
	v_cvt_pk_bf16_f32 v35, v16, v17
	v_pk_fma_f32 v[10:11], v[26:27], v[12:13], v[10:11]
	v_and_b32_e32 v13, 0xffff0000, v7
	v_lshlrev_b32_e32 v12, 16, v7
	v_and_b32_e32 v7, 0xffff0000, v3
	v_pk_mul_f32 v[2:3], v[32:33], v[6:7]
	v_and_b32_e32 v17, 0xffff0000, v4
	v_pk_fma_f32 v[2:3], v[28:29], v[12:13], v[2:3] neg_lo:[0,0,1] neg_hi:[0,0,1]
	v_pk_mul_f32 v[12:13], v[32:33], v[12:13]
	v_lshlrev_b32_e32 v16, 16, v4
	v_pk_fma_f32 v[6:7], v[28:29], v[6:7], v[12:13]
	v_and_b32_e32 v13, 0xffff0000, v8
	v_lshlrev_b32_e32 v12, 16, v8
	v_pk_mul_f32 v[26:27], v[22:23], v[16:17]
	v_lshlrev_b32_e32 v8, 16, v5
	v_pk_fma_f32 v[26:27], v[18:19], v[12:13], v[26:27] neg_lo:[0,0,1] neg_hi:[0,0,1]
	v_pk_mul_f32 v[12:13], v[22:23], v[12:13]
	v_cvt_pk_bf16_f32 v37, v48, v49
	v_pk_fma_f32 v[12:13], v[18:19], v[16:17], v[12:13]
	v_and_b32_e32 v17, 0xffff0000, v9
	v_lshlrev_b32_e32 v16, 16, v9
	v_and_b32_e32 v9, 0xffff0000, v5
	v_pk_mul_f32 v[4:5], v[24:25], v[8:9]
	v_mov_b32_e32 v78, v1
	v_pk_fma_f32 v[4:5], v[20:21], v[16:17], v[4:5] neg_lo:[0,0,1] neg_hi:[0,0,1]
	v_pk_mul_f32 v[16:17], v[24:25], v[16:17]
	v_cvt_pk_bf16_f32 v4, v4, v5
	v_cvt_pk_bf16_f32 v5, v10, v11
	v_lshlrev_b32_e32 v10, 16, v37
	v_and_b32_e32 v11, 0xffff0000, v37
	v_pk_fma_f32 v[8:9], v[20:21], v[8:9], v[16:17]
	v_mul_f32_e32 v10, 0x3e0293ee, v10
	v_mul_f32_e32 v11, 0x3e0293ee, v11
	v_cvt_pk_bf16_f32 v8, v8, v9
	v_lshlrev_b32_e32 v9, 16, v0
	v_and_b32_e32 v0, 0xffff0000, v0
	v_cvt_pk_fp8_f32 v79, v10, v11
	v_mul_f32_e32 v9, 0x3e0293ee, v9
	v_mul_f32_e32 v0, 0x3e0293ee, v0
	v_cvt_pk_bf16_f32 v6, v6, v7
	v_cvt_pk_bf16_f32 v7, v12, v13
	v_lshlrev_b32_e32 v13, 16, v38
	v_cvt_pk_fp8_f32 v78, v9, v0
	v_and_b32_e32 v0, 0xffff0000, v38
	v_cvt_pk_bf16_f32 v14, v14, v15
	v_mul_f32_e32 v13, 0x3e0293ee, v13
	v_mul_f32_e32 v0, 0x3e0293ee, v0
	v_cvt_pk_fp8_f32 v79, v13, v0 op_sel:[0,0,1]
	v_lshlrev_b32_e32 v0, 16, v14
	v_and_b32_e32 v10, 0xffff0000, v14
	v_cvt_pk_bf16_f32 v2, v2, v3
	v_cvt_pk_bf16_f32 v3, v26, v27
	v_mul_f32_e32 v0, 0x3e0293ee, v0
	v_mul_f32_e32 v10, 0x3e0293ee, v10
	v_mov_b32_e32 v80, v1
	v_lshlrev_b32_e32 v9, 16, v3
	v_and_b32_e32 v3, 0xffff0000, v3
	v_cvt_pk_fp8_f32 v80, v0, v10
	v_mul_f32_e32 v9, 0x3e0293ee, v9
	v_mul_f32_e32 v3, 0x3e0293ee, v3
	v_mov_b32_e32 v81, v1
	v_lshlrev_b32_e32 v12, 16, v36
	v_and_b32_e32 v15, 0xffff0000, v36
	v_lshlrev_b32_e32 v11, 16, v2
	v_and_b32_e32 v2, 0xffff0000, v2
	v_cvt_pk_fp8_f32 v81, v9, v3
	v_mul_f32_e32 v12, 0x3e0293ee, v12
	v_mul_f32_e32 v15, 0x3e0293ee, v15
	v_mul_f32_e32 v11, 0x3e0293ee, v11
	v_mul_f32_e32 v2, 0x3e0293ee, v2
	v_cvt_pk_fp8_f32 v78, v12, v15 op_sel:[0,0,1]
	v_lshlrev_b32_e32 v12, 16, v4
	v_and_b32_e32 v0, 0xffff0000, v4
	v_cvt_pk_fp8_f32 v80, v11, v2 op_sel:[0,0,1]
	v_lshlrev_b32_e32 v2, 16, v34
	v_and_b32_e32 v4, 0xffff0000, v34
	v_cvt_pk_bf16_f32 v39, v42, v43
	v_mul_f32_e32 v12, 0x3e0293ee, v12
	v_mul_f32_e32 v0, 0x3e0293ee, v0
	v_mul_f32_e32 v2, 0x3e0293ee, v2
	v_mul_f32_e32 v4, 0x3e0293ee, v4
	v_mov_b32_e32 v83, v1
	v_cvt_pk_fp8_f32 v81, v12, v0 op_sel:[0,0,1]
	v_lshlrev_b32_e32 v0, 16, v39
	v_and_b32_e32 v3, 0xffff0000, v39
	v_cvt_pk_fp8_f32 v83, v2, v4
	v_mul_f32_e32 v0, 0x3e0293ee, v0
	v_mul_f32_e32 v3, 0x3e0293ee, v3
	v_mov_b32_e32 v82, v1
	v_lshlrev_b32_e32 v10, 16, v35
	v_cvt_pk_fp8_f32 v82, v0, v3
	v_and_b32_e32 v0, 0xffff0000, v35
	v_mul_f32_e32 v10, 0x3e0293ee, v10
	v_mul_f32_e32 v0, 0x3e0293ee, v0
	v_cvt_pk_fp8_f32 v83, v10, v0 op_sel:[0,0,1]
	v_lshlrev_b32_e32 v0, 16, v5
	v_lshlrev_b32_e32 v2, 16, v7
	v_and_b32_e32 v3, 0xffff0000, v5
	v_and_b32_e32 v4, 0xffff0000, v7
	v_mul_f32_e32 v0, 0x3e0293ee, v0
	v_mul_f32_e32 v2, 0x3e0293ee, v2
	v_mul_f32_e32 v3, 0x3e0293ee, v3
	v_mul_f32_e32 v4, 0x3e0293ee, v4
	v_mov_b32_e32 v84, v1
	v_mov_b32_e32 v85, v1
	v_cvt_pk_fp8_f32 v84, v0, v3
	v_cvt_pk_fp8_f32 v85, v2, v4
	v_lshlrev_b32_e32 v9, 16, v40
	v_and_b32_e32 v11, 0xffff0000, v40
	v_lshlrev_b32_e32 v5, 16, v6
	v_lshlrev_b32_e32 v7, 16, v8
	v_and_b32_e32 v6, 0xffff0000, v6
	v_and_b32_e32 v0, 0xffff0000, v8
	v_mul_f32_e32 v9, 0x3e0293ee, v9
	v_mul_f32_e32 v11, 0x3e0293ee, v11
	v_mul_f32_e32 v5, 0x3e0293ee, v5
	v_mul_f32_e32 v7, 0x3e0293ee, v7
	v_mul_f32_e32 v6, 0x3e0293ee, v6
	v_mul_f32_e32 v0, 0x3e0293ee, v0
	v_cvt_pk_fp8_f32 v82, v9, v11 op_sel:[0,0,1]
	v_cvt_pk_fp8_f32 v84, v5, v6 op_sel:[0,0,1]
	v_cvt_pk_fp8_f32 v85, v7, v0 op_sel:[0,0,1]
	s_waitcnt lgkmcnt(0)
	s_mov_b64 s[10:11], s[52:53]
	s_cmp_eq_u64 vcc, 0
	s_cbranch_scc1 .LBB0_889
; template <bool SLC, class Desc>
; __device__ __forceinline__ void attn_run_frag8(const i64_t (&qf)[4], const unsigned char* __restrict__ KF, const unsigned char* __restrict__ VF, const Desc& desc, int n,
;                                                int lo_in, int hi, int qi, AState& st, int lane) {
;     if (n <= 0) return;
;     Frag8 fa, fb, fc;
;     constexpr int NM = ~(1 << 30);
;     int d0 = desc(0), d1 = desc(n > 1 ? 1 : 0);
;     load_frag8(fa, KF, VF, SLC ? (d0 & 0xfffff) : (d0 & NM), lane);
;     load_frag8(fb, KF, VF, SLC ? (d1 & 0xfffff) : (d1 & NM), lane);
; __device__ __forceinline__ void nsa_unit(int unit, const bf16_t* proj, const bf16_t* kc, const bf16_t* vc, const bf16_t* gn, const float* cs, const float* sn, ...
;     ...
;     astate_init(st);
;     { auto desc = [&](int i) { return __builtin_amdgcn_readfirstlane(list[i]); };
;       unsigned long long goff = (unsigned long long)g * S * 128; asm volatile("" : "+s"(goff));
;       attn_run_frag8<true>(q8, (const unsigned char*)kslf + goff, (const unsigned char*)kslf + ((size_t)8 << 20) + goff, desc, nslc, 0, tc, qi, st, lane); }
	v_mov_b32_e32 v0, s3
	ds_read_b64 v[2:3], v0 offset:13632
	s_bcnt1_i32_b64 s12, vcc
	s_lshl_b32 s56, s12, 1
	s_add_u32 s12, s79, s10
	s_addc_u32 s13, s80, s11
	s_add_u32 s10, s77, s10
	s_waitcnt lgkmcnt(0)
	v_readfirstlane_b32 s59, v2
	s_addc_u32 s11, s78, s11
	s_lshl_b32 s16, s59, 7
	s_and_b32 s14, s16, 0x7fff800
	s_add_u32 s14, s10, s14
	s_addc_u32 s15, s11, 0
	v_readfirstlane_b32 s97, v3
	v_lshl_add_u64 v[2:3], s[14:15], 0, v[118:119]
	s_and_b32 s14, s16, 0x7fff000
	s_add_u32 s14, s12, s14
	s_addc_u32 s15, s13, 0
	s_lshl_b32 s16, s97, 7
	v_lshl_add_u64 v[244:245], v[2:3], 0, v[118:119]
	global_load_dwordx4 v[138:141], v[244:245], off
	global_load_dwordx4 v[142:145], v[244:245], off offset:1024
	global_load_dwordx4 v[146:149], v[244:245], off offset:2048
	global_load_dwordx4 v[150:153], v[244:245], off offset:3072
	v_lshl_add_u64 v[2:3], s[14:15], 0, v[118:119]
	s_and_b32 s14, s16, 0x7fff800
	s_add_u32 s14, s10, s14
	s_addc_u32 s15, s11, 0
	v_lshl_add_u64 v[246:247], v[2:3], 0, v[118:119]
	global_load_dwordx4 v[90:93], v[246:247], off
	global_load_dwordx4 v[94:97], v[246:247], off offset:1024
	global_load_dwordx4 v[98:101], v[246:247], off offset:2048
	global_load_dwordx4 v[102:105], v[246:247], off offset:3072
	v_lshl_add_u64 v[2:3], s[14:15], 0, v[118:119]
	s_and_b32 s14, s16, 0x7fff000
	s_add_u32 s14, s12, s14
	s_addc_u32 s15, s13, 0
	v_lshl_add_u64 v[244:245], v[2:3], 0, v[118:119]
	global_load_dwordx4 v[154:157], v[244:245], off
	global_load_dwordx4 v[158:161], v[244:245], off offset:1024
	global_load_dwordx4 v[162:165], v[244:245], off offset:2048
	global_load_dwordx4 v[166:169], v[244:245], off offset:3072
	v_lshl_add_u64 v[2:3], s[14:15], 0, v[118:119]
	v_lshl_add_u64 v[246:247], v[2:3], 0, v[118:119]
	global_load_dwordx4 v[106:109], v[246:247], off
	global_load_dwordx4 v[110:113], v[246:247], off offset:1024
	global_load_dwordx4 v[114:117], v[246:247], off offset:2048
	global_load_dwordx4 v[134:137], v[246:247], off offset:3072
	v_mov_b32_e32 v2, v1
	v_mov_b32_e32 v3, v1
	v_mov_b32_e32 v0, v1
	v_mov_b64_e32 v[38:39], v[2:3]
	v_mov_b64_e32 v[42:43], v[2:3]
	v_mov_b64_e32 v[46:47], v[2:3]
	v_mov_b64_e32 v[50:51], v[2:3]
	v_mov_b64_e32 v[54:55], v[2:3]
	v_mov_b64_e32 v[58:59], v[2:3]
	v_mov_b64_e32 v[62:63], v[2:3]
	v_mov_b64_e32 v[66:67], v[2:3]
	v_lshl_add_u64 v[86:87], s[10:11], 0, v[118:119]
	v_lshl_add_u64 v[88:89], s[12:13], 0, v[118:119]
	s_add_i32 s57, s56, -1
	v_mov_b32_e32 v202, 0xf149f2ca
	v_mov_b32_e32 v203, 0
	s_mov_b32 s58, 4
	v_mov_b64_e32 v[36:37], v[0:1]
	v_mov_b64_e32 v[40:41], v[0:1]
	v_mov_b64_e32 v[44:45], v[0:1]
	v_mov_b64_e32 v[48:49], v[0:1]
	v_mov_b64_e32 v[52:53], v[0:1]
	v_mov_b64_e32 v[56:57], v[0:1]
	v_mov_b64_e32 v[60:61], v[0:1]
	v_mov_b64_e32 v[64:65], v[0:1]
	s_branch .LBB0_861

; template <bool SLC, bool NOMASK> ...
;     const int kq = lane >> 4;
;     const int pos0 = SLC ? (dcur & 0xfffff) : dcur;
;     const int lo = SLC ? ((((dcur >> 20) == qi) | ((dcur >> 20) == 4)) ? 0 : (1 << 30)) : lo_in;
;     load_frag8(nxt, KF, VF, SLC ? (dnext & 0xfffff) : dnext, lane);
;     f32x4 sa[2] = {(f32x4){0.f, 0.f, 0.f, 0.f}, (f32x4){0.f, 0.f, 0.f, 0.f}};
; #pragma unroll
;     for (int T = 0; T < 2; ++T)
; #pragma unroll
;         for (int s2 = 0; s2 < 4; ++s2) sa[T] = __builtin_amdgcn_mfma_f32_16x16x32_fp8_fp8(cur.k[T][s2], qf[s2], sa[T], 0, 0, 0);
;     float sc[8]; bool vd[8]; float mx = -1e30f;
;     const bool act = lo == 0 || !SLC;
;     if (NOMASK) {
; #pragma unroll
;         for (int j = 0; j < 8; ++j) { sc[j] = sa[j >> 2][j & 3]; vd[j] = act; }
;         mx = fmaxf(fmaxf(fmaxf(sc[0], sc[1]), fmaxf(sc[2], sc[3])), fmaxf(fmaxf(sc[4], sc[5]), fmaxf(sc[6], sc[7])));
;         mx = act ? mx : -1e30f;
;     } else {
; #pragma unroll
;         for (int T = 0; T < 2; ++T)
; #pragma unroll
;             for (int r = 0; r < 4; ++r) { const int p = pos0 + 16 * T + 4 * kq + r; const bool v = (p >= lo) & (p <= hi); const float x = sa[T][r];
;                 sc[4 * T + r] = x; vd[4 * T + r] = v; mx = v ? fmaxf(mx, x) : mx; }
;     }
;     if (__builtin_amdgcn_ballot_w64(mx > st.m + 4.f) != 0ull) {
;         mx = fmaxf(mx, __shfl_xor(mx, 16)); mx = fmaxf(mx, __shfl_xor(mx, 32));
;         const float mn = fmaxf(st.m, mx), alpha = __builtin_amdgcn_exp2f(st.m - mn); st.m = mn; st.l *= alpha;
; #pragma unroll
;         for (int j = 0; j < 8; ++j) st.o[j] = st.o[j] * alpha;
;     }
;     f32x4 pa, pb; float ps = 0.f;
;     const float mref = st.m - 4.f;
;     if (NOMASK) {
; #pragma unroll
;         for (int j = 0; j < 4; ++j) { pa[j] = __builtin_amdgcn_exp2f(sc[j] - mref); pb[j] = __builtin_amdgcn_exp2f(sc[4 + j] - mref); }
;         if (SLC) {
; #pragma unroll
;             for (int j = 0; j < 4; ++j) { pa[j] = act ? pa[j] : 0.f; pb[j] = act ? pb[j] : 0.f; }
;         }
; #pragma unroll
;         for (int j = 0; j < 4; ++j) ps += pa[j] + pb[j];
;     } else {
; #pragma unroll
;         for (int j = 0; j < 4; ++j) { pa[j] = vd[j] ? __builtin_amdgcn_exp2f(sc[j] - mref) : 0.f; pb[j] = vd[4 + j] ? __builtin_amdgcn_exp2f(sc[4 + j] - mref) : 0.f; ps += pa[j] + pb[j]; }
;     }
;     st.l += ps;
;     const u32x2 pw = pack8_fp8(pa, pb);
.LBB0_867:
	s_and_b32 s13, s12, 0xfffffbff
	s_cmp_eq_u32 s13, 4
	s_cselect_b64 s[10:11], -1, 0
	s_lshl_b32 s14, s66, 7
	s_and_b32 s50, s14, 0x7fff800
	v_lshl_add_u64 v[10:11], v[86:87], 0, s[50:51]
	s_and_b32 s50, s14, 0x7fff000
	v_lshl_add_u64 v[244:245], v[10:11], 0, v[118:119]
	global_load_dwordx4 v[186:189], v[244:245], off
	global_load_dwordx4 v[190:193], v[244:245], off offset:1024
	global_load_dwordx4 v[194:197], v[244:245], off offset:2048
	global_load_dwordx4 v[198:201], v[244:245], off offset:3072
	v_lshl_add_u64 v[10:11], v[88:89], 0, s[50:51]
	v_lshl_add_u64 v[246:247], v[10:11], 0, v[118:119]
	global_load_dwordx4 v[170:173], v[246:247], off
	global_load_dwordx4 v[174:177], v[246:247], off offset:1024
	global_load_dwordx4 v[178:181], v[246:247], off offset:2048
	global_load_dwordx4 v[182:185], v[246:247], off offset:3072
	s_waitcnt vmcnt(20)
	v_mfma_f32_16x16x32_fp8_fp8 v[2:5], v[138:139], v[78:79], 0
	v_cmp_eq_u32_e32 vcc, s13, v209
	s_or_b64 s[10:11], s[10:11], vcc
	v_mov_b64_e32 v[74:75], v[38:39]
	v_mfma_f32_16x16x32_fp8_fp8 v[6:9], v[146:147], v[78:79], 0
	v_mov_b64_e32 v[70:71], v[42:43]
	v_mov_b64_e32 v[30:31], v[44:45]
	v_mov_b64_e32 v[26:27], v[48:49]
	v_mfma_f32_16x16x32_fp8_fp8 v[2:5], v[140:141], v[80:81], v[2:5]
	v_mov_b64_e32 v[22:23], v[52:53]
	v_mov_b64_e32 v[18:19], v[56:57]
	v_mov_b64_e32 v[14:15], v[60:61]
	v_mfma_f32_16x16x32_fp8_fp8 v[6:9], v[148:149], v[80:81], v[6:9]
	v_mov_b64_e32 v[72:73], v[36:37]
	v_mov_b64_e32 v[68:69], v[40:41]
	v_mov_b64_e32 v[32:33], v[46:47]
	v_mfma_f32_16x16x32_fp8_fp8 v[2:5], v[142:143], v[82:83], v[2:5]
	v_mov_b64_e32 v[28:29], v[50:51]
	v_mov_b64_e32 v[24:25], v[54:55]
	v_mov_b64_e32 v[20:21], v[58:59]
	v_mfma_f32_16x16x32_fp8_fp8 v[6:9], v[150:151], v[82:83], v[6:9]
	v_mov_b64_e32 v[16:17], v[62:63]
	v_mov_b32_e32 v133, v203
	v_mfma_f32_16x16x32_fp8_fp8 v[2:5], v[144:145], v[84:85], v[2:5]
	v_mfma_f32_16x16x32_fp8_fp8 v[6:9], v[152:153], v[84:85], v[6:9]
	s_nop 5
	v_max_f32_e32 v0, v3, v3
	v_max_f32_e32 v10, v2, v2
	v_max_f32_e32 v0, v10, v0
	v_max_f32_e32 v10, v5, v5
	v_max_f32_e32 v11, v4, v4
	v_max_f32_e32 v10, v11, v10
	v_max_f32_e32 v11, v9, v9
	v_max_f32_e32 v12, v8, v8
	v_max_f32_e32 v11, v12, v11
	v_max3_f32 v11, v6, v7, v11
	v_max3_f32 v0, v0, v10, v11
	v_cndmask_b32_e64 v34, v223, v0, s[10:11]
	v_mov_b64_e32 v[10:11], v[64:65]
	v_cmp_gt_f32_e32 vcc, v34, v204
	v_mov_b32_e32 v0, v202
	v_mov_b64_e32 v[12:13], v[66:67]
	s_cbranch_vccz .LBB0_869
	ds_bpermute_b32 v0, v227, v34
	v_max_f32_e32 v10, v34, v34
	s_waitcnt lgkmcnt(0)
	v_max_f32_e32 v0, v0, v0
	v_max_f32_e32 v0, v10, v0
	ds_bpermute_b32 v10, v226, v0
	s_waitcnt lgkmcnt(0)
	v_max3_f32 v0, v202, v0, v10
	v_sub_f32_e32 v10, v202, v0
	v_exp_f32_e32 v34, v10
	s_nop 0
	v_mul_f32_e32 v133, v203, v34
	v_pk_mul_f32 v[12:13], v[66:67], v[34:35] op_sel_hi:[1,0]
	v_pk_mul_f32 v[10:11], v[64:65], v[34:35] op_sel_hi:[1,0]
	v_pk_mul_f32 v[16:17], v[62:63], v[34:35] op_sel_hi:[1,0]
	v_pk_mul_f32 v[14:15], v[60:61], v[34:35] op_sel_hi:[1,0]
	v_pk_mul_f32 v[20:21], v[58:59], v[34:35] op_sel_hi:[1,0]
	v_pk_mul_f32 v[18:19], v[56:57], v[34:35] op_sel_hi:[1,0]
	v_pk_mul_f32 v[24:25], v[54:55], v[34:35] op_sel_hi:[1,0]
	v_pk_mul_f32 v[22:23], v[52:53], v[34:35] op_sel_hi:[1,0]
	v_pk_mul_f32 v[28:29], v[50:51], v[34:35] op_sel_hi:[1,0]
	v_pk_mul_f32 v[26:27], v[48:49], v[34:35] op_sel_hi:[1,0]
	v_pk_mul_f32 v[32:33], v[46:47], v[34:35] op_sel_hi:[1,0]
	v_pk_mul_f32 v[30:31], v[44:45], v[34:35] op_sel_hi:[1,0]
	v_pk_mul_f32 v[70:71], v[42:43], v[34:35] op_sel_hi:[1,0]
	v_pk_mul_f32 v[68:69], v[40:41], v[34:35] op_sel_hi:[1,0]
	v_pk_mul_f32 v[74:75], v[38:39], v[34:35] op_sel_hi:[1,0]
	v_pk_mul_f32 v[72:73], v[36:37], v[34:35] op_sel_hi:[1,0]
.LBB0_869:
	v_add_f32_e32 v34, -4.0, v0
	v_sub_f32_e32 v2, v2, v34
	v_sub_f32_e32 v6, v6, v34
	v_sub_f32_e32 v3, v3, v34
	v_sub_f32_e32 v7, v7, v34
	v_exp_f32_e32 v2, v2
	v_exp_f32_e32 v6, v6
	v_exp_f32_e32 v3, v3
	v_exp_f32_e32 v7, v7
	v_sub_f32_e32 v4, v4, v34
	v_sub_f32_e32 v8, v8, v34
	v_sub_f32_e32 v5, v5, v34
	v_sub_f32_e32 v9, v9, v34
	v_exp_f32_e32 v4, v4
	v_exp_f32_e32 v8, v8
	v_exp_f32_e32 v5, v5
	v_exp_f32_e32 v9, v9
	v_cndmask_b32_e64 v34, 0, v2, s[10:11]
	v_cndmask_b32_e64 v6, 0, v6, s[10:11]
	v_cndmask_b32_e64 v35, 0, v3, s[10:11]
	v_cndmask_b32_e64 v7, 0, v7, s[10:11]
	v_mov_b32_e32 v2, v1
	v_mov_b32_e32 v3, v1
	v_cvt_pk_fp8_f32 v2, v34, v35
	v_cvt_pk_fp8_f32 v3, v6, v7
	v_cndmask_b32_e64 v4, 0, v4, s[10:11]
	v_cndmask_b32_e64 v205, 0, v8, s[10:11]
	v_cndmask_b32_e64 v5, 0, v5, s[10:11]
	v_cndmask_b32_e64 v229, 0, v9, s[10:11]
	v_add_f32_e32 v6, v34, v6
	v_cvt_pk_fp8_f32 v2, v4, v5 op_sel:[0,0,1]
	v_cvt_pk_fp8_f32 v3, v205, v229 op_sel:[0,0,1]
	v_add_f32_e32 v6, 0, v6
	v_add_f32_e32 v7, v35, v7
	v_add_f32_e32 v6, v7, v6
	v_add_f32_e32 v4, v4, v205
	v_add_f32_e32 v4, v4, v6
	v_add_f32_e32 v5, v5, v229
	v_add_f32_e32 v4, v5, v4
	s_waitcnt vmcnt(19)
	v_mfma_f32_16x16x32_fp8_fp8 v[8:11], v[90:91], v[2:3], v[10:13]
	v_add_f32_e32 v133, v133, v4
	v_mfma_f32_16x16x32_fp8_fp8 v[12:15], v[92:93], v[2:3], v[14:17]
	s_waitcnt vmcnt(18)
	v_mfma_f32_16x16x32_fp8_fp8 v[16:19], v[94:95], v[2:3], v[18:21]
	v_mfma_f32_16x16x32_fp8_fp8 v[20:23], v[96:97], v[2:3], v[22:25]
	s_waitcnt vmcnt(17)
	v_mfma_f32_16x16x32_fp8_fp8 v[24:27], v[98:99], v[2:3], v[26:29]
	v_mfma_f32_16x16x32_fp8_fp8 v[32:35], v[100:101], v[2:3], v[30:33]
	s_waitcnt vmcnt(16)
	v_mfma_f32_16x16x32_fp8_fp8 v[28:31], v[102:103], v[2:3], v[68:71]
	v_mfma_f32_16x16x32_fp8_fp8 v[4:7], v[104:105], v[2:3], v[72:75]
	s_branch .LBB0_863
; template <bool SLC, bool NOMASK> ...
;     const int kq = lane >> 4;
;     const int pos0 = SLC ? (dcur & 0xfffff) : dcur;
;     const int lo = SLC ? ((((dcur >> 20) == qi) | ((dcur >> 20) == 4)) ? 0 : (1 << 30)) : lo_in;
;     load_frag8(nxt, KF, VF, SLC ? (dnext & 0xfffff) : dnext, lane);
;     f32x4 sa[2] = {(f32x4){0.f, 0.f, 0.f, 0.f}, (f32x4){0.f, 0.f, 0.f, 0.f}};
; #pragma unroll
;     for (int T = 0; T < 2; ++T)
; #pragma unroll
;         for (int s2 = 0; s2 < 4; ++s2) sa[T] = __builtin_amdgcn_mfma_f32_16x16x32_fp8_fp8(cur.k[T][s2], qf[s2], sa[T], 0, 0, 0);
;     float sc[8]; bool vd[8]; float mx = -1e30f;
;     const bool act = lo == 0 || !SLC;
;     if (NOMASK) {
; #pragma unroll
;         for (int j = 0; j < 8; ++j) { sc[j] = sa[j >> 2][j & 3]; vd[j] = act; }
;         mx = fmaxf(fmaxf(fmaxf(sc[0], sc[1]), fmaxf(sc[2], sc[3])), fmaxf(fmaxf(sc[4], sc[5]), fmaxf(sc[6], sc[7])));
;         mx = act ? mx : -1e30f;
;     } else {
; #pragma unroll
;         for (int T = 0; T < 2; ++T)
; #pragma unroll
;             for (int r = 0; r < 4; ++r) { const int p = pos0 + 16 * T + 4 * kq + r; const bool v = (p >= lo) & (p <= hi); const float x = sa[T][r];
;                 sc[4 * T + r] = x; vd[4 * T + r] = v; mx = v ? fmaxf(mx, x) : mx; }
;     }
;     if (__builtin_amdgcn_ballot_w64(mx > st.m + 4.f) != 0ull) {
;         mx = fmaxf(mx, __shfl_xor(mx, 16)); mx = fmaxf(mx, __shfl_xor(mx, 32));
;         const float mn = fmaxf(st.m, mx), alpha = __builtin_amdgcn_exp2f(st.m - mn); st.m = mn; st.l *= alpha;
; #pragma unroll
;         for (int j = 0; j < 8; ++j) st.o[j] = st.o[j] * alpha;
;     }
;     f32x4 pa, pb; float ps = 0.f;
;     const float mref = st.m - 4.f;
;     if (NOMASK) {
; #pragma unroll
;         for (int j = 0; j < 4; ++j) { pa[j] = __builtin_amdgcn_exp2f(sc[j] - mref); pb[j] = __builtin_amdgcn_exp2f(sc[4 + j] - mref); }
;         if (SLC) {
; #pragma unroll
;             for (int j = 0; j < 4; ++j) { pa[j] = act ? pa[j] : 0.f; pb[j] = act ? pb[j] : 0.f; }
;         }
; #pragma unroll
;         for (int j = 0; j < 4; ++j) ps += pa[j] + pb[j];
;     } else {
; #pragma unroll
;         for (int j = 0; j < 4; ++j) { pa[j] = vd[j] ? __builtin_amdgcn_exp2f(sc[j] - mref) : 0.f; pb[j] = vd[4 + j] ? __builtin_amdgcn_exp2f(sc[4 + j] - mref) : 0.f; ps += pa[j] + pb[j]; }
;     }
;     st.l += ps;
;     const u32x2 pw = pack8_fp8(pa, pb);
.LBB0_870:
	s_cmp_eq_u32 s12, 4
	s_cselect_b64 s[10:11], -1, 0
	s_lshl_b32 s13, s66, 7
	s_and_b32 s50, s13, 0x7fff800
	v_lshl_add_u64 v[10:11], v[86:87], 0, s[50:51]
	s_and_b32 s50, s13, 0x7fff000
	v_lshl_add_u64 v[244:245], v[10:11], 0, v[118:119]
	global_load_dwordx4 v[186:189], v[244:245], off
	global_load_dwordx4 v[190:193], v[244:245], off offset:1024
	global_load_dwordx4 v[194:197], v[244:245], off offset:2048
	global_load_dwordx4 v[198:201], v[244:245], off offset:3072
	v_lshl_add_u64 v[10:11], v[88:89], 0, s[50:51]
	v_lshl_add_u64 v[246:247], v[10:11], 0, v[118:119]
	global_load_dwordx4 v[170:173], v[246:247], off
	global_load_dwordx4 v[174:177], v[246:247], off offset:1024
	global_load_dwordx4 v[178:181], v[246:247], off offset:2048
	global_load_dwordx4 v[182:185], v[246:247], off offset:3072
	s_waitcnt vmcnt(20)
	v_mfma_f32_16x16x32_fp8_fp8 v[2:5], v[138:139], v[78:79], 0
	s_and_b32 s13, s59, 0xfffff
	v_cmp_eq_u32_e32 vcc, s12, v209
	v_add_u32_e32 v0, s13, v211
	v_mfma_f32_16x16x32_fp8_fp8 v[2:5], v[140:141], v[80:81], v[2:5]
	s_or_b64 s[18:19], s[10:11], vcc
	v_cmp_le_i32_e32 vcc, v0, v132
	s_and_b64 s[16:17], s[18:19], vcc
	v_mfma_f32_16x16x32_fp8_fp8 v[2:5], v[142:143], v[82:83], v[2:5]
	v_cmp_lt_i32_e32 vcc, v0, v132
	s_and_b64 s[12:13], s[18:19], vcc
	v_mfma_f32_16x16x32_fp8_fp8 v[6:9], v[146:147], v[78:79], 0
	v_mfma_f32_16x16x32_fp8_fp8 v[2:5], v[144:145], v[84:85], v[2:5]
	v_mfma_f32_16x16x32_fp8_fp8 v[6:9], v[148:149], v[80:81], v[6:9]
	v_mfma_f32_16x16x32_fp8_fp8 v[6:9], v[150:151], v[82:83], v[6:9]
	s_nop 3
	v_max_f32_e32 v10, v2, v2
	v_max_f32_e32 v10, 0xf149f2ca, v10
	v_cndmask_b32_e64 v10, v223, v10, s[16:17]
	v_max_f32_e32 v11, v3, v3
	v_max_f32_e32 v11, v10, v11
	v_cndmask_b32_e64 v10, v10, v11, s[12:13]
	v_add_u32_e32 v11, 2, v0
	v_cmp_le_i32_e32 vcc, v11, v132
	v_max_f32_e32 v11, v4, v4
	v_max_f32_e32 v11, v10, v11
	s_and_b64 s[14:15], s[18:19], vcc
	v_mfma_f32_16x16x32_fp8_fp8 v[6:9], v[152:153], v[84:85], v[6:9]
	v_cndmask_b32_e64 v10, v10, v11, s[14:15]
	v_add_u32_e32 v11, 3, v0
	v_cmp_le_i32_e32 vcc, v11, v132
	v_max_f32_e32 v11, v5, v5
	v_max_f32_e32 v11, v10, v11
	s_and_b64 s[10:11], s[18:19], vcc
	v_cndmask_b32_e64 v10, v10, v11, s[10:11]
	v_add_u32_e32 v11, 16, v0
	v_cmp_le_i32_e32 vcc, v11, v132
	v_max_f32_e32 v11, v6, v6
	v_max_f32_e32 v11, v10, v11
	s_and_b64 s[24:25], s[18:19], vcc
	v_cndmask_b32_e64 v10, v10, v11, s[24:25]
	v_add_u32_e32 v11, 17, v0
	v_cmp_le_i32_e32 vcc, v11, v132
	v_max_f32_e32 v11, v10, v10
	v_max_f32_e32 v12, v7, v7
	v_max_f32_e32 v11, v11, v12
	s_and_b64 s[20:21], s[18:19], vcc
	v_cndmask_b32_e64 v10, v10, v11, s[20:21]
	v_add_u32_e32 v11, 18, v0
	v_cmp_le_i32_e32 vcc, v11, v132
	v_max_f32_e32 v11, v10, v10
	v_max_f32_e32 v12, v8, v8
	v_max_f32_e32 v11, v11, v12
	s_and_b64 s[22:23], s[18:19], vcc
	v_cndmask_b32_e64 v10, v10, v11, s[22:23]
	v_add_u32_e32 v0, 19, v0
	v_cmp_le_i32_e32 vcc, v0, v132
	v_max_f32_e32 v0, v10, v10
	v_max_f32_e32 v11, v9, v9
	v_max_f32_e32 v0, v0, v11
	s_and_b64 s[18:19], s[18:19], vcc
	v_cndmask_b32_e64 v0, v10, v0, s[18:19]
	v_cmp_gt_f32_e32 vcc, v0, v204
	s_cbranch_vccz .LBB0_872
	ds_bpermute_b32 v10, v227, v0
	v_max_f32_e32 v0, v0, v0
	s_waitcnt lgkmcnt(0)
	v_max_f32_e32 v10, v10, v10
	v_max_f32_e32 v0, v0, v10
	ds_bpermute_b32 v10, v226, v0
	s_waitcnt lgkmcnt(0)
	v_max3_f32 v10, v202, v0, v10
	v_sub_f32_e32 v0, v202, v10
	v_exp_f32_e32 v0, v0
	v_mov_b32_e32 v202, v10
	v_mul_f32_e32 v203, v203, v0
	v_pk_mul_f32 v[66:67], v[66:67], v[0:1] op_sel_hi:[1,0]
	v_pk_mul_f32 v[64:65], v[64:65], v[0:1] op_sel_hi:[1,0]
	v_pk_mul_f32 v[62:63], v[62:63], v[0:1] op_sel_hi:[1,0]
	v_pk_mul_f32 v[60:61], v[60:61], v[0:1] op_sel_hi:[1,0]
	v_pk_mul_f32 v[58:59], v[58:59], v[0:1] op_sel_hi:[1,0]
	v_pk_mul_f32 v[56:57], v[56:57], v[0:1] op_sel_hi:[1,0]
	v_pk_mul_f32 v[54:55], v[54:55], v[0:1] op_sel_hi:[1,0]
	v_pk_mul_f32 v[52:53], v[52:53], v[0:1] op_sel_hi:[1,0]
	v_pk_mul_f32 v[50:51], v[50:51], v[0:1] op_sel_hi:[1,0]
	v_pk_mul_f32 v[48:49], v[48:49], v[0:1] op_sel_hi:[1,0]
	v_pk_mul_f32 v[46:47], v[46:47], v[0:1] op_sel_hi:[1,0]
	v_pk_mul_f32 v[44:45], v[44:45], v[0:1] op_sel_hi:[1,0]
	v_pk_mul_f32 v[42:43], v[42:43], v[0:1] op_sel_hi:[1,0]
	v_pk_mul_f32 v[40:41], v[40:41], v[0:1] op_sel_hi:[1,0]
	v_pk_mul_f32 v[38:39], v[38:39], v[0:1] op_sel_hi:[1,0]
	v_pk_mul_f32 v[36:37], v[36:37], v[0:1] op_sel_hi:[1,0]
.LBB0_872:
	v_add_f32_e32 v0, -4.0, v202
	v_sub_f32_e32 v2, v2, v0
	v_exp_f32_e32 v2, v2
	v_sub_f32_e32 v6, v6, v0
	v_exp_f32_e32 v6, v6
	v_sub_f32_e32 v4, v4, v0
	v_cndmask_b32_e64 v28, 0, v2, s[16:17]
	v_sub_f32_e32 v2, v3, v0
	v_exp_f32_e32 v2, v2
	v_sub_f32_e32 v3, v7, v0
	v_exp_f32_e32 v3, v3
	v_sub_f32_e32 v7, v8, v0
	v_cndmask_b32_e64 v29, 0, v2, s[12:13]
	v_sub_f32_e32 v2, v5, v0
	v_sub_f32_e32 v0, v9, v0
	v_cndmask_b32_e64 v6, 0, v6, s[24:25]
	v_exp_f32_e32 v4, v4
	v_exp_f32_e32 v7, v7
	v_cndmask_b32_e64 v30, 0, v3, s[20:21]
	v_exp_f32_e32 v5, v2
	v_exp_f32_e32 v0, v0
	v_mov_b32_e32 v2, v1
	v_mov_b32_e32 v3, v1
	v_cvt_pk_fp8_f32 v2, v28, v29
	v_cvt_pk_fp8_f32 v3, v6, v30
	v_cndmask_b32_e64 v4, 0, v4, s[14:15]
	v_cndmask_b32_e64 v7, 0, v7, s[22:23]
	v_cndmask_b32_e64 v5, 0, v5, s[10:11]
	v_cndmask_b32_e64 v0, 0, v0, s[18:19]
	v_cvt_pk_fp8_f32 v2, v4, v5 op_sel:[0,0,1]
	v_cvt_pk_fp8_f32 v3, v7, v0 op_sel:[0,0,1]
	v_add_f32_e32 v6, v28, v6
	v_add_f32_e32 v6, 0, v6
	v_add_f32_e32 v28, v29, v30
	v_add_f32_e32 v6, v28, v6
	v_add_f32_e32 v4, v4, v7
	v_add_f32_e32 v4, v4, v6
	v_add_f32_e32 v0, v5, v0
	s_waitcnt vmcnt(19)
	v_mfma_f32_16x16x32_fp8_fp8 v[8:11], v[90:91], v[2:3], v[64:67]
	v_add_f32_e32 v0, v0, v4
	v_add_f32_e32 v133, v203, v0
	v_mov_b32_e32 v0, v202
	v_mfma_f32_16x16x32_fp8_fp8 v[12:15], v[92:93], v[2:3], v[60:63]
	s_waitcnt vmcnt(18)
	v_mfma_f32_16x16x32_fp8_fp8 v[16:19], v[94:95], v[2:3], v[56:59]
	v_mfma_f32_16x16x32_fp8_fp8 v[20:23], v[96:97], v[2:3], v[52:55]
	s_waitcnt vmcnt(17)
	v_mfma_f32_16x16x32_fp8_fp8 v[24:27], v[98:99], v[2:3], v[48:51]
	v_mfma_f32_16x16x32_fp8_fp8 v[32:35], v[100:101], v[2:3], v[44:47]
	s_waitcnt vmcnt(16)
	v_mfma_f32_16x16x32_fp8_fp8 v[28:31], v[102:103], v[2:3], v[40:43]
	v_mfma_f32_16x16x32_fp8_fp8 v[4:7], v[104:105], v[2:3], v[36:39]
	s_add_i32 s10, s58, -3
	s_cmp_ge_u32 s10, s56
	s_mov_b64 s[10:11], -1
	s_cbranch_scc0 .LBB0_864

; template <bool SLC, bool NOMASK> ...
;     const int kq = lane >> 4;
;     const int pos0 = SLC ? (dcur & 0xfffff) : dcur;
;     const int lo = SLC ? ((((dcur >> 20) == qi) | ((dcur >> 20) == 4)) ? 0 : (1 << 30)) : lo_in;
;     load_frag8(nxt, KF, VF, SLC ? (dnext & 0xfffff) : dnext, lane);
;     f32x4 sa[2] = {(f32x4){0.f, 0.f, 0.f, 0.f}, (f32x4){0.f, 0.f, 0.f, 0.f}};
; #pragma unroll
;     for (int T = 0; T < 2; ++T)
; #pragma unroll
;         for (int s2 = 0; s2 < 4; ++s2) sa[T] = __builtin_amdgcn_mfma_f32_16x16x32_fp8_fp8(cur.k[T][s2], qf[s2], sa[T], 0, 0, 0);
;     float sc[8]; bool vd[8]; float mx = -1e30f;
;     const bool act = lo == 0 || !SLC;
;     if (NOMASK) {
; #pragma unroll
;         for (int j = 0; j < 8; ++j) { sc[j] = sa[j >> 2][j & 3]; vd[j] = act; }
;         mx = fmaxf(fmaxf(fmaxf(sc[0], sc[1]), fmaxf(sc[2], sc[3])), fmaxf(fmaxf(sc[4], sc[5]), fmaxf(sc[6], sc[7])));
;         mx = act ? mx : -1e30f;
;     } else {
; #pragma unroll
;         for (int T = 0; T < 2; ++T)
; #pragma unroll
;             for (int r = 0; r < 4; ++r) { const int p = pos0 + 16 * T + 4 * kq + r; const bool v = (p >= lo) & (p <= hi); const float x = sa[T][r];
;                 sc[4 * T + r] = x; vd[4 * T + r] = v; mx = v ? fmaxf(mx, x) : mx; }
;     }
;     if (__builtin_amdgcn_ballot_w64(mx > st.m + 4.f) != 0ull) {
;         mx = fmaxf(mx, __shfl_xor(mx, 16)); mx = fmaxf(mx, __shfl_xor(mx, 32));
;         const float mn = fmaxf(st.m, mx), alpha = __builtin_amdgcn_exp2f(st.m - mn); st.m = mn; st.l *= alpha;
; #pragma unroll
;         for (int j = 0; j < 8; ++j) st.o[j] = st.o[j] * alpha;
;     }
;     f32x4 pa, pb; float ps = 0.f;
;     const float mref = st.m - 4.f;
;     if (NOMASK) {
; #pragma unroll
;         for (int j = 0; j < 4; ++j) { pa[j] = __builtin_amdgcn_exp2f(sc[j] - mref); pb[j] = __builtin_amdgcn_exp2f(sc[4 + j] - mref); }
;         if (SLC) {
; #pragma unroll
;             for (int j = 0; j < 4; ++j) { pa[j] = act ? pa[j] : 0.f; pb[j] = act ? pb[j] : 0.f; }
;         }
; #pragma unroll
;         for (int j = 0; j < 4; ++j) ps += pa[j] + pb[j];
;     } else {
; #pragma unroll
;         for (int j = 0; j < 4; ++j) { pa[j] = vd[j] ? __builtin_amdgcn_exp2f(sc[j] - mref) : 0.f; pb[j] = vd[4 + j] ? __builtin_amdgcn_exp2f(sc[4 + j] - mref) : 0.f; ps += pa[j] + pb[j]; }
;     }
;     st.l += ps;
;     const u32x2 pw = pack8_fp8(pa, pb);
.LBB0_874:
	s_and_b32 s13, s12, 0xfffffbff
	s_cmp_eq_u32 s13, 4
	s_cselect_b64 s[10:11], -1, 0
	s_lshl_b32 s14, s59, 7
	s_and_b32 s50, s14, 0x7fff800
	v_lshl_add_u64 v[44:45], v[86:87], 0, s[50:51]
	s_and_b32 s50, s14, 0x7fff000
	v_lshl_add_u64 v[244:245], v[44:45], 0, v[118:119]
	global_load_dwordx4 v[138:141], v[244:245], off
	global_load_dwordx4 v[142:145], v[244:245], off offset:1024
	global_load_dwordx4 v[146:149], v[244:245], off offset:2048
	global_load_dwordx4 v[150:153], v[244:245], off offset:3072
	v_lshl_add_u64 v[44:45], v[88:89], 0, s[50:51]
	v_lshl_add_u64 v[246:247], v[44:45], 0, v[118:119]
	global_load_dwordx4 v[90:93], v[246:247], off
	global_load_dwordx4 v[94:97], v[246:247], off offset:1024
	global_load_dwordx4 v[98:101], v[246:247], off offset:2048
	global_load_dwordx4 v[102:105], v[246:247], off offset:3072
	s_waitcnt vmcnt(20)
	v_mfma_f32_16x16x32_fp8_fp8 v[36:39], v[154:155], v[78:79], 0
	v_cmp_eq_u32_e32 vcc, s13, v209
	s_or_b64 s[10:11], s[10:11], vcc
	v_mov_b64_e32 v[74:75], v[6:7]
	v_mfma_f32_16x16x32_fp8_fp8 v[40:43], v[162:163], v[78:79], 0
	v_mov_b64_e32 v[70:71], v[30:31]
	v_mov_b64_e32 v[66:67], v[34:35]
	v_mov_b64_e32 v[62:63], v[26:27]
	v_mfma_f32_16x16x32_fp8_fp8 v[36:39], v[156:157], v[80:81], v[36:39]
	v_mov_b64_e32 v[58:59], v[22:23]
	v_mov_b64_e32 v[54:55], v[18:19]
	v_mov_b64_e32 v[50:51], v[14:15]
	v_mfma_f32_16x16x32_fp8_fp8 v[40:43], v[164:165], v[80:81], v[40:43]
	v_mov_b32_e32 v203, v0
	v_mov_b64_e32 v[72:73], v[4:5]
	v_mov_b64_e32 v[68:69], v[28:29]
	v_mfma_f32_16x16x32_fp8_fp8 v[36:39], v[158:159], v[82:83], v[36:39]
	v_mov_b64_e32 v[64:65], v[32:33]
	v_mov_b64_e32 v[60:61], v[24:25]
	v_mov_b64_e32 v[56:57], v[20:21]
	v_mfma_f32_16x16x32_fp8_fp8 v[40:43], v[166:167], v[82:83], v[40:43]
	v_mov_b64_e32 v[52:53], v[16:17]
	v_mov_b64_e32 v[48:49], v[12:13]
	v_mfma_f32_16x16x32_fp8_fp8 v[36:39], v[160:161], v[84:85], v[36:39]
	v_mfma_f32_16x16x32_fp8_fp8 v[40:43], v[168:169], v[84:85], v[40:43]
	s_nop 5
	v_max_f32_e32 v3, v37, v37
	v_max_f32_e32 v44, v36, v36
	v_max_f32_e32 v3, v44, v3
	v_max_f32_e32 v44, v39, v39
	v_max_f32_e32 v45, v38, v38
	v_max_f32_e32 v44, v45, v44
	v_max_f32_e32 v45, v43, v43
	v_max_f32_e32 v46, v42, v42
	v_max_f32_e32 v45, v46, v45
	v_max3_f32 v45, v40, v41, v45
	v_max3_f32 v3, v3, v44, v45
	v_cndmask_b32_e64 v202, v223, v3, s[10:11]
	v_mov_b64_e32 v[46:47], v[10:11]
	v_cmp_gt_f32_e32 vcc, v202, v2
	v_mov_b64_e32 v[44:45], v[8:9]
	v_mov_b32_e32 v3, v133
	s_cbranch_vccz .LBB0_876
	ds_bpermute_b32 v3, v227, v202
	v_max_f32_e32 v44, v202, v202
	s_waitcnt lgkmcnt(0)
	v_max_f32_e32 v3, v3, v3
	v_max_f32_e32 v3, v44, v3
	ds_bpermute_b32 v44, v226, v3
	s_waitcnt lgkmcnt(0)
	v_max3_f32 v203, v0, v3, v44
	v_sub_f32_e32 v3, v0, v203
	v_exp_f32_e32 v72, v3
	s_nop 0
	v_mul_f32_e32 v3, v133, v72
	v_pk_mul_f32 v[46:47], v[10:11], v[72:73] op_sel_hi:[1,0]
	v_pk_mul_f32 v[44:45], v[8:9], v[72:73] op_sel_hi:[1,0]
	v_pk_mul_f32 v[50:51], v[14:15], v[72:73] op_sel_hi:[1,0]
	v_pk_mul_f32 v[48:49], v[12:13], v[72:73] op_sel_hi:[1,0]
	v_pk_mul_f32 v[54:55], v[18:19], v[72:73] op_sel_hi:[1,0]
	v_pk_mul_f32 v[52:53], v[16:17], v[72:73] op_sel_hi:[1,0]
	v_pk_mul_f32 v[58:59], v[22:23], v[72:73] op_sel_hi:[1,0]
	v_pk_mul_f32 v[56:57], v[20:21], v[72:73] op_sel_hi:[1,0]
	v_pk_mul_f32 v[62:63], v[26:27], v[72:73] op_sel_hi:[1,0]
	v_pk_mul_f32 v[60:61], v[24:25], v[72:73] op_sel_hi:[1,0]
	v_pk_mul_f32 v[66:67], v[34:35], v[72:73] op_sel_hi:[1,0]
	v_pk_mul_f32 v[64:65], v[32:33], v[72:73] op_sel_hi:[1,0]
	v_pk_mul_f32 v[70:71], v[30:31], v[72:73] op_sel_hi:[1,0]
	v_pk_mul_f32 v[68:69], v[28:29], v[72:73] op_sel_hi:[1,0]
	v_pk_mul_f32 v[74:75], v[6:7], v[72:73] op_sel_hi:[1,0]
	v_pk_mul_f32 v[72:73], v[4:5], v[72:73] op_sel_hi:[1,0]
.LBB0_876:
	v_add_f32_e32 v202, -4.0, v203
	v_sub_f32_e32 v36, v36, v202
	v_sub_f32_e32 v40, v40, v202
	v_sub_f32_e32 v37, v37, v202
	v_sub_f32_e32 v41, v41, v202
	v_exp_f32_e32 v36, v36
	v_exp_f32_e32 v40, v40
	v_exp_f32_e32 v37, v37
	v_exp_f32_e32 v41, v41
	v_sub_f32_e32 v38, v38, v202
	v_sub_f32_e32 v42, v42, v202
	v_sub_f32_e32 v39, v39, v202
	v_sub_f32_e32 v43, v43, v202
	v_exp_f32_e32 v38, v38
	v_exp_f32_e32 v42, v42
	v_exp_f32_e32 v39, v39
	v_exp_f32_e32 v43, v43
	v_cndmask_b32_e64 v202, 0, v36, s[10:11]
	v_cndmask_b32_e64 v204, 0, v40, s[10:11]
	v_cndmask_b32_e64 v205, 0, v37, s[10:11]
	v_cndmask_b32_e64 v229, 0, v41, s[10:11]
	v_mov_b32_e32 v230, v1
	v_mov_b32_e32 v231, v1
	v_cvt_pk_fp8_f32 v230, v202, v205
	v_cvt_pk_fp8_f32 v231, v204, v229
	v_cndmask_b32_e64 v232, 0, v38, s[10:11]
	v_cndmask_b32_e64 v233, 0, v42, s[10:11]
	v_cndmask_b32_e64 v234, 0, v39, s[10:11]
	v_cndmask_b32_e64 v235, 0, v43, s[10:11]
	v_cvt_pk_fp8_f32 v230, v232, v234 op_sel:[0,0,1]
	v_cvt_pk_fp8_f32 v231, v233, v235 op_sel:[0,0,1]
	s_nop 0
	s_waitcnt vmcnt(19)
	v_mfma_f32_16x16x32_fp8_fp8 v[40:43], v[108:109], v[230:231], v[48:51]
	v_mfma_f32_16x16x32_fp8_fp8 v[48:51], v[112:113], v[230:231], v[56:59]
	s_nop 2
	v_add_f32_e32 v56, v202, v204
	s_waitcnt vmcnt(18)
	v_mfma_f32_16x16x32_fp8_fp8 v[36:39], v[106:107], v[230:231], v[44:47]
	v_mfma_f32_16x16x32_fp8_fp8 v[44:47], v[110:111], v[230:231], v[52:55]
	s_waitcnt vmcnt(17)
	v_mfma_f32_16x16x32_fp8_fp8 v[52:55], v[114:115], v[230:231], v[60:63]
	s_nop 2
	v_add_f32_e32 v60, 0, v56
	v_add_f32_e32 v61, v205, v229
	v_add_f32_e32 v60, v61, v60
	v_add_f32_e32 v61, v232, v233
	v_mfma_f32_16x16x32_fp8_fp8 v[56:59], v[116:117], v[230:231], v[64:67]
	s_nop 2
	v_add_f32_e32 v64, v61, v60
	v_add_f32_e32 v65, v234, v235
	v_add_f32_e32 v64, v65, v64
	s_waitcnt vmcnt(16)
	v_mfma_f32_16x16x32_fp8_fp8 v[60:63], v[134:135], v[230:231], v[68:71]
	v_add_f32_e32 v204, v3, v64
	v_mfma_f32_16x16x32_fp8_fp8 v[64:67], v[136:137], v[230:231], v[72:75]
	s_branch .LBB0_866
; template <bool SLC, bool NOMASK> ...
;     const int kq = lane >> 4;
;     const int pos0 = SLC ? (dcur & 0xfffff) : dcur;
;     const int lo = SLC ? ((((dcur >> 20) == qi) | ((dcur >> 20) == 4)) ? 0 : (1 << 30)) : lo_in;
;     load_frag8(nxt, KF, VF, SLC ? (dnext & 0xfffff) : dnext, lane);
;     f32x4 sa[2] = {(f32x4){0.f, 0.f, 0.f, 0.f}, (f32x4){0.f, 0.f, 0.f, 0.f}};
; #pragma unroll
;     for (int T = 0; T < 2; ++T)
; #pragma unroll
;         for (int s2 = 0; s2 < 4; ++s2) sa[T] = __builtin_amdgcn_mfma_f32_16x16x32_fp8_fp8(cur.k[T][s2], qf[s2], sa[T], 0, 0, 0);
;     float sc[8]; bool vd[8]; float mx = -1e30f;
;     const bool act = lo == 0 || !SLC;
;     if (NOMASK) {
; #pragma unroll
;         for (int j = 0; j < 8; ++j) { sc[j] = sa[j >> 2][j & 3]; vd[j] = act; }
;         mx = fmaxf(fmaxf(fmaxf(sc[0], sc[1]), fmaxf(sc[2], sc[3])), fmaxf(fmaxf(sc[4], sc[5]), fmaxf(sc[6], sc[7])));
;         mx = act ? mx : -1e30f;
;     } else {
; #pragma unroll
;         for (int T = 0; T < 2; ++T)
; #pragma unroll
;             for (int r = 0; r < 4; ++r) { const int p = pos0 + 16 * T + 4 * kq + r; const bool v = (p >= lo) & (p <= hi); const float x = sa[T][r];
;                 sc[4 * T + r] = x; vd[4 * T + r] = v; mx = v ? fmaxf(mx, x) : mx; }
;     }
;     if (__builtin_amdgcn_ballot_w64(mx > st.m + 4.f) != 0ull) {
;         mx = fmaxf(mx, __shfl_xor(mx, 16)); mx = fmaxf(mx, __shfl_xor(mx, 32));
;         const float mn = fmaxf(st.m, mx), alpha = __builtin_amdgcn_exp2f(st.m - mn); st.m = mn; st.l *= alpha;
; #pragma unroll
;         for (int j = 0; j < 8; ++j) st.o[j] = st.o[j] * alpha;
;     }
;     f32x4 pa, pb; float ps = 0.f;
;     const float mref = st.m - 4.f;
;     if (NOMASK) {
; #pragma unroll
;         for (int j = 0; j < 4; ++j) { pa[j] = __builtin_amdgcn_exp2f(sc[j] - mref); pb[j] = __builtin_amdgcn_exp2f(sc[4 + j] - mref); }
;         if (SLC) {
; #pragma unroll
;             for (int j = 0; j < 4; ++j) { pa[j] = act ? pa[j] : 0.f; pb[j] = act ? pb[j] : 0.f; }
;         }
; #pragma unroll
;         for (int j = 0; j < 4; ++j) ps += pa[j] + pb[j];
;     } else {
; #pragma unroll
;         for (int j = 0; j < 4; ++j) { pa[j] = vd[j] ? __builtin_amdgcn_exp2f(sc[j] - mref) : 0.f; pb[j] = vd[4 + j] ? __builtin_amdgcn_exp2f(sc[4 + j] - mref) : 0.f; ps += pa[j] + pb[j]; }
;     }
;     st.l += ps;
;     const u32x2 pw = pack8_fp8(pa, pb);
.LBB0_877:
	s_cmp_eq_u32 s12, 4
	s_cselect_b64 s[10:11], -1, 0
	s_lshl_b32 s13, s59, 7
	s_and_b32 s50, s13, 0x7fff800
	v_lshl_add_u64 v[44:45], v[86:87], 0, s[50:51]
	s_and_b32 s50, s13, 0x7fff000
	v_lshl_add_u64 v[244:245], v[44:45], 0, v[118:119]
	global_load_dwordx4 v[138:141], v[244:245], off
	global_load_dwordx4 v[142:145], v[244:245], off offset:1024
	global_load_dwordx4 v[146:149], v[244:245], off offset:2048
	global_load_dwordx4 v[150:153], v[244:245], off offset:3072
	v_lshl_add_u64 v[44:45], v[88:89], 0, s[50:51]
	v_lshl_add_u64 v[246:247], v[44:45], 0, v[118:119]
	global_load_dwordx4 v[90:93], v[246:247], off
	global_load_dwordx4 v[94:97], v[246:247], off offset:1024
	global_load_dwordx4 v[98:101], v[246:247], off offset:2048
	global_load_dwordx4 v[102:105], v[246:247], off offset:3072
	s_waitcnt vmcnt(20)
	v_mfma_f32_16x16x32_fp8_fp8 v[36:39], v[154:155], v[78:79], 0
	s_and_b32 s13, s97, 0xfffff
	v_cmp_eq_u32_e32 vcc, s12, v209
	v_add_u32_e32 v3, s13, v211
	v_mfma_f32_16x16x32_fp8_fp8 v[36:39], v[156:157], v[80:81], v[36:39]
	s_or_b64 s[18:19], s[10:11], vcc
	v_cmp_le_i32_e32 vcc, v3, v132
	s_and_b64 s[16:17], s[18:19], vcc
	v_mfma_f32_16x16x32_fp8_fp8 v[36:39], v[158:159], v[82:83], v[36:39]
	v_cmp_lt_i32_e32 vcc, v3, v132
	s_and_b64 s[12:13], s[18:19], vcc
	v_mfma_f32_16x16x32_fp8_fp8 v[40:43], v[162:163], v[78:79], 0
	v_mfma_f32_16x16x32_fp8_fp8 v[36:39], v[160:161], v[84:85], v[36:39]
	v_mfma_f32_16x16x32_fp8_fp8 v[40:43], v[164:165], v[80:81], v[40:43]
	v_mfma_f32_16x16x32_fp8_fp8 v[40:43], v[166:167], v[82:83], v[40:43]
	s_nop 3
	v_max_f32_e32 v44, v36, v36
	v_max_f32_e32 v44, 0xf149f2ca, v44
	v_cndmask_b32_e64 v44, v223, v44, s[16:17]
	v_max_f32_e32 v45, v37, v37
	v_max_f32_e32 v45, v44, v45
	v_cndmask_b32_e64 v44, v44, v45, s[12:13]
	v_add_u32_e32 v45, 2, v3
	v_cmp_le_i32_e32 vcc, v45, v132
	v_max_f32_e32 v45, v38, v38
	v_max_f32_e32 v45, v44, v45
	s_and_b64 s[14:15], s[18:19], vcc
	v_mfma_f32_16x16x32_fp8_fp8 v[40:43], v[168:169], v[84:85], v[40:43]
	v_cndmask_b32_e64 v44, v44, v45, s[14:15]
	v_add_u32_e32 v45, 3, v3
	v_cmp_le_i32_e32 vcc, v45, v132
	v_max_f32_e32 v45, v39, v39
	v_max_f32_e32 v45, v44, v45
	s_and_b64 s[10:11], s[18:19], vcc
	v_cndmask_b32_e64 v44, v44, v45, s[10:11]
	v_add_u32_e32 v45, 16, v3
	v_cmp_le_i32_e32 vcc, v45, v132
	v_max_f32_e32 v45, v40, v40
	v_max_f32_e32 v45, v44, v45
	s_and_b64 s[24:25], s[18:19], vcc
	v_cndmask_b32_e64 v44, v44, v45, s[24:25]
	v_add_u32_e32 v45, 17, v3
	v_cmp_le_i32_e32 vcc, v45, v132
	v_max_f32_e32 v45, v44, v44
	v_max_f32_e32 v46, v41, v41
	v_max_f32_e32 v45, v45, v46
	s_and_b64 s[20:21], s[18:19], vcc
	v_cndmask_b32_e64 v44, v44, v45, s[20:21]
	v_add_u32_e32 v45, 18, v3
	v_cmp_le_i32_e32 vcc, v45, v132
	v_max_f32_e32 v45, v44, v44
	v_max_f32_e32 v46, v42, v42
	v_max_f32_e32 v45, v45, v46
	s_and_b64 s[22:23], s[18:19], vcc
	v_cndmask_b32_e64 v44, v44, v45, s[22:23]
	v_add_u32_e32 v3, 19, v3
	v_cmp_le_i32_e32 vcc, v3, v132
	v_max_f32_e32 v3, v44, v44
	v_max_f32_e32 v45, v43, v43
	v_max_f32_e32 v3, v3, v45
	s_and_b64 s[18:19], s[18:19], vcc
	v_cndmask_b32_e64 v3, v44, v3, s[18:19]
	v_cmp_gt_f32_e32 vcc, v3, v2
	s_cbranch_vccz .LBB0_879
	ds_bpermute_b32 v2, v227, v3
	v_max_f32_e32 v3, v3, v3
	s_waitcnt lgkmcnt(0)
	v_max_f32_e32 v2, v2, v2
	v_max_f32_e32 v2, v3, v2
	ds_bpermute_b32 v3, v226, v2
	s_waitcnt lgkmcnt(0)
	v_max3_f32 v2, v0, v2, v3
	v_sub_f32_e32 v0, v0, v2
	v_exp_f32_e32 v0, v0
	s_nop 0
	v_mul_f32_e32 v133, v133, v0
	v_pk_mul_f32 v[10:11], v[10:11], v[0:1] op_sel_hi:[1,0]
	v_pk_mul_f32 v[8:9], v[8:9], v[0:1] op_sel_hi:[1,0]
	v_pk_mul_f32 v[14:15], v[14:15], v[0:1] op_sel_hi:[1,0]
	v_pk_mul_f32 v[12:13], v[12:13], v[0:1] op_sel_hi:[1,0]
	v_pk_mul_f32 v[18:19], v[18:19], v[0:1] op_sel_hi:[1,0]
	v_pk_mul_f32 v[16:17], v[16:17], v[0:1] op_sel_hi:[1,0]
	v_pk_mul_f32 v[22:23], v[22:23], v[0:1] op_sel_hi:[1,0]
	v_pk_mul_f32 v[20:21], v[20:21], v[0:1] op_sel_hi:[1,0]
	v_pk_mul_f32 v[26:27], v[26:27], v[0:1] op_sel_hi:[1,0]
	v_pk_mul_f32 v[24:25], v[24:25], v[0:1] op_sel_hi:[1,0]
	v_pk_mul_f32 v[34:35], v[34:35], v[0:1] op_sel_hi:[1,0]
	v_pk_mul_f32 v[32:33], v[32:33], v[0:1] op_sel_hi:[1,0]
	v_pk_mul_f32 v[30:31], v[30:31], v[0:1] op_sel_hi:[1,0]
	v_pk_mul_f32 v[28:29], v[28:29], v[0:1] op_sel_hi:[1,0]
	v_pk_mul_f32 v[6:7], v[6:7], v[0:1] op_sel_hi:[1,0]
	v_pk_mul_f32 v[4:5], v[4:5], v[0:1] op_sel_hi:[1,0]
	v_mov_b32_e32 v0, v2

; template <bool SLC, bool NOMASK> ...
;     const int kq = lane >> 4;
;     const int pos0 = SLC ? (dcur & 0xfffff) : dcur;
;     const int lo = SLC ? ((((dcur >> 20) == qi) | ((dcur >> 20) == 4)) ? 0 : (1 << 30)) : lo_in;
;     load_frag8(nxt, KF, VF, SLC ? (dnext & 0xfffff) : dnext, lane);
;     f32x4 sa[2] = {(f32x4){0.f, 0.f, 0.f, 0.f}, (f32x4){0.f, 0.f, 0.f, 0.f}};
; #pragma unroll
;     for (int T = 0; T < 2; ++T)
; #pragma unroll
;         for (int s2 = 0; s2 < 4; ++s2) sa[T] = __builtin_amdgcn_mfma_f32_16x16x32_fp8_fp8(cur.k[T][s2], qf[s2], sa[T], 0, 0, 0);
;     float sc[8]; bool vd[8]; float mx = -1e30f;
;     const bool act = lo == 0 || !SLC;
;     if (NOMASK) {
; #pragma unroll
;         for (int j = 0; j < 8; ++j) { sc[j] = sa[j >> 2][j & 3]; vd[j] = act; }
;         mx = fmaxf(fmaxf(fmaxf(sc[0], sc[1]), fmaxf(sc[2], sc[3])), fmaxf(fmaxf(sc[4], sc[5]), fmaxf(sc[6], sc[7])));
;         mx = act ? mx : -1e30f;
;     } else {
; #pragma unroll
;         for (int T = 0; T < 2; ++T)
; #pragma unroll
;             for (int r = 0; r < 4; ++r) { const int p = pos0 + 16 * T + 4 * kq + r; const bool v = (p >= lo) & (p <= hi); const float x = sa[T][r];
;                 sc[4 * T + r] = x; vd[4 * T + r] = v; mx = v ? fmaxf(mx, x) : mx; }
;     }
;     if (__builtin_amdgcn_ballot_w64(mx > st.m + 4.f) != 0ull) {
;         mx = fmaxf(mx, __shfl_xor(mx, 16)); mx = fmaxf(mx, __shfl_xor(mx, 32));
;         const float mn = fmaxf(st.m, mx), alpha = __builtin_amdgcn_exp2f(st.m - mn); st.m = mn; st.l *= alpha;
; #pragma unroll
;         for (int j = 0; j < 8; ++j) st.o[j] = st.o[j] * alpha;
;     }
;     f32x4 pa, pb; float ps = 0.f;
;     const float mref = st.m - 4.f;
;     if (NOMASK) {
; #pragma unroll
;         for (int j = 0; j < 4; ++j) { pa[j] = __builtin_amdgcn_exp2f(sc[j] - mref); pb[j] = __builtin_amdgcn_exp2f(sc[4 + j] - mref); }
;         if (SLC) {
; #pragma unroll
;             for (int j = 0; j < 4; ++j) { pa[j] = act ? pa[j] : 0.f; pb[j] = act ? pb[j] : 0.f; }
;         }
; #pragma unroll
;         for (int j = 0; j < 4; ++j) ps += pa[j] + pb[j];
;     } else {
; #pragma unroll
;         for (int j = 0; j < 4; ++j) { pa[j] = vd[j] ? __builtin_amdgcn_exp2f(sc[j] - mref) : 0.f; pb[j] = vd[4 + j] ? __builtin_amdgcn_exp2f(sc[4 + j] - mref) : 0.f; ps += pa[j] + pb[j]; }
;     }
;     st.l += ps;
;     const u32x2 pw = pack8_fp8(pa, pb);
.LBB0_880:
	s_cmp_lt_u32 s58, s56
	s_cselect_b32 s10, s58, s57
	s_lshl_b32 s10, s10, 2
	s_add_i32 s10, s3, s10
	v_mov_b32_e32 v0, s10
	ds_read_b32 v0, v0 offset:13632
	s_and_b32 s13, s66, 2.0
	s_ashr_i32 s12, s66, 20
	s_mov_b64 s[10:11], -1
	s_cmp_eq_u32 s13, 0
	s_waitcnt lgkmcnt(0)
	v_readfirstlane_b32 s97, v0
	v_add_f32_e32 v0, 4.0, v203
	s_cbranch_scc1 .LBB0_884
	s_and_b32 s13, s12, 0xfffffbff
	s_cmp_eq_u32 s13, 4
	s_cselect_b64 s[10:11], -1, 0
	s_lshl_b32 s14, s97, 7
	s_and_b32 s50, s14, 0x7fff800
	v_lshl_add_u64 v[10:11], v[86:87], 0, s[50:51]
	s_and_b32 s50, s14, 0x7fff000
	v_lshl_add_u64 v[244:245], v[10:11], 0, v[118:119]
	global_load_dwordx4 v[154:157], v[244:245], off
	global_load_dwordx4 v[158:161], v[244:245], off offset:1024
	global_load_dwordx4 v[162:165], v[244:245], off offset:2048
	global_load_dwordx4 v[166:169], v[244:245], off offset:3072
	v_lshl_add_u64 v[10:11], v[88:89], 0, s[50:51]
	v_lshl_add_u64 v[246:247], v[10:11], 0, v[118:119]
	global_load_dwordx4 v[106:109], v[246:247], off
	global_load_dwordx4 v[110:113], v[246:247], off offset:1024
	global_load_dwordx4 v[114:117], v[246:247], off offset:2048
	global_load_dwordx4 v[134:137], v[246:247], off offset:3072
	s_waitcnt vmcnt(20)
	v_mfma_f32_16x16x32_fp8_fp8 v[2:5], v[186:187], v[78:79], 0
	v_cmp_eq_u32_e32 vcc, s13, v209
	s_or_b64 s[10:11], s[10:11], vcc
	v_mov_b64_e32 v[74:75], v[66:67]
	v_mfma_f32_16x16x32_fp8_fp8 v[6:9], v[194:195], v[78:79], 0
	v_mov_b64_e32 v[70:71], v[62:63]
	v_mov_b64_e32 v[30:31], v[56:57]
	v_mov_b64_e32 v[26:27], v[52:53]
	v_mfma_f32_16x16x32_fp8_fp8 v[2:5], v[188:189], v[80:81], v[2:5]
	v_mov_b64_e32 v[22:23], v[48:49]
	v_mov_b64_e32 v[18:19], v[44:45]
	v_mov_b64_e32 v[14:15], v[40:41]
	v_mfma_f32_16x16x32_fp8_fp8 v[6:9], v[196:197], v[80:81], v[6:9]
	v_mov_b32_e32 v202, v203
	v_mov_b64_e32 v[72:73], v[64:65]
	v_mov_b64_e32 v[68:69], v[60:61]
	v_mfma_f32_16x16x32_fp8_fp8 v[2:5], v[190:191], v[82:83], v[2:5]
	v_mov_b64_e32 v[32:33], v[58:59]
	v_mov_b64_e32 v[28:29], v[54:55]
	v_mov_b64_e32 v[24:25], v[50:51]
	v_mfma_f32_16x16x32_fp8_fp8 v[6:9], v[198:199], v[82:83], v[6:9]
	v_mov_b64_e32 v[20:21], v[46:47]
	v_mov_b64_e32 v[16:17], v[42:43]
	v_mov_b32_e32 v133, v204
	v_mfma_f32_16x16x32_fp8_fp8 v[2:5], v[192:193], v[84:85], v[2:5]
	v_mfma_f32_16x16x32_fp8_fp8 v[6:9], v[200:201], v[84:85], v[6:9]
	s_nop 5
	v_max_f32_e32 v10, v3, v3
	v_max_f32_e32 v11, v2, v2
	v_max_f32_e32 v10, v11, v10
	v_max_f32_e32 v11, v5, v5
	v_max_f32_e32 v12, v4, v4
	v_max_f32_e32 v11, v12, v11
	v_max_f32_e32 v12, v9, v9
	v_max_f32_e32 v13, v8, v8
	v_max_f32_e32 v12, v13, v12
	v_max3_f32 v12, v6, v7, v12
	v_max3_f32 v10, v10, v11, v12
	v_cndmask_b32_e64 v34, v223, v10, s[10:11]
	v_mov_b64_e32 v[10:11], v[36:37]
	v_cmp_gt_f32_e32 vcc, v34, v0
	v_mov_b64_e32 v[12:13], v[38:39]
	s_cbranch_vccz .LBB0_883
	ds_bpermute_b32 v10, v227, v34
	v_max_f32_e32 v11, v34, v34
	s_waitcnt lgkmcnt(0)
	v_max_f32_e32 v10, v10, v10
	v_max_f32_e32 v10, v11, v10
	ds_bpermute_b32 v11, v226, v10
	s_waitcnt lgkmcnt(0)
	v_max3_f32 v202, v203, v10, v11
	v_sub_f32_e32 v10, v203, v202
	v_exp_f32_e32 v34, v10
	s_nop 0
	v_mul_f32_e32 v133, v204, v34
	v_pk_mul_f32 v[12:13], v[38:39], v[34:35] op_sel_hi:[1,0]
	v_pk_mul_f32 v[10:11], v[36:37], v[34:35] op_sel_hi:[1,0]
	v_pk_mul_f32 v[16:17], v[42:43], v[34:35] op_sel_hi:[1,0]
	v_pk_mul_f32 v[14:15], v[40:41], v[34:35] op_sel_hi:[1,0]
	v_pk_mul_f32 v[20:21], v[46:47], v[34:35] op_sel_hi:[1,0]
	v_pk_mul_f32 v[18:19], v[44:45], v[34:35] op_sel_hi:[1,0]
	v_pk_mul_f32 v[24:25], v[50:51], v[34:35] op_sel_hi:[1,0]
	v_pk_mul_f32 v[22:23], v[48:49], v[34:35] op_sel_hi:[1,0]
	v_pk_mul_f32 v[28:29], v[54:55], v[34:35] op_sel_hi:[1,0]
	v_pk_mul_f32 v[26:27], v[52:53], v[34:35] op_sel_hi:[1,0]
	v_pk_mul_f32 v[32:33], v[58:59], v[34:35] op_sel_hi:[1,0]
	v_pk_mul_f32 v[30:31], v[56:57], v[34:35] op_sel_hi:[1,0]
	v_pk_mul_f32 v[70:71], v[62:63], v[34:35] op_sel_hi:[1,0]
	v_pk_mul_f32 v[68:69], v[60:61], v[34:35] op_sel_hi:[1,0]
	v_pk_mul_f32 v[74:75], v[66:67], v[34:35] op_sel_hi:[1,0]
	v_pk_mul_f32 v[72:73], v[64:65], v[34:35] op_sel_hi:[1,0]
.LBB0_883:
	v_add_f32_e32 v34, -4.0, v202
	v_sub_f32_e32 v2, v2, v34
	v_sub_f32_e32 v6, v6, v34
	v_sub_f32_e32 v3, v3, v34
	v_sub_f32_e32 v7, v7, v34
	v_exp_f32_e32 v2, v2
	v_exp_f32_e32 v6, v6
	v_exp_f32_e32 v3, v3
	v_exp_f32_e32 v7, v7
	v_sub_f32_e32 v4, v4, v34
	v_sub_f32_e32 v8, v8, v34
	v_sub_f32_e32 v5, v5, v34
	v_sub_f32_e32 v9, v9, v34
	v_exp_f32_e32 v4, v4
	v_exp_f32_e32 v8, v8
	v_exp_f32_e32 v5, v5
	v_exp_f32_e32 v9, v9
	v_cndmask_b32_e64 v34, 0, v2, s[10:11]
	v_cndmask_b32_e64 v6, 0, v6, s[10:11]
	v_cndmask_b32_e64 v35, 0, v3, s[10:11]
	v_cndmask_b32_e64 v7, 0, v7, s[10:11]
	v_mov_b32_e32 v2, v1
	v_mov_b32_e32 v3, v1
	v_cvt_pk_fp8_f32 v2, v34, v35
	v_cvt_pk_fp8_f32 v3, v6, v7
	v_cndmask_b32_e64 v4, 0, v4, s[10:11]
	v_cndmask_b32_e64 v205, 0, v8, s[10:11]
	v_cndmask_b32_e64 v5, 0, v5, s[10:11]
	v_cndmask_b32_e64 v229, 0, v9, s[10:11]
	v_add_f32_e32 v6, v34, v6
	v_cvt_pk_fp8_f32 v2, v4, v5 op_sel:[0,0,1]
	v_cvt_pk_fp8_f32 v3, v205, v229 op_sel:[0,0,1]
	v_add_f32_e32 v6, 0, v6
	v_add_f32_e32 v7, v35, v7
	v_add_f32_e32 v6, v7, v6
	v_add_f32_e32 v4, v4, v205
	v_add_f32_e32 v4, v4, v6
	v_add_f32_e32 v5, v5, v229
	v_add_f32_e32 v4, v5, v4
	s_waitcnt vmcnt(19)
	v_mfma_f32_16x16x32_fp8_fp8 v[8:11], v[170:171], v[2:3], v[10:13]
	v_add_f32_e32 v133, v133, v4
	s_mov_b64 s[10:11], 0
	v_mfma_f32_16x16x32_fp8_fp8 v[12:15], v[172:173], v[2:3], v[14:17]
	s_waitcnt vmcnt(18)
	v_mfma_f32_16x16x32_fp8_fp8 v[16:19], v[174:175], v[2:3], v[18:21]
	v_mfma_f32_16x16x32_fp8_fp8 v[20:23], v[176:177], v[2:3], v[22:25]
	s_waitcnt vmcnt(17)
	v_mfma_f32_16x16x32_fp8_fp8 v[24:27], v[178:179], v[2:3], v[26:29]
	v_mfma_f32_16x16x32_fp8_fp8 v[32:35], v[180:181], v[2:3], v[30:33]
	s_waitcnt vmcnt(16)
	v_mfma_f32_16x16x32_fp8_fp8 v[28:31], v[182:183], v[2:3], v[68:71]
	v_mfma_f32_16x16x32_fp8_fp8 v[4:7], v[184:185], v[2:3], v[72:75]
; template <bool SLC, bool NOMASK> ...
;     const int kq = lane >> 4;
;     const int pos0 = SLC ? (dcur & 0xfffff) : dcur;
;     const int lo = SLC ? ((((dcur >> 20) == qi) | ((dcur >> 20) == 4)) ? 0 : (1 << 30)) : lo_in;
;     load_frag8(nxt, KF, VF, SLC ? (dnext & 0xfffff) : dnext, lane);
;     f32x4 sa[2] = {(f32x4){0.f, 0.f, 0.f, 0.f}, (f32x4){0.f, 0.f, 0.f, 0.f}};
; #pragma unroll
;     for (int T = 0; T < 2; ++T)
; #pragma unroll
;         for (int s2 = 0; s2 < 4; ++s2) sa[T] = __builtin_amdgcn_mfma_f32_16x16x32_fp8_fp8(cur.k[T][s2], qf[s2], sa[T], 0, 0, 0);
;     float sc[8]; bool vd[8]; float mx = -1e30f;
;     const bool act = lo == 0 || !SLC;
;     if (NOMASK) {
; #pragma unroll
;         for (int j = 0; j < 8; ++j) { sc[j] = sa[j >> 2][j & 3]; vd[j] = act; }
;         mx = fmaxf(fmaxf(fmaxf(sc[0], sc[1]), fmaxf(sc[2], sc[3])), fmaxf(fmaxf(sc[4], sc[5]), fmaxf(sc[6], sc[7])));
;         mx = act ? mx : -1e30f;
;     } else {
; #pragma unroll
;         for (int T = 0; T < 2; ++T)
; #pragma unroll
;             for (int r = 0; r < 4; ++r) { const int p = pos0 + 16 * T + 4 * kq + r; const bool v = (p >= lo) & (p <= hi); const float x = sa[T][r];
;                 sc[4 * T + r] = x; vd[4 * T + r] = v; mx = v ? fmaxf(mx, x) : mx; }
;     }
;     if (__builtin_amdgcn_ballot_w64(mx > st.m + 4.f) != 0ull) {
;         mx = fmaxf(mx, __shfl_xor(mx, 16)); mx = fmaxf(mx, __shfl_xor(mx, 32));
;         const float mn = fmaxf(st.m, mx), alpha = __builtin_amdgcn_exp2f(st.m - mn); st.m = mn; st.l *= alpha;
; #pragma unroll
;         for (int j = 0; j < 8; ++j) st.o[j] = st.o[j] * alpha;
;     }
;     f32x4 pa, pb; float ps = 0.f;
;     const float mref = st.m - 4.f;
;     if (NOMASK) {
; #pragma unroll
;         for (int j = 0; j < 4; ++j) { pa[j] = __builtin_amdgcn_exp2f(sc[j] - mref); pb[j] = __builtin_amdgcn_exp2f(sc[4 + j] - mref); }
;         if (SLC) {
; #pragma unroll
;             for (int j = 0; j < 4; ++j) { pa[j] = act ? pa[j] : 0.f; pb[j] = act ? pb[j] : 0.f; }
;         }
; #pragma unroll
;         for (int j = 0; j < 4; ++j) ps += pa[j] + pb[j];
;     } else {
; #pragma unroll
;         for (int j = 0; j < 4; ++j) { pa[j] = vd[j] ? __builtin_amdgcn_exp2f(sc[j] - mref) : 0.f; pb[j] = vd[4 + j] ? __builtin_amdgcn_exp2f(sc[4 + j] - mref) : 0.f; ps += pa[j] + pb[j]; }
;     }
;     st.l += ps;
;     const u32x2 pw = pack8_fp8(pa, pb);
.LBB0_884:
	s_and_b64 vcc, exec, s[10:11]
	s_cbranch_vccz .LBB0_888
	s_cmp_eq_u32 s12, 4
	s_cselect_b64 s[10:11], -1, 0
	s_lshl_b32 s13, s97, 7
	s_and_b32 s50, s13, 0x7fff800
	v_lshl_add_u64 v[10:11], v[86:87], 0, s[50:51]
	s_and_b32 s50, s13, 0x7fff000
	v_lshl_add_u64 v[244:245], v[10:11], 0, v[118:119]
	global_load_dwordx4 v[154:157], v[244:245], off
	global_load_dwordx4 v[158:161], v[244:245], off offset:1024
	global_load_dwordx4 v[162:165], v[244:245], off offset:2048
	global_load_dwordx4 v[166:169], v[244:245], off offset:3072
	v_lshl_add_u64 v[10:11], v[88:89], 0, s[50:51]
	v_lshl_add_u64 v[246:247], v[10:11], 0, v[118:119]
	global_load_dwordx4 v[106:109], v[246:247], off
	global_load_dwordx4 v[110:113], v[246:247], off offset:1024
	global_load_dwordx4 v[114:117], v[246:247], off offset:2048
	global_load_dwordx4 v[134:137], v[246:247], off offset:3072
	s_waitcnt vmcnt(20)
	v_mfma_f32_16x16x32_fp8_fp8 v[2:5], v[186:187], v[78:79], 0
	s_and_b32 s13, s66, 0xfffff
	v_cmp_eq_u32_e32 vcc, s12, v209
	v_add_u32_e32 v10, s13, v211
	v_mfma_f32_16x16x32_fp8_fp8 v[2:5], v[188:189], v[80:81], v[2:5]
	s_or_b64 s[18:19], s[10:11], vcc
	v_cmp_le_i32_e32 vcc, v10, v132
	s_and_b64 s[16:17], s[18:19], vcc
	v_mfma_f32_16x16x32_fp8_fp8 v[2:5], v[190:191], v[82:83], v[2:5]
	v_cmp_lt_i32_e32 vcc, v10, v132
	s_and_b64 s[12:13], s[18:19], vcc
	v_mfma_f32_16x16x32_fp8_fp8 v[6:9], v[194:195], v[78:79], 0
	v_mfma_f32_16x16x32_fp8_fp8 v[2:5], v[192:193], v[84:85], v[2:5]
	v_mfma_f32_16x16x32_fp8_fp8 v[6:9], v[196:197], v[80:81], v[6:9]
	v_mfma_f32_16x16x32_fp8_fp8 v[6:9], v[198:199], v[82:83], v[6:9]
	s_nop 3
	v_max_f32_e32 v11, v2, v2
	v_max_f32_e32 v11, 0xf149f2ca, v11
	v_cndmask_b32_e64 v11, v223, v11, s[16:17]
	v_max_f32_e32 v12, v3, v3
	v_max_f32_e32 v12, v11, v12
	v_cndmask_b32_e64 v11, v11, v12, s[12:13]
	v_add_u32_e32 v12, 2, v10
	v_cmp_le_i32_e32 vcc, v12, v132
	v_max_f32_e32 v12, v4, v4
	v_max_f32_e32 v12, v11, v12
	s_and_b64 s[14:15], s[18:19], vcc
	v_mfma_f32_16x16x32_fp8_fp8 v[6:9], v[200:201], v[84:85], v[6:9]
	v_cndmask_b32_e64 v11, v11, v12, s[14:15]
	v_add_u32_e32 v12, 3, v10
	v_cmp_le_i32_e32 vcc, v12, v132
	v_max_f32_e32 v12, v5, v5
	v_max_f32_e32 v12, v11, v12
	s_and_b64 s[10:11], s[18:19], vcc
	v_cndmask_b32_e64 v11, v11, v12, s[10:11]
	v_add_u32_e32 v12, 16, v10
	v_cmp_le_i32_e32 vcc, v12, v132
	v_max_f32_e32 v12, v6, v6
	v_max_f32_e32 v12, v11, v12
	s_and_b64 s[24:25], s[18:19], vcc
	v_cndmask_b32_e64 v11, v11, v12, s[24:25]
	v_add_u32_e32 v12, 17, v10
	v_cmp_le_i32_e32 vcc, v12, v132
	v_max_f32_e32 v12, v11, v11
	v_max_f32_e32 v13, v7, v7
	v_max_f32_e32 v12, v12, v13
	s_and_b64 s[20:21], s[18:19], vcc
	v_cndmask_b32_e64 v11, v11, v12, s[20:21]
	v_add_u32_e32 v12, 18, v10
	v_cmp_le_i32_e32 vcc, v12, v132
	v_max_f32_e32 v12, v11, v11
	v_max_f32_e32 v13, v8, v8
	v_max_f32_e32 v12, v12, v13
	s_and_b64 s[22:23], s[18:19], vcc
	v_cndmask_b32_e64 v11, v11, v12, s[22:23]
	v_add_u32_e32 v10, 19, v10
	v_cmp_le_i32_e32 vcc, v10, v132
	v_max_f32_e32 v10, v11, v11
	v_max_f32_e32 v12, v9, v9
	v_max_f32_e32 v10, v10, v12
	s_and_b64 s[18:19], s[18:19], vcc
	v_cndmask_b32_e64 v10, v11, v10, s[18:19]
	v_cmp_gt_f32_e32 vcc, v10, v0
	s_cbranch_vccz .LBB0_887
	ds_bpermute_b32 v0, v227, v10
	v_max_f32_e32 v10, v10, v10
	s_waitcnt lgkmcnt(0)
	v_max_f32_e32 v0, v0, v0
	v_max_f32_e32 v0, v10, v0
	ds_bpermute_b32 v10, v226, v0
	s_waitcnt lgkmcnt(0)
	v_max3_f32 v10, v203, v0, v10
	v_sub_f32_e32 v0, v203, v10
	v_exp_f32_e32 v0, v0
	v_mov_b32_e32 v203, v10
	v_mul_f32_e32 v204, v204, v0
	v_pk_mul_f32 v[38:39], v[38:39], v[0:1] op_sel_hi:[1,0]
	v_pk_mul_f32 v[36:37], v[36:37], v[0:1] op_sel_hi:[1,0]
	v_pk_mul_f32 v[42:43], v[42:43], v[0:1] op_sel_hi:[1,0]
	v_pk_mul_f32 v[40:41], v[40:41], v[0:1] op_sel_hi:[1,0]
	v_pk_mul_f32 v[46:47], v[46:47], v[0:1] op_sel_hi:[1,0]
	v_pk_mul_f32 v[44:45], v[44:45], v[0:1] op_sel_hi:[1,0]
	v_pk_mul_f32 v[50:51], v[50:51], v[0:1] op_sel_hi:[1,0]
	v_pk_mul_f32 v[48:49], v[48:49], v[0:1] op_sel_hi:[1,0]
	v_pk_mul_f32 v[54:55], v[54:55], v[0:1] op_sel_hi:[1,0]
	v_pk_mul_f32 v[52:53], v[52:53], v[0:1] op_sel_hi:[1,0]
	v_pk_mul_f32 v[58:59], v[58:59], v[0:1] op_sel_hi:[1,0]
	v_pk_mul_f32 v[56:57], v[56:57], v[0:1] op_sel_hi:[1,0]
	v_pk_mul_f32 v[62:63], v[62:63], v[0:1] op_sel_hi:[1,0]
	v_pk_mul_f32 v[60:61], v[60:61], v[0:1] op_sel_hi:[1,0]
	v_pk_mul_f32 v[66:67], v[66:67], v[0:1] op_sel_hi:[1,0]
	v_pk_mul_f32 v[64:65], v[64:65], v[0:1] op_sel_hi:[1,0]
.LBB0_887:
	v_add_f32_e32 v0, -4.0, v203
	v_sub_f32_e32 v2, v2, v0
	v_exp_f32_e32 v2, v2
	v_sub_f32_e32 v6, v6, v0
	v_exp_f32_e32 v6, v6
	v_sub_f32_e32 v4, v4, v0
	v_cndmask_b32_e64 v28, 0, v2, s[16:17]
	v_sub_f32_e32 v2, v3, v0
	v_exp_f32_e32 v2, v2
	v_sub_f32_e32 v3, v7, v0
	v_exp_f32_e32 v3, v3
	v_sub_f32_e32 v7, v8, v0
	v_cndmask_b32_e64 v29, 0, v2, s[12:13]
	v_sub_f32_e32 v2, v5, v0
	v_sub_f32_e32 v0, v9, v0
	v_cndmask_b32_e64 v6, 0, v6, s[24:25]
	v_exp_f32_e32 v4, v4
	v_exp_f32_e32 v7, v7
	v_cndmask_b32_e64 v30, 0, v3, s[20:21]
	v_exp_f32_e32 v5, v2
	v_exp_f32_e32 v0, v0
	v_mov_b32_e32 v2, v1
	v_mov_b32_e32 v3, v1
	v_cvt_pk_fp8_f32 v2, v28, v29
	v_cvt_pk_fp8_f32 v3, v6, v30
	v_cndmask_b32_e64 v4, 0, v4, s[14:15]
	v_cndmask_b32_e64 v7, 0, v7, s[22:23]
	v_cndmask_b32_e64 v5, 0, v5, s[10:11]
	v_cndmask_b32_e64 v0, 0, v0, s[18:19]
	v_cvt_pk_fp8_f32 v2, v4, v5 op_sel:[0,0,1]
	v_cvt_pk_fp8_f32 v3, v7, v0 op_sel:[0,0,1]
	v_add_f32_e32 v6, v28, v6
	v_add_f32_e32 v6, 0, v6
	v_add_f32_e32 v28, v29, v30
	v_add_f32_e32 v6, v28, v6
	v_add_f32_e32 v4, v4, v7
	v_add_f32_e32 v4, v4, v6
	v_add_f32_e32 v0, v5, v0
	s_waitcnt vmcnt(19)
	v_mfma_f32_16x16x32_fp8_fp8 v[8:11], v[170:171], v[2:3], v[36:39]
	v_add_f32_e32 v0, v0, v4
	v_add_f32_e32 v133, v204, v0
	v_mov_b32_e32 v202, v203
	v_mfma_f32_16x16x32_fp8_fp8 v[12:15], v[172:173], v[2:3], v[40:43]
	s_waitcnt vmcnt(18)
	v_mfma_f32_16x16x32_fp8_fp8 v[16:19], v[174:175], v[2:3], v[44:47]
	v_mfma_f32_16x16x32_fp8_fp8 v[20:23], v[176:177], v[2:3], v[48:51]
	s_waitcnt vmcnt(17)
	v_mfma_f32_16x16x32_fp8_fp8 v[24:27], v[178:179], v[2:3], v[52:55]
	v_mfma_f32_16x16x32_fp8_fp8 v[32:35], v[180:181], v[2:3], v[56:59]
	s_waitcnt vmcnt(16)
	v_mfma_f32_16x16x32_fp8_fp8 v[28:31], v[182:183], v[2:3], v[60:63]
	v_mfma_f32_16x16x32_fp8_fp8 v[4:7], v[184:185], v[2:3], v[64:67]
.LBB0_888:
	s_add_i32 s58, s58, 3
	s_cmp_ge_u32 s42, s56
	s_cselect_b64 s[10:11], -1, 0
	s_branch .LBB0_860

; __device__ __forceinline__ unsigned cvt_pk_bf16(float lo, float hi) { f32x2 v = {lo, hi}; bf16x2_t b = __builtin_convertvector(v, bf16x2_t); return __builtin_bit_cast(unsigned, b); }
; __device__ __forceinline__ float bf2f(unsigned short b) { return __uint_as_float(((unsigned)b) << 16); }
; __device__ __forceinline__ float bflo(unsigned w) { return __uint_as_float(w << 16); }
; __device__ __forceinline__ float bfhi(unsigned w) { return __uint_as_float(w & 0xffff0000u); }
; __device__ __forceinline__ float quad_total(float v) { v += __shfl_xor(v, 16); v += __shfl_xor(v, 32); return v; }
; __device__ __forceinline__ void nsa_unit(int unit, const bf16_t* proj, const bf16_t* kc, const bf16_t* vc, const bf16_t* gn, const float* cs, const float* sn, ...
;     ...
;     { const float g1 = bf2f(gn[(size_t)tc * 32 + head * 3 + 1]); const float lt = quad_total(st.l), inv = (lt > 0.f ? 1.f / lt : 0.f) * g1;
; #pragma unroll
;         for (int i = 0; i < 8; ++i) { const f32x4 o = st.o[i] * inv; u32x2 w = outl[64 * i]; w.x = cvt_pk_bf16(bflo(w.x) + o[0], bfhi(w.x) + o[1]); w.y = cvt_pk_bf16(bflo(w.y) + o[2], bfhi(w.y) + o[3]); outl[64 * i] = w; } }
;     ...
;     { const int lo = tc - 511 < 0 ? 0 : tc - 511; const int first = t0 < 511 ? 0 : (t0 - 511) >> 5, last = (t0 + 3) >> 5;
.LBB0_890:
	s_waitcnt vmcnt(8)
	global_load_ushort v0, v[76:77], off offset:2
	ds_bpermute_b32 v2, v227, v133
	ds_read2st64_b64 v[36:39], v228 offset0:27 offset1:28
	ds_read2st64_b64 v[40:43], v228 offset0:29 offset1:30
	ds_read2st64_b64 v[44:47], v228 offset0:31 offset1:32
	ds_read2st64_b64 v[48:51], v228 offset0:33 offset1:34
	s_mov_b32 s58, 0
	s_waitcnt lgkmcnt(3)
	v_and_b32_e32 v3, 0xffff0000, v36
	v_lshlrev_b32_e32 v52, 16, v38
	v_add_f32_e32 v64, v133, v2
	ds_bpermute_b32 v65, v226, v64
	v_lshlrev_b32_e32 v2, 16, v36
	v_lshlrev_b32_e32 v36, 16, v37
	v_and_b32_e32 v37, 0xffff0000, v37
	v_and_b32_e32 v53, 0xffff0000, v38
	s_waitcnt lgkmcnt(0)
	v_add_f32_e32 v64, v64, v65
	v_div_scale_f32 v65, s[10:11], v64, v64, 1.0
	v_rcp_f32_e32 v66, v65
	v_div_scale_f32 v67, vcc, 1.0, v64, 1.0
	v_lshlrev_b32_e32 v38, 16, v39
	v_fma_f32 v68, -v65, v66, 1.0
	v_fmac_f32_e32 v66, v68, v66
	v_mul_f32_e32 v68, v67, v66
	v_fma_f32 v69, -v65, v68, v67
	v_fmac_f32_e32 v68, v69, v66
	v_fma_f32 v65, -v65, v68, v67
	v_div_fmas_f32 v65, v65, v66, v68
	v_div_fixup_f32 v65, v65, v64, 1.0
	v_cmp_lt_f32_e32 vcc, 0, v64
	v_and_b32_e32 v39, 0xffff0000, v39
	v_lshlrev_b32_e32 v54, 16, v40
	v_cndmask_b32_e32 v64, 0, v65, vcc
	v_and_b32_e32 v55, 0xffff0000, v40
	v_lshlrev_b32_e32 v40, 16, v41
	v_and_b32_e32 v41, 0xffff0000, v41
	v_lshlrev_b32_e32 v56, 16, v42
	v_and_b32_e32 v57, 0xffff0000, v42
	v_lshlrev_b32_e32 v42, 16, v43
	v_and_b32_e32 v43, 0xffff0000, v43
	v_lshlrev_b32_e32 v58, 16, v44
	v_and_b32_e32 v59, 0xffff0000, v44
	v_lshlrev_b32_e32 v44, 16, v45
	v_and_b32_e32 v45, 0xffff0000, v45
	v_lshlrev_b32_e32 v60, 16, v46
	v_and_b32_e32 v61, 0xffff0000, v46
	v_lshlrev_b32_e32 v46, 16, v47
	v_and_b32_e32 v47, 0xffff0000, v47
	v_lshlrev_b32_e32 v62, 16, v48
	v_and_b32_e32 v63, 0xffff0000, v48
	v_lshlrev_b32_e32 v48, 16, v49
	v_and_b32_e32 v49, 0xffff0000, v49
	s_add_i32 s10, s96, 0xfffffe01
	s_lshr_b32 s10, s10, 5
	s_cmpk_gt_i32 s96, 0x1fe
	s_cselect_b32 s26, s10, 0
	s_ashr_i32 s15, s72, 4
	s_sub_i32 s27, s15, s26
	s_mov_b64 s[12:13], s[52:53]
	s_cmp_lt_i32 s27, 0
	s_waitcnt vmcnt(0)
	v_lshlrev_b32_e32 v0, 16, v0
	v_mul_f32_e32 v0, v64, v0
	v_pk_fma_f32 v[2:3], v[8:9], v[0:1], v[2:3] op_sel_hi:[1,0,1]
	v_pk_fma_f32 v[8:9], v[10:11], v[0:1], v[36:37] op_sel_hi:[1,0,1]
	v_pk_fma_f32 v[10:11], v[12:13], v[0:1], v[52:53] op_sel_hi:[1,0,1]
	v_pk_fma_f32 v[12:13], v[14:15], v[0:1], v[38:39] op_sel_hi:[1,0,1]
	v_pk_fma_f32 v[14:15], v[16:17], v[0:1], v[54:55] op_sel_hi:[1,0,1]
	v_pk_fma_f32 v[16:17], v[18:19], v[0:1], v[40:41] op_sel_hi:[1,0,1]
	v_pk_fma_f32 v[18:19], v[20:21], v[0:1], v[56:57] op_sel_hi:[1,0,1]
	v_pk_fma_f32 v[20:21], v[22:23], v[0:1], v[42:43] op_sel_hi:[1,0,1]
	v_pk_fma_f32 v[22:23], v[24:25], v[0:1], v[58:59] op_sel_hi:[1,0,1]
	v_pk_fma_f32 v[24:25], v[26:27], v[0:1], v[44:45] op_sel_hi:[1,0,1]
	v_pk_fma_f32 v[26:27], v[32:33], v[0:1], v[60:61] op_sel_hi:[1,0,1]
	v_pk_fma_f32 v[32:33], v[34:35], v[0:1], v[46:47] op_sel_hi:[1,0,1]
	v_cvt_pk_bf16_f32 v2, v2, v3
	v_cvt_pk_bf16_f32 v3, v8, v9
	v_cvt_pk_bf16_f32 v8, v10, v11
	v_cvt_pk_bf16_f32 v9, v12, v13
	v_cvt_pk_bf16_f32 v10, v14, v15
	v_cvt_pk_bf16_f32 v11, v16, v17
	v_cvt_pk_bf16_f32 v12, v18, v19
	v_cvt_pk_bf16_f32 v13, v20, v21
	v_cvt_pk_bf16_f32 v14, v22, v23
	v_cvt_pk_bf16_f32 v15, v24, v25
	v_cvt_pk_bf16_f32 v16, v26, v27
	v_cvt_pk_bf16_f32 v17, v32, v33
	ds_write2st64_b64 v228, v[2:3], v[8:9] offset0:27 offset1:28
	ds_write2st64_b64 v228, v[10:11], v[12:13] offset0:29 offset1:30
	ds_write2st64_b64 v228, v[14:15], v[16:17] offset0:31 offset1:32
	v_pk_fma_f32 v[2:3], v[30:31], v[0:1], v[48:49] op_sel_hi:[1,0,1]
	v_pk_fma_f32 v[28:29], v[28:29], v[0:1], v[62:63] op_sel_hi:[1,0,1]
	v_cvt_pk_bf16_f32 v19, v2, v3
	v_lshlrev_b32_e32 v2, 16, v50
	v_and_b32_e32 v3, 0xffff0000, v50
	v_pk_fma_f32 v[2:3], v[4:5], v[0:1], v[2:3] op_sel_hi:[1,0,1]
	v_lshlrev_b32_e32 v4, 16, v51
	v_and_b32_e32 v5, 0xffff0000, v51
	v_pk_fma_f32 v[4:5], v[6:7], v[0:1], v[4:5] op_sel_hi:[1,0,1]
	v_cvt_pk_bf16_f32 v18, v28, v29
	v_cvt_pk_bf16_f32 v2, v2, v3
	v_cvt_pk_bf16_f32 v3, v4, v5
	ds_write2st64_b64 v228, v[18:19], v[2:3] offset0:33 offset1:34
	s_cbranch_scc1 .LBB0_825
; template <bool SLC, class Desc>
; __device__ __forceinline__ void attn_run_frag8(const i64_t (&qf)[4], const unsigned char* __restrict__ KF, const unsigned char* __restrict__ VF, const Desc& desc, int n,
;                                                int lo_in, int hi, int qi, AState& st, int lane) {
;     if (n <= 0) return;
;     Frag8 fa, fb, fc;
;     constexpr int NM = ~(1 << 30);
;     int d0 = desc(0), d1 = desc(n > 1 ? 1 : 0);
;     load_frag8(fa, KF, VF, SLC ? (d0 & 0xfffff) : (d0 & NM), lane);
;     load_frag8(fb, KF, VF, SLC ? (d1 & 0xfffff) : (d1 & NM), lane);
; __device__ __forceinline__ void nsa_unit(int unit, const bf16_t* proj, const bf16_t* kc, const bf16_t* vc, const bf16_t* gn, const float* cs, const float* sn, ...
;     ...
;     { const int lo = tc - 511 < 0 ? 0 : tc - 511; const int first = t0 < 511 ? 0 : (t0 - 511) >> 5, last = (t0 + 3) >> 5;
;       auto desc = [&](int i) { const int p0 = 32 * (first + i); return p0 | ((p0 >= t0 + 3 - 511 && p0 + 31 <= t0) ? (1 << 30) : 0); };
;       unsigned long long goff = (unsigned long long)g * S * 128; asm volatile("" : "+s"(goff));
;       attn_run_frag8<false>(q8, (const unsigned char*)kslf + ((size_t)16 << 20) + goff, (const unsigned char*)kslf + ((size_t)24 << 20) + goff, desc, last - first + 1, lo, tc, 0, st, lane); }
	s_add_u32 s10, s81, s12
	s_addc_u32 s11, s82, s13
	s_add_u32 s12, s83, s12
	s_addc_u32 s13, s84, s13
	s_lshl_b32 s20, s26, 5
	s_add_i32 s56, s96, 0xfffffe04
	s_cmp_lt_i32 s20, s56
	s_cselect_b64 s[16:17], -1, 0
	s_or_b32 s14, s20, 31
	s_cmp_gt_i32 s14, s96
	s_cselect_b64 s[18:19], -1, 0
	s_or_b64 s[16:17], s[16:17], s[18:19]
	s_and_b64 s[16:17], s[16:17], exec
	s_cselect_b32 s14, 0, 2.0
	s_or_b32 s14, s14, s20
	s_cmp_lg_u32 s15, s26
	s_cselect_b64 s[16:17], -1, 0
	v_cndmask_b32_e64 v0, 0, 1, s[16:17]
	v_lshl_add_u64 v[86:87], s[12:13], 0, v[118:119]
	v_readfirstlane_b32 s15, v0
	s_add_i32 s15, s26, s15
	s_lshl_b32 s21, s15, 5
	s_cmp_lt_i32 s21, s56
	s_cselect_b64 s[16:17], -1, 0
	s_or_b32 s18, s21, 31
	s_cmp_gt_i32 s18, s96
	s_cselect_b64 s[18:19], -1, 0
	s_or_b64 s[16:17], s[16:17], s[18:19]
	s_and_b64 s[16:17], s[16:17], exec
	s_cselect_b32 s16, 0, 2.0
	s_or_b32 s66, s16, s21
	s_and_b32 s16, s20, 0x3fffffe0
	s_lshr_b32 s50, s16, 4
	s_lshl_b64 s[16:17], s[50:51], 11
	s_add_u32 s16, s12, s16
	s_addc_u32 s17, s13, s17
	s_and_b32 s50, s26, 0x1ffffff
	v_lshl_add_u64 v[2:3], s[16:17], 0, v[118:119]
	s_lshl_b64 s[16:17], s[50:51], 12
	s_add_u32 s16, s10, s16
	s_addc_u32 s17, s11, s17
	v_lshl_add_u64 v[244:245], v[2:3], 0, v[118:119]
	global_load_dwordx4 v[138:141], v[244:245], off
	global_load_dwordx4 v[142:145], v[244:245], off offset:1024
	global_load_dwordx4 v[146:149], v[244:245], off offset:2048
	global_load_dwordx4 v[150:153], v[244:245], off offset:3072
	v_lshl_add_u64 v[2:3], s[16:17], 0, v[118:119]
	s_and_b32 s16, s21, 0x3fffffe0
	s_lshr_b32 s50, s16, 4
	s_lshl_b64 s[16:17], s[50:51], 11
	s_add_u32 s16, s12, s16
	s_addc_u32 s17, s13, s17
	s_and_b32 s50, s15, 0x1ffffff
	v_lshl_add_u64 v[246:247], v[2:3], 0, v[118:119]
	global_load_dwordx4 v[90:93], v[246:247], off
	global_load_dwordx4 v[94:97], v[246:247], off offset:1024
	global_load_dwordx4 v[98:101], v[246:247], off offset:2048
	global_load_dwordx4 v[102:105], v[246:247], off offset:3072
	v_lshl_add_u64 v[2:3], s[16:17], 0, v[118:119]
	s_lshl_b64 s[16:17], s[50:51], 12
	s_add_u32 s16, s10, s16
	s_addc_u32 s17, s11, s17
	v_lshl_add_u64 v[244:245], v[2:3], 0, v[118:119]
	global_load_dwordx4 v[154:157], v[244:245], off
	global_load_dwordx4 v[158:161], v[244:245], off offset:1024
	global_load_dwordx4 v[162:165], v[244:245], off offset:2048
	global_load_dwordx4 v[166:169], v[244:245], off offset:3072
	v_lshl_add_u64 v[2:3], s[16:17], 0, v[118:119]
	v_lshl_add_u64 v[246:247], v[2:3], 0, v[118:119]
	global_load_dwordx4 v[106:109], v[246:247], off
	global_load_dwordx4 v[110:113], v[246:247], off offset:1024
	global_load_dwordx4 v[114:117], v[246:247], off offset:2048
	global_load_dwordx4 v[134:137], v[246:247], off offset:3072
	v_max_i32_e32 v0, 0x1ff, v132
	v_mov_b32_e32 v2, v1
	v_mov_b32_e32 v3, v1
	v_add_u32_e32 v35, 0xfffffe01, v0
	v_mov_b32_e32 v0, v1
	v_mov_b64_e32 v[38:39], v[2:3]
	v_mov_b64_e32 v[42:43], v[2:3]
	v_mov_b64_e32 v[46:47], v[2:3]
	v_mov_b64_e32 v[50:51], v[2:3]
	v_mov_b64_e32 v[54:55], v[2:3]
	v_mov_b64_e32 v[58:59], v[2:3]
	v_mov_b64_e32 v[62:63], v[2:3]
	v_mov_b64_e32 v[66:67], v[2:3]
	v_lshl_add_u64 v[88:89], s[10:11], 0, v[118:119]
	v_mov_b32_e32 v133, 0xf149f2ca
	v_mov_b32_e32 v230, 0
	v_mov_b64_e32 v[36:37], v[0:1]
	v_mov_b64_e32 v[40:41], v[0:1]
	v_mov_b64_e32 v[44:45], v[0:1]
	v_mov_b64_e32 v[48:49], v[0:1]
	v_mov_b64_e32 v[52:53], v[0:1]
	v_mov_b64_e32 v[56:57], v[0:1]
	v_mov_b64_e32 v[60:61], v[0:1]
	v_mov_b64_e32 v[64:65], v[0:1]
	s_branch .LBB0_894

; template <bool SLC, bool NOMASK> ...
;     const int kq = lane >> 4;
;     const int pos0 = SLC ? (dcur & 0xfffff) : dcur;
;     const int lo = SLC ? ((((dcur >> 20) == qi) | ((dcur >> 20) == 4)) ? 0 : (1 << 30)) : lo_in;
;     load_frag8(nxt, KF, VF, SLC ? (dnext & 0xfffff) : dnext, lane);
;     f32x4 sa[2] = {(f32x4){0.f, 0.f, 0.f, 0.f}, (f32x4){0.f, 0.f, 0.f, 0.f}};
; #pragma unroll
;     for (int T = 0; T < 2; ++T)
; #pragma unroll
;         for (int s2 = 0; s2 < 4; ++s2) sa[T] = __builtin_amdgcn_mfma_f32_16x16x32_fp8_fp8(cur.k[T][s2], qf[s2], sa[T], 0, 0, 0);
;     float sc[8]; bool vd[8]; float mx = -1e30f;
;     const bool act = lo == 0 || !SLC;
;     if (NOMASK) {
; #pragma unroll
;         for (int j = 0; j < 8; ++j) { sc[j] = sa[j >> 2][j & 3]; vd[j] = act; }
;         mx = fmaxf(fmaxf(fmaxf(sc[0], sc[1]), fmaxf(sc[2], sc[3])), fmaxf(fmaxf(sc[4], sc[5]), fmaxf(sc[6], sc[7])));
;         mx = act ? mx : -1e30f;
;     } else {
; #pragma unroll
;         for (int T = 0; T < 2; ++T)
; #pragma unroll
;             for (int r = 0; r < 4; ++r) { const int p = pos0 + 16 * T + 4 * kq + r; const bool v = (p >= lo) & (p <= hi); const float x = sa[T][r];
;                 sc[4 * T + r] = x; vd[4 * T + r] = v; mx = v ? fmaxf(mx, x) : mx; }
;     }
;     if (__builtin_amdgcn_ballot_w64(mx > st.m + 4.f) != 0ull) {
;         mx = fmaxf(mx, __shfl_xor(mx, 16)); mx = fmaxf(mx, __shfl_xor(mx, 32));
;         const float mn = fmaxf(st.m, mx), alpha = __builtin_amdgcn_exp2f(st.m - mn); st.m = mn; st.l *= alpha;
; #pragma unroll
;         for (int j = 0; j < 8; ++j) st.o[j] = st.o[j] * alpha;
;     }
;     f32x4 pa, pb; float ps = 0.f;
;     const float mref = st.m - 4.f;
;     if (NOMASK) {
; #pragma unroll
;         for (int j = 0; j < 4; ++j) { pa[j] = __builtin_amdgcn_exp2f(sc[j] - mref); pb[j] = __builtin_amdgcn_exp2f(sc[4 + j] - mref); }
;         if (SLC) {
; #pragma unroll
;             for (int j = 0; j < 4; ++j) { pa[j] = act ? pa[j] : 0.f; pb[j] = act ? pb[j] : 0.f; }
;         }
; #pragma unroll
;         for (int j = 0; j < 4; ++j) ps += pa[j] + pb[j];
;     } else {
; #pragma unroll
;         for (int j = 0; j < 4; ++j) { pa[j] = vd[j] ? __builtin_amdgcn_exp2f(sc[j] - mref) : 0.f; pb[j] = vd[4 + j] ? __builtin_amdgcn_exp2f(sc[4 + j] - mref) : 0.f; ps += pa[j] + pb[j]; }
;     }
;     st.l += ps;
;     const u32x2 pw = pack8_fp8(pa, pb);
.LBB0_900:
	v_lshl_add_u64 v[244:245], v[204:205], 0, v[118:119]
	global_load_dwordx4 v[186:189], v[244:245], off
	global_load_dwordx4 v[190:193], v[244:245], off offset:1024
	global_load_dwordx4 v[194:197], v[244:245], off offset:2048
	global_load_dwordx4 v[198:201], v[244:245], off offset:3072
	v_lshl_add_u64 v[246:247], v[202:203], 0, v[118:119]
	global_load_dwordx4 v[170:173], v[246:247], off
	global_load_dwordx4 v[174:177], v[246:247], off offset:1024
	global_load_dwordx4 v[178:181], v[246:247], off offset:2048
	global_load_dwordx4 v[182:185], v[246:247], off offset:3072
	s_waitcnt vmcnt(20)
	v_mfma_f32_16x16x32_fp8_fp8 v[2:5], v[138:139], v[78:79], 0
	v_mov_b64_e32 v[74:75], v[38:39]
	v_mov_b64_e32 v[70:71], v[42:43]
	v_mov_b64_e32 v[30:31], v[44:45]
	v_mfma_f32_16x16x32_fp8_fp8 v[6:9], v[146:147], v[78:79], 0
	v_mov_b64_e32 v[26:27], v[48:49]
	v_mov_b64_e32 v[22:23], v[52:53]
	v_mov_b64_e32 v[18:19], v[56:57]
	v_mfma_f32_16x16x32_fp8_fp8 v[2:5], v[140:141], v[80:81], v[2:5]
	v_mov_b64_e32 v[14:15], v[60:61]
	v_mov_b32_e32 v229, v133
	v_mov_b64_e32 v[72:73], v[36:37]
	v_mfma_f32_16x16x32_fp8_fp8 v[6:9], v[148:149], v[80:81], v[6:9]
	v_mov_b64_e32 v[68:69], v[40:41]
	v_mov_b64_e32 v[32:33], v[46:47]
	v_mov_b64_e32 v[28:29], v[50:51]
	v_mfma_f32_16x16x32_fp8_fp8 v[2:5], v[142:143], v[82:83], v[2:5]
	v_mov_b64_e32 v[24:25], v[54:55]
	v_mov_b64_e32 v[20:21], v[58:59]
	v_mov_b64_e32 v[16:17], v[62:63]
	v_mfma_f32_16x16x32_fp8_fp8 v[6:9], v[150:151], v[82:83], v[6:9]
	v_mov_b32_e32 v34, v230
	v_mfma_f32_16x16x32_fp8_fp8 v[2:5], v[144:145], v[84:85], v[2:5]
	v_mfma_f32_16x16x32_fp8_fp8 v[6:9], v[152:153], v[84:85], v[6:9]
	s_nop 5
	v_max_f32_e32 v0, v3, v3
	v_max_f32_e32 v10, v2, v2
	v_max_f32_e32 v0, v10, v0
	v_max_f32_e32 v10, v5, v5
	v_max_f32_e32 v11, v4, v4
	v_max_f32_e32 v10, v11, v10
	v_max_f32_e32 v11, v9, v9
	v_max_f32_e32 v12, v8, v8
	v_max_f32_e32 v11, v12, v11
	v_max3_f32 v11, v6, v7, v11
	v_max3_f32 v0, v0, v10, v11
	v_mov_b64_e32 v[10:11], v[64:65]
	v_cmp_gt_f32_e32 vcc, v0, v231
	v_mov_b64_e32 v[12:13], v[66:67]
	s_cbranch_vccz .LBB0_902
	ds_bpermute_b32 v10, v227, v0
	v_max_f32_e32 v0, v0, v0
	s_waitcnt lgkmcnt(0)
	v_max_f32_e32 v10, v10, v10
	v_max_f32_e32 v0, v0, v10
	ds_bpermute_b32 v10, v226, v0
	s_waitcnt lgkmcnt(0)
	v_max3_f32 v229, v133, v0, v10
	v_sub_f32_e32 v0, v133, v229
	v_exp_f32_e32 v0, v0
	s_nop 0
	v_mul_f32_e32 v34, v230, v0
	v_pk_mul_f32 v[12:13], v[66:67], v[0:1] op_sel_hi:[1,0]
	v_pk_mul_f32 v[10:11], v[64:65], v[0:1] op_sel_hi:[1,0]
	v_pk_mul_f32 v[16:17], v[62:63], v[0:1] op_sel_hi:[1,0]
	v_pk_mul_f32 v[14:15], v[60:61], v[0:1] op_sel_hi:[1,0]
	v_pk_mul_f32 v[20:21], v[58:59], v[0:1] op_sel_hi:[1,0]
	v_pk_mul_f32 v[18:19], v[56:57], v[0:1] op_sel_hi:[1,0]
	v_pk_mul_f32 v[24:25], v[54:55], v[0:1] op_sel_hi:[1,0]
	v_pk_mul_f32 v[22:23], v[52:53], v[0:1] op_sel_hi:[1,0]
	v_pk_mul_f32 v[28:29], v[50:51], v[0:1] op_sel_hi:[1,0]
	v_pk_mul_f32 v[26:27], v[48:49], v[0:1] op_sel_hi:[1,0]
	v_pk_mul_f32 v[32:33], v[46:47], v[0:1] op_sel_hi:[1,0]
	v_pk_mul_f32 v[30:31], v[44:45], v[0:1] op_sel_hi:[1,0]
	v_pk_mul_f32 v[70:71], v[42:43], v[0:1] op_sel_hi:[1,0]
	v_pk_mul_f32 v[68:69], v[40:41], v[0:1] op_sel_hi:[1,0]
	v_pk_mul_f32 v[74:75], v[38:39], v[0:1] op_sel_hi:[1,0]
	v_pk_mul_f32 v[72:73], v[36:37], v[0:1] op_sel_hi:[1,0]
.LBB0_902:
	v_add_f32_e32 v232, -4.0, v229
	v_sub_f32_e32 v0, v2, v232
	v_exp_f32_e32 v233, v0
	v_sub_f32_e32 v0, v6, v232
	v_exp_f32_e32 v236, v0
	v_sub_f32_e32 v0, v3, v232
	v_exp_f32_e32 v2, v0
	v_sub_f32_e32 v0, v7, v232
	v_exp_f32_e32 v0, v0
	v_sub_f32_e32 v3, v4, v232
	v_exp_f32_e32 v237, v3
	v_sub_f32_e32 v3, v8, v232
	v_exp_f32_e32 v238, v3
	v_sub_f32_e32 v3, v5, v232
	v_exp_f32_e32 v4, v3
	v_sub_f32_e32 v3, v9, v232
	v_mov_b32_e32 v234, v1
	v_mov_b32_e32 v235, v1
	v_exp_f32_e32 v232, v3
	v_cvt_pk_fp8_f32 v234, v233, v2
	v_cvt_pk_fp8_f32 v235, v236, v0
	v_add_f32_e32 v3, v233, v236
	v_pk_add_f32 v[2:3], v[2:3], v[0:1]
	v_cvt_pk_fp8_f32 v234, v237, v4 op_sel:[0,0,1]
	v_cvt_pk_fp8_f32 v235, v238, v232 op_sel:[0,0,1]
	v_pk_add_f32 v[2:3], v[2:3], v[2:3] op_sel_hi:[0,1]
	v_add_f32_e32 v5, v237, v238
	v_mov_b32_e32 v233, v3
	v_pk_add_f32 v[2:3], v[4:5], v[232:233]
	s_waitcnt vmcnt(19)
	v_mfma_f32_16x16x32_fp8_fp8 v[6:9], v[90:91], v[234:235], v[10:13]
	v_add_f32_e32 v0, v2, v3
	v_add_f32_e32 v34, v0, v34
	v_mfma_f32_16x16x32_fp8_fp8 v[10:13], v[92:93], v[234:235], v[14:17]
	s_waitcnt vmcnt(18)
	v_mfma_f32_16x16x32_fp8_fp8 v[14:17], v[94:95], v[234:235], v[18:21]
	v_mfma_f32_16x16x32_fp8_fp8 v[18:21], v[96:97], v[234:235], v[22:25]
	s_waitcnt vmcnt(17)
	v_mfma_f32_16x16x32_fp8_fp8 v[22:25], v[98:99], v[234:235], v[26:29]
	v_mfma_f32_16x16x32_fp8_fp8 v[26:29], v[100:101], v[234:235], v[30:33]
	s_waitcnt vmcnt(16)
	v_mfma_f32_16x16x32_fp8_fp8 v[30:33], v[102:103], v[234:235], v[68:71]
	v_mfma_f32_16x16x32_fp8_fp8 v[2:5], v[104:105], v[234:235], v[72:75]
	s_branch .LBB0_896
; template <bool SLC, bool NOMASK> ...
;     const int kq = lane >> 4;
;     const int pos0 = SLC ? (dcur & 0xfffff) : dcur;
;     const int lo = SLC ? ((((dcur >> 20) == qi) | ((dcur >> 20) == 4)) ? 0 : (1 << 30)) : lo_in;
;     load_frag8(nxt, KF, VF, SLC ? (dnext & 0xfffff) : dnext, lane);
;     f32x4 sa[2] = {(f32x4){0.f, 0.f, 0.f, 0.f}, (f32x4){0.f, 0.f, 0.f, 0.f}};
; #pragma unroll
;     for (int T = 0; T < 2; ++T)
; #pragma unroll
;         for (int s2 = 0; s2 < 4; ++s2) sa[T] = __builtin_amdgcn_mfma_f32_16x16x32_fp8_fp8(cur.k[T][s2], qf[s2], sa[T], 0, 0, 0);
;     float sc[8]; bool vd[8]; float mx = -1e30f;
;     const bool act = lo == 0 || !SLC;
;     if (NOMASK) {
; #pragma unroll
;         for (int j = 0; j < 8; ++j) { sc[j] = sa[j >> 2][j & 3]; vd[j] = act; }
;         mx = fmaxf(fmaxf(fmaxf(sc[0], sc[1]), fmaxf(sc[2], sc[3])), fmaxf(fmaxf(sc[4], sc[5]), fmaxf(sc[6], sc[7])));
;         mx = act ? mx : -1e30f;
;     } else {
; #pragma unroll
;         for (int T = 0; T < 2; ++T)
; #pragma unroll
;             for (int r = 0; r < 4; ++r) { const int p = pos0 + 16 * T + 4 * kq + r; const bool v = (p >= lo) & (p <= hi); const float x = sa[T][r];
;                 sc[4 * T + r] = x; vd[4 * T + r] = v; mx = v ? fmaxf(mx, x) : mx; }
;     }
;     if (__builtin_amdgcn_ballot_w64(mx > st.m + 4.f) != 0ull) {
;         mx = fmaxf(mx, __shfl_xor(mx, 16)); mx = fmaxf(mx, __shfl_xor(mx, 32));
;         const float mn = fmaxf(st.m, mx), alpha = __builtin_amdgcn_exp2f(st.m - mn); st.m = mn; st.l *= alpha;
; #pragma unroll
;         for (int j = 0; j < 8; ++j) st.o[j] = st.o[j] * alpha;
;     }
;     f32x4 pa, pb; float ps = 0.f;
;     const float mref = st.m - 4.f;
;     if (NOMASK) {
; #pragma unroll
;         for (int j = 0; j < 4; ++j) { pa[j] = __builtin_amdgcn_exp2f(sc[j] - mref); pb[j] = __builtin_amdgcn_exp2f(sc[4 + j] - mref); }
;         if (SLC) {
; #pragma unroll
;             for (int j = 0; j < 4; ++j) { pa[j] = act ? pa[j] : 0.f; pb[j] = act ? pb[j] : 0.f; }
;         }
; #pragma unroll
;         for (int j = 0; j < 4; ++j) ps += pa[j] + pb[j];
;     } else {
; #pragma unroll
;         for (int j = 0; j < 4; ++j) { pa[j] = vd[j] ? __builtin_amdgcn_exp2f(sc[j] - mref) : 0.f; pb[j] = vd[4 + j] ? __builtin_amdgcn_exp2f(sc[4 + j] - mref) : 0.f; ps += pa[j] + pb[j]; }
;     }
;     st.l += ps;
;     const u32x2 pw = pack8_fp8(pa, pb);
.LBB0_903:
	v_lshl_add_u64 v[244:245], v[204:205], 0, v[118:119]
	global_load_dwordx4 v[186:189], v[244:245], off
	global_load_dwordx4 v[190:193], v[244:245], off offset:1024
	global_load_dwordx4 v[194:197], v[244:245], off offset:2048
	global_load_dwordx4 v[198:201], v[244:245], off offset:3072
	v_lshl_add_u64 v[246:247], v[202:203], 0, v[118:119]
	global_load_dwordx4 v[170:173], v[246:247], off
	global_load_dwordx4 v[174:177], v[246:247], off offset:1024
	global_load_dwordx4 v[178:181], v[246:247], off offset:2048
	global_load_dwordx4 v[182:185], v[246:247], off offset:3072
	s_waitcnt vmcnt(20)
	v_mfma_f32_16x16x32_fp8_fp8 v[2:5], v[138:139], v[78:79], 0
	v_add_u32_e32 v0, s14, v211
	v_cmp_ge_i32_e32 vcc, v0, v35
	v_cmp_le_i32_e64 s[10:11], v0, v132
	v_mfma_f32_16x16x32_fp8_fp8 v[2:5], v[140:141], v[80:81], v[2:5]
	s_and_b64 s[16:17], vcc, s[10:11]
	v_add_u32_e32 v11, 1, v0
	v_cmp_ge_i32_e32 vcc, v11, v35
	v_mfma_f32_16x16x32_fp8_fp8 v[2:5], v[142:143], v[82:83], v[2:5]
	v_cmp_lt_i32_e64 s[10:11], v0, v132
	s_and_b64 s[12:13], s[10:11], vcc
	v_mfma_f32_16x16x32_fp8_fp8 v[6:9], v[146:147], v[78:79], 0
	v_mfma_f32_16x16x32_fp8_fp8 v[2:5], v[144:145], v[84:85], v[2:5]
	v_mfma_f32_16x16x32_fp8_fp8 v[6:9], v[148:149], v[80:81], v[6:9]
	v_mfma_f32_16x16x32_fp8_fp8 v[6:9], v[150:151], v[82:83], v[6:9]
	s_nop 3
	v_max_f32_e32 v10, v2, v2
	v_max_f32_e32 v10, 0xf149f2ca, v10
	v_cndmask_b32_e64 v10, v223, v10, s[16:17]
	v_max_f32_e32 v11, v3, v3
	v_max_f32_e32 v11, v10, v11
	v_cndmask_b32_e64 v10, v10, v11, s[12:13]
	v_add_u32_e32 v11, 2, v0
	v_cmp_ge_i32_e32 vcc, v11, v35
	v_cmp_le_i32_e64 s[10:11], v11, v132
	v_max_f32_e32 v11, v4, v4
	v_max_f32_e32 v11, v10, v11
	s_and_b64 s[14:15], vcc, s[10:11]
	v_mfma_f32_16x16x32_fp8_fp8 v[6:9], v[152:153], v[84:85], v[6:9]
	v_cndmask_b32_e64 v10, v10, v11, s[14:15]
	v_add_u32_e32 v11, 3, v0
	v_cmp_ge_i32_e32 vcc, v11, v35
	v_cmp_le_i32_e64 s[10:11], v11, v132
	v_max_f32_e32 v11, v5, v5
	v_max_f32_e32 v11, v10, v11
	s_and_b64 s[10:11], vcc, s[10:11]
	v_cndmask_b32_e64 v10, v10, v11, s[10:11]
	v_add_u32_e32 v11, 16, v0
	v_cmp_ge_i32_e32 vcc, v11, v35
	v_cmp_le_i32_e64 s[18:19], v11, v132
	v_max_f32_e32 v11, v6, v6
	v_max_f32_e32 v11, v10, v11
	s_and_b64 s[24:25], vcc, s[18:19]
	v_cndmask_b32_e64 v10, v10, v11, s[24:25]
	v_add_u32_e32 v11, 17, v0
	v_cmp_ge_i32_e32 vcc, v11, v35
	v_cmp_le_i32_e64 s[18:19], v11, v132
	v_max_f32_e32 v11, v10, v10
	v_max_f32_e32 v12, v7, v7
	v_max_f32_e32 v11, v11, v12
	s_and_b64 s[20:21], vcc, s[18:19]
	v_cndmask_b32_e64 v10, v10, v11, s[20:21]
	v_add_u32_e32 v11, 18, v0
	v_cmp_ge_i32_e32 vcc, v11, v35
	v_cmp_le_i32_e64 s[18:19], v11, v132
	v_max_f32_e32 v11, v10, v10
	v_max_f32_e32 v12, v8, v8
	v_max_f32_e32 v11, v11, v12
	s_and_b64 s[22:23], vcc, s[18:19]
	v_cndmask_b32_e64 v10, v10, v11, s[22:23]
	v_add_u32_e32 v0, 19, v0
	v_cmp_ge_i32_e32 vcc, v0, v35
	v_cmp_le_i32_e64 s[18:19], v0, v132
	v_max_f32_e32 v0, v10, v10
	v_max_f32_e32 v11, v9, v9
	v_max_f32_e32 v0, v0, v11
	s_and_b64 s[18:19], vcc, s[18:19]
	v_cndmask_b32_e64 v0, v10, v0, s[18:19]
	v_cmp_gt_f32_e32 vcc, v0, v231
	s_cbranch_vccz .LBB0_905
	ds_bpermute_b32 v10, v227, v0
	v_max_f32_e32 v0, v0, v0
	s_waitcnt lgkmcnt(0)
	v_max_f32_e32 v10, v10, v10
	v_max_f32_e32 v0, v0, v10
	ds_bpermute_b32 v10, v226, v0
	s_waitcnt lgkmcnt(0)
	v_max3_f32 v10, v133, v0, v10
	v_sub_f32_e32 v0, v133, v10
	v_exp_f32_e32 v0, v0
	v_mov_b32_e32 v133, v10
	v_mul_f32_e32 v230, v230, v0
	v_pk_mul_f32 v[66:67], v[66:67], v[0:1] op_sel_hi:[1,0]
	v_pk_mul_f32 v[64:65], v[64:65], v[0:1] op_sel_hi:[1,0]
	v_pk_mul_f32 v[62:63], v[62:63], v[0:1] op_sel_hi:[1,0]
	v_pk_mul_f32 v[60:61], v[60:61], v[0:1] op_sel_hi:[1,0]
	v_pk_mul_f32 v[58:59], v[58:59], v[0:1] op_sel_hi:[1,0]
	v_pk_mul_f32 v[56:57], v[56:57], v[0:1] op_sel_hi:[1,0]
	v_pk_mul_f32 v[54:55], v[54:55], v[0:1] op_sel_hi:[1,0]
	v_pk_mul_f32 v[52:53], v[52:53], v[0:1] op_sel_hi:[1,0]
	v_pk_mul_f32 v[50:51], v[50:51], v[0:1] op_sel_hi:[1,0]
	v_pk_mul_f32 v[48:49], v[48:49], v[0:1] op_sel_hi:[1,0]
	v_pk_mul_f32 v[46:47], v[46:47], v[0:1] op_sel_hi:[1,0]
	v_pk_mul_f32 v[44:45], v[44:45], v[0:1] op_sel_hi:[1,0]
	v_pk_mul_f32 v[42:43], v[42:43], v[0:1] op_sel_hi:[1,0]
	v_pk_mul_f32 v[40:41], v[40:41], v[0:1] op_sel_hi:[1,0]
	v_pk_mul_f32 v[38:39], v[38:39], v[0:1] op_sel_hi:[1,0]
	v_pk_mul_f32 v[36:37], v[36:37], v[0:1] op_sel_hi:[1,0]
.LBB0_905:
	v_add_f32_e32 v0, -4.0, v133
	v_sub_f32_e32 v2, v2, v0
	v_exp_f32_e32 v2, v2
	v_sub_f32_e32 v6, v6, v0
	v_exp_f32_e32 v6, v6
	v_sub_f32_e32 v4, v4, v0
	v_cndmask_b32_e64 v26, 0, v2, s[16:17]
	v_sub_f32_e32 v2, v3, v0
	v_exp_f32_e32 v2, v2
	v_sub_f32_e32 v3, v7, v0
	v_exp_f32_e32 v3, v3
	v_cndmask_b32_e64 v27, 0, v6, s[24:25]
	v_sub_f32_e32 v6, v8, v0
	v_cndmask_b32_e64 v28, 0, v2, s[12:13]
	v_sub_f32_e32 v2, v5, v0
	v_sub_f32_e32 v0, v9, v0
	v_exp_f32_e32 v4, v4
	v_exp_f32_e32 v6, v6
	v_cndmask_b32_e64 v29, 0, v3, s[20:21]
	v_exp_f32_e32 v5, v2
	v_exp_f32_e32 v0, v0
	v_mov_b32_e32 v2, v1
	v_mov_b32_e32 v3, v1
	v_cvt_pk_fp8_f32 v2, v26, v28
	v_cvt_pk_fp8_f32 v3, v27, v29
	v_cndmask_b32_e64 v4, 0, v4, s[14:15]
	v_cndmask_b32_e64 v30, 0, v6, s[22:23]
	v_cndmask_b32_e64 v5, 0, v5, s[10:11]
	v_cndmask_b32_e64 v0, 0, v0, s[18:19]
	v_cvt_pk_fp8_f32 v2, v4, v5 op_sel:[0,0,1]
	v_cvt_pk_fp8_f32 v3, v30, v0 op_sel:[0,0,1]
	v_add_f32_e32 v26, v26, v27
	v_add_f32_e32 v31, 0, v26
	v_add_f32_e32 v32, v28, v29
	v_add_f32_e32 v31, v32, v31
	v_add_f32_e32 v4, v4, v30
	v_add_f32_e32 v4, v4, v31
	v_add_f32_e32 v0, v5, v0
	s_waitcnt vmcnt(19)
	v_mfma_f32_16x16x32_fp8_fp8 v[6:9], v[90:91], v[2:3], v[64:67]
	v_add_f32_e32 v0, v0, v4
	v_add_f32_e32 v34, v230, v0
	v_mov_b32_e32 v229, v133
	v_mfma_f32_16x16x32_fp8_fp8 v[10:13], v[92:93], v[2:3], v[60:63]
	s_waitcnt vmcnt(18)
	v_mfma_f32_16x16x32_fp8_fp8 v[14:17], v[94:95], v[2:3], v[56:59]
	v_mfma_f32_16x16x32_fp8_fp8 v[18:21], v[96:97], v[2:3], v[52:55]
	s_waitcnt vmcnt(17)
	v_mfma_f32_16x16x32_fp8_fp8 v[22:25], v[98:99], v[2:3], v[48:51]
	v_mfma_f32_16x16x32_fp8_fp8 v[26:29], v[100:101], v[2:3], v[44:47]
	s_waitcnt vmcnt(16)
	v_mfma_f32_16x16x32_fp8_fp8 v[30:33], v[102:103], v[2:3], v[40:43]
	v_mfma_f32_16x16x32_fp8_fp8 v[2:5], v[104:105], v[2:3], v[36:39]
	s_cmp_ge_i32 s58, s27
	s_mov_b64 s[10:11], -1
	s_cbranch_scc0 .LBB0_897

; template <bool SLC, bool NOMASK> ...
;     const int kq = lane >> 4;
;     const int pos0 = SLC ? (dcur & 0xfffff) : dcur;
;     const int lo = SLC ? ((((dcur >> 20) == qi) | ((dcur >> 20) == 4)) ? 0 : (1 << 30)) : lo_in;
;     load_frag8(nxt, KF, VF, SLC ? (dnext & 0xfffff) : dnext, lane);
;     f32x4 sa[2] = {(f32x4){0.f, 0.f, 0.f, 0.f}, (f32x4){0.f, 0.f, 0.f, 0.f}};
; #pragma unroll
;     for (int T = 0; T < 2; ++T)
; #pragma unroll
;         for (int s2 = 0; s2 < 4; ++s2) sa[T] = __builtin_amdgcn_mfma_f32_16x16x32_fp8_fp8(cur.k[T][s2], qf[s2], sa[T], 0, 0, 0);
;     float sc[8]; bool vd[8]; float mx = -1e30f;
;     const bool act = lo == 0 || !SLC;
;     if (NOMASK) {
; #pragma unroll
;         for (int j = 0; j < 8; ++j) { sc[j] = sa[j >> 2][j & 3]; vd[j] = act; }
;         mx = fmaxf(fmaxf(fmaxf(sc[0], sc[1]), fmaxf(sc[2], sc[3])), fmaxf(fmaxf(sc[4], sc[5]), fmaxf(sc[6], sc[7])));
;         mx = act ? mx : -1e30f;
;     } else {
; #pragma unroll
;         for (int T = 0; T < 2; ++T)
; #pragma unroll
;             for (int r = 0; r < 4; ++r) { const int p = pos0 + 16 * T + 4 * kq + r; const bool v = (p >= lo) & (p <= hi); const float x = sa[T][r];
;                 sc[4 * T + r] = x; vd[4 * T + r] = v; mx = v ? fmaxf(mx, x) : mx; }
;     }
;     if (__builtin_amdgcn_ballot_w64(mx > st.m + 4.f) != 0ull) {
;         mx = fmaxf(mx, __shfl_xor(mx, 16)); mx = fmaxf(mx, __shfl_xor(mx, 32));
;         const float mn = fmaxf(st.m, mx), alpha = __builtin_amdgcn_exp2f(st.m - mn); st.m = mn; st.l *= alpha;
; #pragma unroll
;         for (int j = 0; j < 8; ++j) st.o[j] = st.o[j] * alpha;
;     }
;     f32x4 pa, pb; float ps = 0.f;
;     const float mref = st.m - 4.f;
;     if (NOMASK) {
; #pragma unroll
;         for (int j = 0; j < 4; ++j) { pa[j] = __builtin_amdgcn_exp2f(sc[j] - mref); pb[j] = __builtin_amdgcn_exp2f(sc[4 + j] - mref); }
;         if (SLC) {
; #pragma unroll
;             for (int j = 0; j < 4; ++j) { pa[j] = act ? pa[j] : 0.f; pb[j] = act ? pb[j] : 0.f; }
;         }
; #pragma unroll
;         for (int j = 0; j < 4; ++j) ps += pa[j] + pb[j];
;     } else {
; #pragma unroll
;         for (int j = 0; j < 4; ++j) { pa[j] = vd[j] ? __builtin_amdgcn_exp2f(sc[j] - mref) : 0.f; pb[j] = vd[4 + j] ? __builtin_amdgcn_exp2f(sc[4 + j] - mref) : 0.f; ps += pa[j] + pb[j]; }
;     }
;     st.l += ps;
;     const u32x2 pw = pack8_fp8(pa, pb);
.LBB0_907:
	v_lshl_add_u64 v[244:245], v[204:205], 0, v[118:119]
	global_load_dwordx4 v[138:141], v[244:245], off
	global_load_dwordx4 v[142:145], v[244:245], off offset:1024
	global_load_dwordx4 v[146:149], v[244:245], off offset:2048
	global_load_dwordx4 v[150:153], v[244:245], off offset:3072
	v_lshl_add_u64 v[246:247], v[202:203], 0, v[118:119]
	global_load_dwordx4 v[90:93], v[246:247], off
	global_load_dwordx4 v[94:97], v[246:247], off offset:1024
	global_load_dwordx4 v[98:101], v[246:247], off offset:2048
	global_load_dwordx4 v[102:105], v[246:247], off offset:3072
	s_waitcnt vmcnt(20)
	v_mfma_f32_16x16x32_fp8_fp8 v[36:39], v[154:155], v[78:79], 0
	v_mov_b64_e32 v[74:75], v[4:5]
	v_mov_b64_e32 v[70:71], v[32:33]
	v_mov_b64_e32 v[66:67], v[28:29]
	v_mfma_f32_16x16x32_fp8_fp8 v[40:43], v[162:163], v[78:79], 0
	v_mov_b64_e32 v[62:63], v[24:25]
	v_mov_b64_e32 v[58:59], v[20:21]
	v_mov_b64_e32 v[54:55], v[16:17]
	v_mfma_f32_16x16x32_fp8_fp8 v[36:39], v[156:157], v[80:81], v[36:39]
	v_mov_b64_e32 v[50:51], v[12:13]
	v_mov_b32_e32 v230, v229
	v_mov_b64_e32 v[72:73], v[2:3]
	v_mfma_f32_16x16x32_fp8_fp8 v[40:43], v[164:165], v[80:81], v[40:43]
	v_mov_b64_e32 v[68:69], v[30:31]
	v_mov_b64_e32 v[64:65], v[26:27]
	v_mov_b64_e32 v[60:61], v[22:23]
	v_mfma_f32_16x16x32_fp8_fp8 v[36:39], v[158:159], v[82:83], v[36:39]
	v_mov_b64_e32 v[56:57], v[18:19]
	v_mov_b64_e32 v[52:53], v[14:15]
	v_mov_b64_e32 v[48:49], v[10:11]
	v_mfma_f32_16x16x32_fp8_fp8 v[40:43], v[166:167], v[82:83], v[40:43]
	v_mov_b32_e32 v231, v34
	v_mfma_f32_16x16x32_fp8_fp8 v[36:39], v[160:161], v[84:85], v[36:39]
	v_mfma_f32_16x16x32_fp8_fp8 v[40:43], v[168:169], v[84:85], v[40:43]
	s_nop 5
	v_max_f32_e32 v0, v37, v37
	v_max_f32_e32 v44, v36, v36
	v_max_f32_e32 v0, v44, v0
	v_max_f32_e32 v44, v39, v39
	v_max_f32_e32 v45, v38, v38
	v_max_f32_e32 v44, v45, v44
	v_max_f32_e32 v45, v43, v43
	v_max_f32_e32 v46, v42, v42
	v_max_f32_e32 v45, v46, v45
	v_max3_f32 v45, v40, v41, v45
	v_max3_f32 v0, v0, v44, v45
	v_mov_b64_e32 v[46:47], v[8:9]
	v_cmp_gt_f32_e32 vcc, v0, v133
	v_mov_b64_e32 v[44:45], v[6:7]
	s_cbranch_vccz .LBB0_909
	ds_bpermute_b32 v44, v227, v0
	v_max_f32_e32 v0, v0, v0
	s_waitcnt lgkmcnt(0)
	v_max_f32_e32 v44, v44, v44
	v_max_f32_e32 v0, v0, v44
	ds_bpermute_b32 v44, v226, v0
	s_waitcnt lgkmcnt(0)
	v_max3_f32 v230, v229, v0, v44
	v_sub_f32_e32 v0, v229, v230
	v_exp_f32_e32 v0, v0
	s_nop 0
	v_mul_f32_e32 v231, v34, v0
	v_pk_mul_f32 v[46:47], v[8:9], v[0:1] op_sel_hi:[1,0]
	v_pk_mul_f32 v[44:45], v[6:7], v[0:1] op_sel_hi:[1,0]
	v_pk_mul_f32 v[50:51], v[12:13], v[0:1] op_sel_hi:[1,0]
	v_pk_mul_f32 v[48:49], v[10:11], v[0:1] op_sel_hi:[1,0]
	v_pk_mul_f32 v[54:55], v[16:17], v[0:1] op_sel_hi:[1,0]
	v_pk_mul_f32 v[52:53], v[14:15], v[0:1] op_sel_hi:[1,0]
	v_pk_mul_f32 v[58:59], v[20:21], v[0:1] op_sel_hi:[1,0]
	v_pk_mul_f32 v[56:57], v[18:19], v[0:1] op_sel_hi:[1,0]
	v_pk_mul_f32 v[62:63], v[24:25], v[0:1] op_sel_hi:[1,0]
	v_pk_mul_f32 v[60:61], v[22:23], v[0:1] op_sel_hi:[1,0]
	v_pk_mul_f32 v[66:67], v[28:29], v[0:1] op_sel_hi:[1,0]
	v_pk_mul_f32 v[64:65], v[26:27], v[0:1] op_sel_hi:[1,0]
	v_pk_mul_f32 v[70:71], v[32:33], v[0:1] op_sel_hi:[1,0]
	v_pk_mul_f32 v[68:69], v[30:31], v[0:1] op_sel_hi:[1,0]
	v_pk_mul_f32 v[74:75], v[4:5], v[0:1] op_sel_hi:[1,0]
	v_pk_mul_f32 v[72:73], v[2:3], v[0:1] op_sel_hi:[1,0]
.LBB0_909:
	v_add_f32_e32 v233, -4.0, v230
	v_sub_f32_e32 v0, v36, v233
	v_exp_f32_e32 v235, v0
	v_sub_f32_e32 v0, v40, v233
	v_exp_f32_e32 v237, v0
	v_sub_f32_e32 v0, v37, v233
	v_exp_f32_e32 v232, v0
	v_sub_f32_e32 v0, v41, v233
	v_exp_f32_e32 v0, v0
	v_sub_f32_e32 v36, v38, v233
	v_exp_f32_e32 v240, v36
	v_sub_f32_e32 v36, v42, v233
	v_exp_f32_e32 v241, v36
	v_sub_f32_e32 v36, v39, v233
	v_exp_f32_e32 v234, v36
	v_sub_f32_e32 v36, v43, v233
	v_mov_b32_e32 v238, v1
	v_mov_b32_e32 v239, v1
	v_exp_f32_e32 v236, v36
	v_cvt_pk_fp8_f32 v238, v235, v232
	v_cvt_pk_fp8_f32 v239, v237, v0
	v_add_f32_e32 v233, v235, v237
	v_add_f32_e32 v235, v240, v241
	v_cvt_pk_fp8_f32 v238, v240, v234 op_sel:[0,0,1]
	v_cvt_pk_fp8_f32 v239, v241, v236 op_sel:[0,0,1]
	s_nop 0
	s_waitcnt vmcnt(19)
	v_mfma_f32_16x16x32_fp8_fp8 v[36:39], v[106:107], v[238:239], v[44:47]
	v_mfma_f32_16x16x32_fp8_fp8 v[44:47], v[110:111], v[238:239], v[52:55]
	s_waitcnt vmcnt(18)
	v_mfma_f32_16x16x32_fp8_fp8 v[52:55], v[114:115], v[238:239], v[60:63]
	s_nop 2
	v_add_f32_e64 v60, v232, v0
	v_add_f32_e64 v61, v233, v1
	v_mfma_f32_16x16x32_fp8_fp8 v[40:43], v[108:109], v[238:239], v[48:51]
	v_pk_add_f32 v[60:61], v[60:61], v[60:61] op_sel_hi:[0,1]
	v_mov_b32_e32 v237, v61
	s_waitcnt vmcnt(17)
	v_mfma_f32_16x16x32_fp8_fp8 v[48:51], v[112:113], v[238:239], v[56:59]
	v_mfma_f32_16x16x32_fp8_fp8 v[56:59], v[116:117], v[238:239], v[64:67]
	s_nop 2
	v_add_f32_e64 v64, v234, v236
	v_add_f32_e64 v65, v235, v237
	s_waitcnt vmcnt(16)
	v_mfma_f32_16x16x32_fp8_fp8 v[60:63], v[134:135], v[238:239], v[68:71]
	v_add_f32_e32 v0, v64, v65
	v_add_f32_e32 v231, v0, v231
	v_mfma_f32_16x16x32_fp8_fp8 v[64:67], v[136:137], v[238:239], v[72:75]
	s_branch .LBB0_899
; template <bool SLC, bool NOMASK> ...
;     const int kq = lane >> 4;
;     const int pos0 = SLC ? (dcur & 0xfffff) : dcur;
;     const int lo = SLC ? ((((dcur >> 20) == qi) | ((dcur >> 20) == 4)) ? 0 : (1 << 30)) : lo_in;
;     load_frag8(nxt, KF, VF, SLC ? (dnext & 0xfffff) : dnext, lane);
;     f32x4 sa[2] = {(f32x4){0.f, 0.f, 0.f, 0.f}, (f32x4){0.f, 0.f, 0.f, 0.f}};
; #pragma unroll
;     for (int T = 0; T < 2; ++T)
; #pragma unroll
;         for (int s2 = 0; s2 < 4; ++s2) sa[T] = __builtin_amdgcn_mfma_f32_16x16x32_fp8_fp8(cur.k[T][s2], qf[s2], sa[T], 0, 0, 0);
;     float sc[8]; bool vd[8]; float mx = -1e30f;
;     const bool act = lo == 0 || !SLC;
;     if (NOMASK) {
; #pragma unroll
;         for (int j = 0; j < 8; ++j) { sc[j] = sa[j >> 2][j & 3]; vd[j] = act; }
;         mx = fmaxf(fmaxf(fmaxf(sc[0], sc[1]), fmaxf(sc[2], sc[3])), fmaxf(fmaxf(sc[4], sc[5]), fmaxf(sc[6], sc[7])));
;         mx = act ? mx : -1e30f;
;     } else {
; #pragma unroll
;         for (int T = 0; T < 2; ++T)
; #pragma unroll
;             for (int r = 0; r < 4; ++r) { const int p = pos0 + 16 * T + 4 * kq + r; const bool v = (p >= lo) & (p <= hi); const float x = sa[T][r];
;                 sc[4 * T + r] = x; vd[4 * T + r] = v; mx = v ? fmaxf(mx, x) : mx; }
;     }
;     if (__builtin_amdgcn_ballot_w64(mx > st.m + 4.f) != 0ull) {
;         mx = fmaxf(mx, __shfl_xor(mx, 16)); mx = fmaxf(mx, __shfl_xor(mx, 32));
;         const float mn = fmaxf(st.m, mx), alpha = __builtin_amdgcn_exp2f(st.m - mn); st.m = mn; st.l *= alpha;
; #pragma unroll
;         for (int j = 0; j < 8; ++j) st.o[j] = st.o[j] * alpha;
;     }
;     f32x4 pa, pb; float ps = 0.f;
;     const float mref = st.m - 4.f;
;     if (NOMASK) {
; #pragma unroll
;         for (int j = 0; j < 4; ++j) { pa[j] = __builtin_amdgcn_exp2f(sc[j] - mref); pb[j] = __builtin_amdgcn_exp2f(sc[4 + j] - mref); }
;         if (SLC) {
; #pragma unroll
;             for (int j = 0; j < 4; ++j) { pa[j] = act ? pa[j] : 0.f; pb[j] = act ? pb[j] : 0.f; }
;         }
; #pragma unroll
;         for (int j = 0; j < 4; ++j) ps += pa[j] + pb[j];
;     } else {
; #pragma unroll
;         for (int j = 0; j < 4; ++j) { pa[j] = vd[j] ? __builtin_amdgcn_exp2f(sc[j] - mref) : 0.f; pb[j] = vd[4 + j] ? __builtin_amdgcn_exp2f(sc[4 + j] - mref) : 0.f; ps += pa[j] + pb[j]; }
;     }
;     st.l += ps;
;     const u32x2 pw = pack8_fp8(pa, pb);
.LBB0_910:
	v_lshl_add_u64 v[244:245], v[204:205], 0, v[118:119]
	global_load_dwordx4 v[138:141], v[244:245], off
	global_load_dwordx4 v[142:145], v[244:245], off offset:1024
	global_load_dwordx4 v[146:149], v[244:245], off offset:2048
	global_load_dwordx4 v[150:153], v[244:245], off offset:3072
	v_lshl_add_u64 v[246:247], v[202:203], 0, v[118:119]
	global_load_dwordx4 v[90:93], v[246:247], off
	global_load_dwordx4 v[94:97], v[246:247], off offset:1024
	global_load_dwordx4 v[98:101], v[246:247], off offset:2048
	global_load_dwordx4 v[102:105], v[246:247], off offset:3072
	s_waitcnt vmcnt(20)
	v_mfma_f32_16x16x32_fp8_fp8 v[36:39], v[154:155], v[78:79], 0
	v_add_u32_e32 v0, s66, v211
	v_cmp_ge_i32_e32 vcc, v0, v35
	v_cmp_le_i32_e64 s[10:11], v0, v132
	v_mfma_f32_16x16x32_fp8_fp8 v[36:39], v[156:157], v[80:81], v[36:39]
	s_and_b64 s[16:17], vcc, s[10:11]
	v_add_u32_e32 v45, 1, v0
	v_cmp_ge_i32_e32 vcc, v45, v35
	v_mfma_f32_16x16x32_fp8_fp8 v[36:39], v[158:159], v[82:83], v[36:39]
	v_cmp_lt_i32_e64 s[10:11], v0, v132
	s_and_b64 s[12:13], s[10:11], vcc
	v_mfma_f32_16x16x32_fp8_fp8 v[40:43], v[162:163], v[78:79], 0
	v_mfma_f32_16x16x32_fp8_fp8 v[36:39], v[160:161], v[84:85], v[36:39]
	v_mfma_f32_16x16x32_fp8_fp8 v[40:43], v[164:165], v[80:81], v[40:43]
	v_mfma_f32_16x16x32_fp8_fp8 v[40:43], v[166:167], v[82:83], v[40:43]
	s_nop 3
	v_max_f32_e32 v44, v36, v36
	v_max_f32_e32 v44, 0xf149f2ca, v44
	v_cndmask_b32_e64 v44, v223, v44, s[16:17]
	v_max_f32_e32 v45, v37, v37
	v_max_f32_e32 v45, v44, v45
	v_cndmask_b32_e64 v44, v44, v45, s[12:13]
	v_add_u32_e32 v45, 2, v0
	v_cmp_ge_i32_e32 vcc, v45, v35
	v_cmp_le_i32_e64 s[10:11], v45, v132
	v_max_f32_e32 v45, v38, v38
	v_max_f32_e32 v45, v44, v45
	s_and_b64 s[14:15], vcc, s[10:11]
	v_mfma_f32_16x16x32_fp8_fp8 v[40:43], v[168:169], v[84:85], v[40:43]
	v_cndmask_b32_e64 v44, v44, v45, s[14:15]
	v_add_u32_e32 v45, 3, v0
	v_cmp_ge_i32_e32 vcc, v45, v35
	v_cmp_le_i32_e64 s[10:11], v45, v132
	v_max_f32_e32 v45, v39, v39
	v_max_f32_e32 v45, v44, v45
	s_and_b64 s[10:11], vcc, s[10:11]
	v_cndmask_b32_e64 v44, v44, v45, s[10:11]
	v_add_u32_e32 v45, 16, v0
	v_cmp_ge_i32_e32 vcc, v45, v35
	v_cmp_le_i32_e64 s[18:19], v45, v132
	v_max_f32_e32 v45, v40, v40
	v_max_f32_e32 v45, v44, v45
	s_and_b64 s[24:25], vcc, s[18:19]
	v_cndmask_b32_e64 v44, v44, v45, s[24:25]
	v_add_u32_e32 v45, 17, v0
	v_cmp_ge_i32_e32 vcc, v45, v35
	v_cmp_le_i32_e64 s[18:19], v45, v132
	v_max_f32_e32 v45, v44, v44
	v_max_f32_e32 v46, v41, v41
	v_max_f32_e32 v45, v45, v46
	s_and_b64 s[20:21], vcc, s[18:19]
	v_cndmask_b32_e64 v44, v44, v45, s[20:21]
	v_add_u32_e32 v45, 18, v0
	v_cmp_ge_i32_e32 vcc, v45, v35
	v_cmp_le_i32_e64 s[18:19], v45, v132
	v_max_f32_e32 v45, v44, v44
	v_max_f32_e32 v46, v42, v42
	v_max_f32_e32 v45, v45, v46
	s_and_b64 s[22:23], vcc, s[18:19]
	v_cndmask_b32_e64 v44, v44, v45, s[22:23]
	v_add_u32_e32 v0, 19, v0
	v_cmp_ge_i32_e32 vcc, v0, v35
	v_cmp_le_i32_e64 s[18:19], v0, v132
	v_max_f32_e32 v0, v44, v44
	v_max_f32_e32 v45, v43, v43
	v_max_f32_e32 v0, v0, v45
	s_and_b64 s[18:19], vcc, s[18:19]
	v_cndmask_b32_e64 v0, v44, v0, s[18:19]
	v_cmp_gt_f32_e32 vcc, v0, v133
	s_cbranch_vccz .LBB0_912
	ds_bpermute_b32 v44, v227, v0
	v_max_f32_e32 v0, v0, v0
	s_waitcnt lgkmcnt(0)
	v_max_f32_e32 v44, v44, v44
	v_max_f32_e32 v0, v0, v44
	ds_bpermute_b32 v44, v226, v0
	s_waitcnt lgkmcnt(0)
	v_max3_f32 v44, v229, v0, v44
	v_sub_f32_e32 v0, v229, v44
	v_exp_f32_e32 v0, v0
	v_mov_b32_e32 v229, v44
	v_mul_f32_e32 v34, v34, v0
	v_pk_mul_f32 v[8:9], v[8:9], v[0:1] op_sel_hi:[1,0]
	v_pk_mul_f32 v[6:7], v[6:7], v[0:1] op_sel_hi:[1,0]
	v_pk_mul_f32 v[12:13], v[12:13], v[0:1] op_sel_hi:[1,0]
	v_pk_mul_f32 v[10:11], v[10:11], v[0:1] op_sel_hi:[1,0]
	v_pk_mul_f32 v[16:17], v[16:17], v[0:1] op_sel_hi:[1,0]
	v_pk_mul_f32 v[14:15], v[14:15], v[0:1] op_sel_hi:[1,0]
	v_pk_mul_f32 v[20:21], v[20:21], v[0:1] op_sel_hi:[1,0]
	v_pk_mul_f32 v[18:19], v[18:19], v[0:1] op_sel_hi:[1,0]
	v_pk_mul_f32 v[24:25], v[24:25], v[0:1] op_sel_hi:[1,0]
	v_pk_mul_f32 v[22:23], v[22:23], v[0:1] op_sel_hi:[1,0]
	v_pk_mul_f32 v[28:29], v[28:29], v[0:1] op_sel_hi:[1,0]
	v_pk_mul_f32 v[26:27], v[26:27], v[0:1] op_sel_hi:[1,0]
	v_pk_mul_f32 v[32:33], v[32:33], v[0:1] op_sel_hi:[1,0]
	v_pk_mul_f32 v[30:31], v[30:31], v[0:1] op_sel_hi:[1,0]
	v_pk_mul_f32 v[4:5], v[4:5], v[0:1] op_sel_hi:[1,0]
	v_pk_mul_f32 v[2:3], v[2:3], v[0:1] op_sel_hi:[1,0]
.LBB0_912:
	v_add_f32_e32 v0, -4.0, v229
	v_sub_f32_e32 v36, v36, v0
	v_exp_f32_e32 v36, v36
	v_sub_f32_e32 v40, v40, v0
	v_exp_f32_e32 v40, v40
	v_sub_f32_e32 v38, v38, v0
	v_cndmask_b32_e64 v56, 0, v36, s[16:17]
	v_sub_f32_e32 v36, v37, v0
	v_exp_f32_e32 v36, v36
	v_sub_f32_e32 v37, v41, v0
	v_exp_f32_e32 v37, v37
	v_cndmask_b32_e64 v57, 0, v40, s[24:25]
	v_sub_f32_e32 v40, v42, v0
	v_cndmask_b32_e64 v58, 0, v36, s[12:13]
	v_sub_f32_e32 v36, v39, v0
	v_sub_f32_e32 v0, v43, v0
	v_exp_f32_e32 v38, v38
	v_exp_f32_e32 v40, v40
	v_cndmask_b32_e64 v59, 0, v37, s[20:21]
	v_exp_f32_e32 v36, v36
	v_exp_f32_e32 v0, v0
	v_mov_b32_e32 v64, v1
	v_mov_b32_e32 v65, v1
	v_cvt_pk_fp8_f32 v64, v56, v58
	v_cvt_pk_fp8_f32 v65, v57, v59
	v_cndmask_b32_e64 v60, 0, v38, s[14:15]
	v_cndmask_b32_e64 v61, 0, v40, s[22:23]
	v_cndmask_b32_e64 v66, 0, v36, s[10:11]
	v_cndmask_b32_e64 v0, 0, v0, s[18:19]
	v_cvt_pk_fp8_f32 v64, v60, v66 op_sel:[0,0,1]
	v_cvt_pk_fp8_f32 v65, v61, v0 op_sel:[0,0,1]
	v_add_f32_e32 v0, v66, v0
	v_mov_b32_e32 v230, v229
	s_waitcnt vmcnt(19)
	v_mfma_f32_16x16x32_fp8_fp8 v[36:39], v[106:107], v[64:65], v[6:9]
	s_nop 2
	v_add_f32_e32 v6, v56, v57
	v_add_f32_e32 v6, 0, v6
	v_add_f32_e32 v7, v58, v59
	v_mfma_f32_16x16x32_fp8_fp8 v[40:43], v[108:109], v[64:65], v[10:13]
	v_add_f32_e32 v6, v7, v6
	v_add_f32_e32 v7, v60, v61
	v_add_f32_e32 v6, v7, v6
	s_waitcnt vmcnt(18)
	v_mfma_f32_16x16x32_fp8_fp8 v[44:47], v[110:111], v[64:65], v[14:17]
	v_add_f32_e32 v0, v0, v6
	v_add_f32_e32 v231, v34, v0
	v_mfma_f32_16x16x32_fp8_fp8 v[48:51], v[112:113], v[64:65], v[18:21]
	s_waitcnt vmcnt(17)
	v_mfma_f32_16x16x32_fp8_fp8 v[52:55], v[114:115], v[64:65], v[22:25]
	v_mfma_f32_16x16x32_fp8_fp8 v[56:59], v[116:117], v[64:65], v[26:29]
	s_waitcnt vmcnt(16)
	v_mfma_f32_16x16x32_fp8_fp8 v[60:63], v[134:135], v[64:65], v[30:33]
	v_mfma_f32_16x16x32_fp8_fp8 v[64:67], v[136:137], v[64:65], v[2:5]
	s_cmp_gt_i32 s57, s27
	s_mov_b64 s[10:11], -1
	s_cbranch_scc1 .LBB0_892
; template <bool SLC, bool NOMASK> ...
;     const int kq = lane >> 4;
;     const int pos0 = SLC ? (dcur & 0xfffff) : dcur;
;     const int lo = SLC ? ((((dcur >> 20) == qi) | ((dcur >> 20) == 4)) ? 0 : (1 << 30)) : lo_in;
;     load_frag8(nxt, KF, VF, SLC ? (dnext & 0xfffff) : dnext, lane);
;     f32x4 sa[2] = {(f32x4){0.f, 0.f, 0.f, 0.f}, (f32x4){0.f, 0.f, 0.f, 0.f}};
; #pragma unroll
;     for (int T = 0; T < 2; ++T)
; #pragma unroll
;         for (int s2 = 0; s2 < 4; ++s2) sa[T] = __builtin_amdgcn_mfma_f32_16x16x32_fp8_fp8(cur.k[T][s2], qf[s2], sa[T], 0, 0, 0);
;     float sc[8]; bool vd[8]; float mx = -1e30f;
;     const bool act = lo == 0 || !SLC;
;     if (NOMASK) {
; #pragma unroll
;         for (int j = 0; j < 8; ++j) { sc[j] = sa[j >> 2][j & 3]; vd[j] = act; }
;         mx = fmaxf(fmaxf(fmaxf(sc[0], sc[1]), fmaxf(sc[2], sc[3])), fmaxf(fmaxf(sc[4], sc[5]), fmaxf(sc[6], sc[7])));
;         mx = act ? mx : -1e30f;
;     } else {
; #pragma unroll
;         for (int T = 0; T < 2; ++T)
; #pragma unroll
;             for (int r = 0; r < 4; ++r) { const int p = pos0 + 16 * T + 4 * kq + r; const bool v = (p >= lo) & (p <= hi); const float x = sa[T][r];
;                 sc[4 * T + r] = x; vd[4 * T + r] = v; mx = v ? fmaxf(mx, x) : mx; }
;     }
;     if (__builtin_amdgcn_ballot_w64(mx > st.m + 4.f) != 0ull) {
;         mx = fmaxf(mx, __shfl_xor(mx, 16)); mx = fmaxf(mx, __shfl_xor(mx, 32));
;         const float mn = fmaxf(st.m, mx), alpha = __builtin_amdgcn_exp2f(st.m - mn); st.m = mn; st.l *= alpha;
; #pragma unroll
;         for (int j = 0; j < 8; ++j) st.o[j] = st.o[j] * alpha;
;     }
;     f32x4 pa, pb; float ps = 0.f;
;     const float mref = st.m - 4.f;
;     if (NOMASK) {
; #pragma unroll
;         for (int j = 0; j < 4; ++j) { pa[j] = __builtin_amdgcn_exp2f(sc[j] - mref); pb[j] = __builtin_amdgcn_exp2f(sc[4 + j] - mref); }
;         if (SLC) {
; #pragma unroll
;             for (int j = 0; j < 4; ++j) { pa[j] = act ? pa[j] : 0.f; pb[j] = act ? pb[j] : 0.f; }
;         }
; #pragma unroll
;         for (int j = 0; j < 4; ++j) ps += pa[j] + pb[j];
;     } else {
; #pragma unroll
;         for (int j = 0; j < 4; ++j) { pa[j] = vd[j] ? __builtin_amdgcn_exp2f(sc[j] - mref) : 0.f; pb[j] = vd[4 + j] ? __builtin_amdgcn_exp2f(sc[4 + j] - mref) : 0.f; ps += pa[j] + pb[j]; }
;     }
;     st.l += ps;
;     const u32x2 pw = pack8_fp8(pa, pb);
.LBB0_913:
	s_cmp_lt_i32 s59, s56
	s_cselect_b64 s[10:11], -1, 0
	s_or_b32 s12, s59, 31
	s_cmp_gt_i32 s12, s96
	s_cselect_b64 s[12:13], -1, 0
	s_or_b64 s[10:11], s[10:11], s[12:13]
	s_and_b64 s[10:11], s[10:11], exec
	s_cselect_b32 s10, 0, 2.0
	s_add_i32 s58, s58, 4
	s_or_b32 s14, s10, s59
	s_min_i32 s10, s58, s27
	s_add_i32 s12, s10, s26
	s_lshl_b32 s43, s12, 5
	s_and_b32 s10, s43, 0x3fffffe0
	s_lshr_b32 s50, s10, 4
	s_lshl_b64 s[10:11], s[50:51], 11
	s_and_b32 s50, s12, 0x1ffffff
	s_lshl_b64 s[12:13], s[50:51], 12
	s_cmp_lt_u32 s14, 2.0
	v_lshl_add_u64 v[204:205], v[86:87], 0, s[10:11]
	v_lshl_add_u64 v[202:203], v[88:89], 0, s[12:13]
	s_mov_b64 s[10:11], -1
	v_add_f32_e32 v229, 4.0, v230
	s_cbranch_scc1 .LBB0_917
	v_lshl_add_u64 v[244:245], v[204:205], 0, v[118:119]
	global_load_dwordx4 v[154:157], v[244:245], off
	global_load_dwordx4 v[158:161], v[244:245], off offset:1024
	global_load_dwordx4 v[162:165], v[244:245], off offset:2048
	global_load_dwordx4 v[166:169], v[244:245], off offset:3072
	v_lshl_add_u64 v[246:247], v[202:203], 0, v[118:119]
	global_load_dwordx4 v[106:109], v[246:247], off
	global_load_dwordx4 v[110:113], v[246:247], off offset:1024
	global_load_dwordx4 v[114:117], v[246:247], off offset:2048
	global_load_dwordx4 v[134:137], v[246:247], off offset:3072
	s_waitcnt vmcnt(20)
	v_mfma_f32_16x16x32_fp8_fp8 v[2:5], v[186:187], v[78:79], 0
	v_mov_b64_e32 v[74:75], v[66:67]
	v_mov_b64_e32 v[70:71], v[62:63]
	v_mov_b64_e32 v[30:31], v[56:57]
	v_mfma_f32_16x16x32_fp8_fp8 v[6:9], v[194:195], v[78:79], 0
	v_mov_b64_e32 v[26:27], v[52:53]
	v_mov_b64_e32 v[22:23], v[48:49]
	v_mov_b64_e32 v[18:19], v[44:45]
	v_mfma_f32_16x16x32_fp8_fp8 v[2:5], v[188:189], v[80:81], v[2:5]
	v_mov_b64_e32 v[14:15], v[40:41]
	v_mov_b32_e32 v133, v230
	v_mov_b64_e32 v[72:73], v[64:65]
	v_mfma_f32_16x16x32_fp8_fp8 v[6:9], v[196:197], v[80:81], v[6:9]
	v_mov_b64_e32 v[68:69], v[60:61]
	v_mov_b64_e32 v[32:33], v[58:59]
	v_mov_b64_e32 v[28:29], v[54:55]
	v_mfma_f32_16x16x32_fp8_fp8 v[2:5], v[190:191], v[82:83], v[2:5]
	v_mov_b64_e32 v[24:25], v[50:51]
	v_mov_b64_e32 v[20:21], v[46:47]
	v_mov_b64_e32 v[16:17], v[42:43]
	v_mfma_f32_16x16x32_fp8_fp8 v[6:9], v[198:199], v[82:83], v[6:9]
	v_mov_b32_e32 v34, v231
	v_mfma_f32_16x16x32_fp8_fp8 v[2:5], v[192:193], v[84:85], v[2:5]
	v_mfma_f32_16x16x32_fp8_fp8 v[6:9], v[200:201], v[84:85], v[6:9]
	s_nop 5
	v_max_f32_e32 v0, v3, v3
	v_max_f32_e32 v10, v2, v2
	v_max_f32_e32 v0, v10, v0
	v_max_f32_e32 v10, v5, v5
	v_max_f32_e32 v11, v4, v4
	v_max_f32_e32 v10, v11, v10
	v_max_f32_e32 v11, v9, v9
	v_max_f32_e32 v12, v8, v8
	v_max_f32_e32 v11, v12, v11
	v_max3_f32 v11, v6, v7, v11
	v_max3_f32 v0, v0, v10, v11
	v_mov_b64_e32 v[10:11], v[36:37]
	v_cmp_gt_f32_e32 vcc, v0, v229
	v_mov_b64_e32 v[12:13], v[38:39]
	s_cbranch_vccz .LBB0_916
	ds_bpermute_b32 v10, v227, v0
	v_max_f32_e32 v0, v0, v0
	s_waitcnt lgkmcnt(0)
	v_max_f32_e32 v10, v10, v10
	v_max_f32_e32 v0, v0, v10
	ds_bpermute_b32 v10, v226, v0
	s_waitcnt lgkmcnt(0)
	v_max3_f32 v133, v230, v0, v10
	v_sub_f32_e32 v0, v230, v133
	v_exp_f32_e32 v0, v0
	s_nop 0
	v_mul_f32_e32 v34, v231, v0
	v_pk_mul_f32 v[12:13], v[38:39], v[0:1] op_sel_hi:[1,0]
	v_pk_mul_f32 v[10:11], v[36:37], v[0:1] op_sel_hi:[1,0]
	v_pk_mul_f32 v[16:17], v[42:43], v[0:1] op_sel_hi:[1,0]
	v_pk_mul_f32 v[14:15], v[40:41], v[0:1] op_sel_hi:[1,0]
	v_pk_mul_f32 v[20:21], v[46:47], v[0:1] op_sel_hi:[1,0]
	v_pk_mul_f32 v[18:19], v[44:45], v[0:1] op_sel_hi:[1,0]
	v_pk_mul_f32 v[24:25], v[50:51], v[0:1] op_sel_hi:[1,0]
	v_pk_mul_f32 v[22:23], v[48:49], v[0:1] op_sel_hi:[1,0]
	v_pk_mul_f32 v[28:29], v[54:55], v[0:1] op_sel_hi:[1,0]
	v_pk_mul_f32 v[26:27], v[52:53], v[0:1] op_sel_hi:[1,0]
	v_pk_mul_f32 v[32:33], v[58:59], v[0:1] op_sel_hi:[1,0]
	v_pk_mul_f32 v[30:31], v[56:57], v[0:1] op_sel_hi:[1,0]
	v_pk_mul_f32 v[70:71], v[62:63], v[0:1] op_sel_hi:[1,0]
	v_pk_mul_f32 v[68:69], v[60:61], v[0:1] op_sel_hi:[1,0]
	v_pk_mul_f32 v[74:75], v[66:67], v[0:1] op_sel_hi:[1,0]
	v_pk_mul_f32 v[72:73], v[64:65], v[0:1] op_sel_hi:[1,0]
.LBB0_916:
	v_add_f32_e32 v232, -4.0, v133
	v_sub_f32_e32 v0, v2, v232
	v_exp_f32_e32 v233, v0
	v_sub_f32_e32 v0, v6, v232
	v_exp_f32_e32 v236, v0
	v_sub_f32_e32 v0, v3, v232
	v_exp_f32_e32 v2, v0
	v_sub_f32_e32 v0, v7, v232
	v_exp_f32_e32 v0, v0
	v_sub_f32_e32 v3, v4, v232
	v_exp_f32_e32 v237, v3
	v_sub_f32_e32 v3, v8, v232
	v_exp_f32_e32 v238, v3
	v_sub_f32_e32 v3, v5, v232
	v_exp_f32_e32 v4, v3
	v_sub_f32_e32 v3, v9, v232
	v_mov_b32_e32 v234, v1
	v_mov_b32_e32 v235, v1
	v_exp_f32_e32 v232, v3
	v_cvt_pk_fp8_f32 v234, v233, v2
	v_cvt_pk_fp8_f32 v235, v236, v0
	v_add_f32_e32 v3, v233, v236
	v_pk_add_f32 v[2:3], v[2:3], v[0:1]
	v_cvt_pk_fp8_f32 v234, v237, v4 op_sel:[0,0,1]
	v_cvt_pk_fp8_f32 v235, v238, v232 op_sel:[0,0,1]
	v_pk_add_f32 v[2:3], v[2:3], v[2:3] op_sel_hi:[0,1]
	v_add_f32_e32 v5, v237, v238
	v_mov_b32_e32 v233, v3
	v_pk_add_f32 v[2:3], v[4:5], v[232:233]
	s_waitcnt vmcnt(19)
	v_mfma_f32_16x16x32_fp8_fp8 v[6:9], v[170:171], v[234:235], v[10:13]
	v_add_f32_e32 v0, v2, v3
	v_add_f32_e32 v34, v0, v34
	s_mov_b64 s[10:11], 0
	v_mfma_f32_16x16x32_fp8_fp8 v[10:13], v[172:173], v[234:235], v[14:17]
	s_waitcnt vmcnt(18)
	v_mfma_f32_16x16x32_fp8_fp8 v[14:17], v[174:175], v[234:235], v[18:21]
	v_mfma_f32_16x16x32_fp8_fp8 v[18:21], v[176:177], v[234:235], v[22:25]
	s_waitcnt vmcnt(17)
	v_mfma_f32_16x16x32_fp8_fp8 v[22:25], v[178:179], v[234:235], v[26:29]
	v_mfma_f32_16x16x32_fp8_fp8 v[26:29], v[180:181], v[234:235], v[30:33]
	s_waitcnt vmcnt(16)
	v_mfma_f32_16x16x32_fp8_fp8 v[30:33], v[182:183], v[234:235], v[68:71]
	v_mfma_f32_16x16x32_fp8_fp8 v[2:5], v[184:185], v[234:235], v[72:75]
; template <bool SLC, bool NOMASK> ...
;     const int kq = lane >> 4;
;     const int pos0 = SLC ? (dcur & 0xfffff) : dcur;
;     const int lo = SLC ? ((((dcur >> 20) == qi) | ((dcur >> 20) == 4)) ? 0 : (1 << 30)) : lo_in;
;     load_frag8(nxt, KF, VF, SLC ? (dnext & 0xfffff) : dnext, lane);
;     f32x4 sa[2] = {(f32x4){0.f, 0.f, 0.f, 0.f}, (f32x4){0.f, 0.f, 0.f, 0.f}};
; #pragma unroll
;     for (int T = 0; T < 2; ++T)
; #pragma unroll
;         for (int s2 = 0; s2 < 4; ++s2) sa[T] = __builtin_amdgcn_mfma_f32_16x16x32_fp8_fp8(cur.k[T][s2], qf[s2], sa[T], 0, 0, 0);
;     float sc[8]; bool vd[8]; float mx = -1e30f;
;     const bool act = lo == 0 || !SLC;
;     if (NOMASK) {
; #pragma unroll
;         for (int j = 0; j < 8; ++j) { sc[j] = sa[j >> 2][j & 3]; vd[j] = act; }
;         mx = fmaxf(fmaxf(fmaxf(sc[0], sc[1]), fmaxf(sc[2], sc[3])), fmaxf(fmaxf(sc[4], sc[5]), fmaxf(sc[6], sc[7])));
;         mx = act ? mx : -1e30f;
;     } else {
; #pragma unroll
;         for (int T = 0; T < 2; ++T)
; #pragma unroll
;             for (int r = 0; r < 4; ++r) { const int p = pos0 + 16 * T + 4 * kq + r; const bool v = (p >= lo) & (p <= hi); const float x = sa[T][r];
;                 sc[4 * T + r] = x; vd[4 * T + r] = v; mx = v ? fmaxf(mx, x) : mx; }
;     }
;     if (__builtin_amdgcn_ballot_w64(mx > st.m + 4.f) != 0ull) {
;         mx = fmaxf(mx, __shfl_xor(mx, 16)); mx = fmaxf(mx, __shfl_xor(mx, 32));
;         const float mn = fmaxf(st.m, mx), alpha = __builtin_amdgcn_exp2f(st.m - mn); st.m = mn; st.l *= alpha;
; #pragma unroll
;         for (int j = 0; j < 8; ++j) st.o[j] = st.o[j] * alpha;
;     }
;     f32x4 pa, pb; float ps = 0.f;
;     const float mref = st.m - 4.f;
;     if (NOMASK) {
; #pragma unroll
;         for (int j = 0; j < 4; ++j) { pa[j] = __builtin_amdgcn_exp2f(sc[j] - mref); pb[j] = __builtin_amdgcn_exp2f(sc[4 + j] - mref); }
;         if (SLC) {
; #pragma unroll
;             for (int j = 0; j < 4; ++j) { pa[j] = act ? pa[j] : 0.f; pb[j] = act ? pb[j] : 0.f; }
;         }
; #pragma unroll
;         for (int j = 0; j < 4; ++j) ps += pa[j] + pb[j];
;     } else {
; #pragma unroll
;         for (int j = 0; j < 4; ++j) { pa[j] = vd[j] ? __builtin_amdgcn_exp2f(sc[j] - mref) : 0.f; pb[j] = vd[4 + j] ? __builtin_amdgcn_exp2f(sc[4 + j] - mref) : 0.f; ps += pa[j] + pb[j]; }
;     }
;     st.l += ps;
;     const u32x2 pw = pack8_fp8(pa, pb);
.LBB0_917:
	s_and_b64 vcc, exec, s[10:11]
	s_cbranch_vccz .LBB0_921
	v_lshl_add_u64 v[244:245], v[204:205], 0, v[118:119]
	global_load_dwordx4 v[154:157], v[244:245], off
	global_load_dwordx4 v[158:161], v[244:245], off offset:1024
	global_load_dwordx4 v[162:165], v[244:245], off offset:2048
	global_load_dwordx4 v[166:169], v[244:245], off offset:3072
	v_lshl_add_u64 v[246:247], v[202:203], 0, v[118:119]
	global_load_dwordx4 v[106:109], v[246:247], off
	global_load_dwordx4 v[110:113], v[246:247], off offset:1024
	global_load_dwordx4 v[114:117], v[246:247], off offset:2048
	global_load_dwordx4 v[134:137], v[246:247], off offset:3072
	s_waitcnt vmcnt(20)
	v_mfma_f32_16x16x32_fp8_fp8 v[2:5], v[186:187], v[78:79], 0
	v_or_b32_e32 v0, s59, v211
	v_cmp_ge_i32_e32 vcc, v0, v35
	v_cmp_le_i32_e64 s[10:11], v0, v132
	v_mfma_f32_16x16x32_fp8_fp8 v[2:5], v[188:189], v[80:81], v[2:5]
	s_and_b64 s[16:17], vcc, s[10:11]
	v_or_b32_e32 v11, 1, v0
	v_cmp_ge_i32_e32 vcc, v11, v35
	v_mfma_f32_16x16x32_fp8_fp8 v[2:5], v[190:191], v[82:83], v[2:5]
	v_cmp_lt_i32_e64 s[10:11], v0, v132
	s_and_b64 s[12:13], s[10:11], vcc
	v_mfma_f32_16x16x32_fp8_fp8 v[6:9], v[194:195], v[78:79], 0
	v_mfma_f32_16x16x32_fp8_fp8 v[2:5], v[192:193], v[84:85], v[2:5]
	v_mfma_f32_16x16x32_fp8_fp8 v[6:9], v[196:197], v[80:81], v[6:9]
	v_mfma_f32_16x16x32_fp8_fp8 v[6:9], v[198:199], v[82:83], v[6:9]
	s_nop 3
	v_max_f32_e32 v10, v2, v2
	v_max_f32_e32 v10, 0xf149f2ca, v10
	v_cndmask_b32_e64 v10, v223, v10, s[16:17]
	v_max_f32_e32 v11, v3, v3
	v_max_f32_e32 v11, v10, v11
	v_cndmask_b32_e64 v10, v10, v11, s[12:13]
	v_or_b32_e32 v11, 2, v0
	v_cmp_ge_i32_e32 vcc, v11, v35
	v_cmp_le_i32_e64 s[10:11], v11, v132
	v_max_f32_e32 v11, v4, v4
	v_max_f32_e32 v11, v10, v11
	s_and_b64 s[14:15], vcc, s[10:11]
	v_mfma_f32_16x16x32_fp8_fp8 v[6:9], v[200:201], v[84:85], v[6:9]
	v_cndmask_b32_e64 v10, v10, v11, s[14:15]
	v_or_b32_e32 v11, 3, v0
	v_cmp_ge_i32_e32 vcc, v11, v35
	v_cmp_le_i32_e64 s[10:11], v11, v132
	v_max_f32_e32 v11, v5, v5
	v_max_f32_e32 v11, v10, v11
	s_and_b64 s[10:11], vcc, s[10:11]
	v_cndmask_b32_e64 v10, v10, v11, s[10:11]
	v_or_b32_e32 v11, 16, v0
	v_cmp_ge_i32_e32 vcc, v11, v35
	v_cmp_le_i32_e64 s[18:19], v11, v132
	v_max_f32_e32 v11, v6, v6
	v_max_f32_e32 v11, v10, v11
	s_and_b64 s[24:25], vcc, s[18:19]
	v_cndmask_b32_e64 v10, v10, v11, s[24:25]
	v_or_b32_e32 v11, 17, v0
	v_cmp_ge_i32_e32 vcc, v11, v35
	v_cmp_le_i32_e64 s[18:19], v11, v132
	v_max_f32_e32 v11, v10, v10
	v_max_f32_e32 v12, v7, v7
	v_max_f32_e32 v11, v11, v12
	s_and_b64 s[20:21], vcc, s[18:19]
	v_cndmask_b32_e64 v10, v10, v11, s[20:21]
	v_or_b32_e32 v11, 18, v0
	v_cmp_ge_i32_e32 vcc, v11, v35
	v_cmp_le_i32_e64 s[18:19], v11, v132
	v_max_f32_e32 v11, v10, v10
	v_max_f32_e32 v12, v8, v8
	v_max_f32_e32 v11, v11, v12
	s_and_b64 s[22:23], vcc, s[18:19]
	v_cndmask_b32_e64 v10, v10, v11, s[22:23]
	v_or_b32_e32 v0, 19, v0
	v_cmp_ge_i32_e32 vcc, v0, v35
	v_cmp_le_i32_e64 s[18:19], v0, v132
	v_max_f32_e32 v0, v10, v10
	v_max_f32_e32 v11, v9, v9
	v_max_f32_e32 v0, v0, v11
	s_and_b64 s[18:19], vcc, s[18:19]
	v_cndmask_b32_e64 v0, v10, v0, s[18:19]
	v_cmp_gt_f32_e32 vcc, v0, v229
	s_cbranch_vccz .LBB0_920
	ds_bpermute_b32 v10, v227, v0
	v_max_f32_e32 v0, v0, v0
	s_waitcnt lgkmcnt(0)
	v_max_f32_e32 v10, v10, v10
	v_max_f32_e32 v0, v0, v10
	ds_bpermute_b32 v10, v226, v0
	s_waitcnt lgkmcnt(0)
	v_max3_f32 v10, v230, v0, v10
	v_sub_f32_e32 v0, v230, v10
	v_exp_f32_e32 v0, v0
	v_mov_b32_e32 v230, v10
	v_mul_f32_e32 v231, v231, v0
	v_pk_mul_f32 v[38:39], v[38:39], v[0:1] op_sel_hi:[1,0]
	v_pk_mul_f32 v[36:37], v[36:37], v[0:1] op_sel_hi:[1,0]
	v_pk_mul_f32 v[42:43], v[42:43], v[0:1] op_sel_hi:[1,0]
	v_pk_mul_f32 v[40:41], v[40:41], v[0:1] op_sel_hi:[1,0]
	v_pk_mul_f32 v[46:47], v[46:47], v[0:1] op_sel_hi:[1,0]
	v_pk_mul_f32 v[44:45], v[44:45], v[0:1] op_sel_hi:[1,0]
	v_pk_mul_f32 v[50:51], v[50:51], v[0:1] op_sel_hi:[1,0]
	v_pk_mul_f32 v[48:49], v[48:49], v[0:1] op_sel_hi:[1,0]
	v_pk_mul_f32 v[54:55], v[54:55], v[0:1] op_sel_hi:[1,0]
	v_pk_mul_f32 v[52:53], v[52:53], v[0:1] op_sel_hi:[1,0]
	v_pk_mul_f32 v[58:59], v[58:59], v[0:1] op_sel_hi:[1,0]
	v_pk_mul_f32 v[56:57], v[56:57], v[0:1] op_sel_hi:[1,0]
	v_pk_mul_f32 v[62:63], v[62:63], v[0:1] op_sel_hi:[1,0]
	v_pk_mul_f32 v[60:61], v[60:61], v[0:1] op_sel_hi:[1,0]
	v_pk_mul_f32 v[66:67], v[66:67], v[0:1] op_sel_hi:[1,0]
	v_pk_mul_f32 v[64:65], v[64:65], v[0:1] op_sel_hi:[1,0]
.LBB0_920:
	v_add_f32_e32 v0, -4.0, v230
	v_sub_f32_e32 v2, v2, v0
	v_exp_f32_e32 v2, v2
	v_sub_f32_e32 v6, v6, v0
	v_exp_f32_e32 v6, v6
	v_sub_f32_e32 v4, v4, v0
	v_cndmask_b32_e64 v26, 0, v2, s[16:17]
	v_sub_f32_e32 v2, v3, v0
	v_exp_f32_e32 v2, v2
	v_sub_f32_e32 v3, v7, v0
	v_exp_f32_e32 v3, v3
	v_cndmask_b32_e64 v27, 0, v6, s[24:25]
	v_sub_f32_e32 v6, v8, v0
	v_cndmask_b32_e64 v28, 0, v2, s[12:13]
	v_sub_f32_e32 v2, v5, v0
	v_sub_f32_e32 v0, v9, v0
	v_exp_f32_e32 v4, v4
	v_exp_f32_e32 v6, v6
	v_cndmask_b32_e64 v29, 0, v3, s[20:21]
	v_exp_f32_e32 v5, v2
	v_exp_f32_e32 v0, v0
	v_mov_b32_e32 v2, v1
	v_mov_b32_e32 v3, v1
	v_cvt_pk_fp8_f32 v2, v26, v28
	v_cvt_pk_fp8_f32 v3, v27, v29
	v_cndmask_b32_e64 v4, 0, v4, s[14:15]
	v_cndmask_b32_e64 v30, 0, v6, s[22:23]
	v_cndmask_b32_e64 v5, 0, v5, s[10:11]
	v_cndmask_b32_e64 v0, 0, v0, s[18:19]
	v_cvt_pk_fp8_f32 v2, v4, v5 op_sel:[0,0,1]
	v_cvt_pk_fp8_f32 v3, v30, v0 op_sel:[0,0,1]
	v_add_f32_e32 v26, v26, v27
	v_add_f32_e32 v31, 0, v26
	v_add_f32_e32 v32, v28, v29
	v_add_f32_e32 v31, v32, v31
	v_add_f32_e32 v4, v4, v30
	v_add_f32_e32 v4, v4, v31
	v_add_f32_e32 v0, v5, v0
	s_waitcnt vmcnt(19)
	v_mfma_f32_16x16x32_fp8_fp8 v[6:9], v[170:171], v[2:3], v[36:39]
	v_add_f32_e32 v0, v0, v4
	v_add_f32_e32 v34, v231, v0
	v_mov_b32_e32 v133, v230
	v_mfma_f32_16x16x32_fp8_fp8 v[10:13], v[172:173], v[2:3], v[40:43]
	s_waitcnt vmcnt(18)
	v_mfma_f32_16x16x32_fp8_fp8 v[14:17], v[174:175], v[2:3], v[44:47]
	v_mfma_f32_16x16x32_fp8_fp8 v[18:21], v[176:177], v[2:3], v[48:51]
	s_waitcnt vmcnt(17)
	v_mfma_f32_16x16x32_fp8_fp8 v[22:25], v[178:179], v[2:3], v[52:55]
	v_mfma_f32_16x16x32_fp8_fp8 v[26:29], v[180:181], v[2:3], v[56:59]
	s_waitcnt vmcnt(16)
	v_mfma_f32_16x16x32_fp8_fp8 v[30:33], v[182:183], v[2:3], v[60:63]
	v_mfma_f32_16x16x32_fp8_fp8 v[2:5], v[184:185], v[2:3], v[64:67]
